# priority raise issued before the barrier that opens each MFMA segment (first MFMA follows the release directly)
# baseline (speedup 1.0000x reference)
.Lrestag_187:
	ds_read_b128 v[162:165], v157
	ds_read_b128 v[170:173], v157 offset:1024
	ds_read_b128 v[174:177], v157 offset:2048
	ds_read_b128 v[178:181], v157 offset:3072
	ds_read_b128 v[182:185], v158
	ds_read_b128 v[186:189], v158 offset:1024
	ds_read_b128 v[190:193], v158 offset:2048
	ds_read_b128 v[194:197], v158 offset:3072
	s_add_u32 s26, s24, 0x100
	s_addc_u32 s27, s25, 0
	s_cmp_eq_u32 s59, 12
	s_cselect_b32 s31, s17, s27
	s_cselect_b32 s30, s55, s26
	s_cselect_b32 s29, s15, s58
	s_cselect_b32 s28, s56, s57
	s_add_i32 m0, s23, 0xc000
	ds_read_b128 v[198:201], v159
	ds_read_b128 v[202:205], v159 offset:1024
	ds_read_b128 v[206:209], v159 offset:2048
	ds_read_b128 v[210:213], v159 offset:3072
	ds_read_b128 v[214:217], v159 offset:4096
	ds_read_b128 v[218:221], v159 offset:5120
	ds_read_b128 v[222:225], v159 offset:6144
	ds_read_b128 v[226:229], v159 offset:7168
	global_load_lds_dwordx4 v142, s[24:25]
	s_add_i32 m0, s23, 0xe000
	s_nop 0
	global_load_lds_dwordx4 v144, s[24:25]
	s_nop 0
	s_waitcnt lgkmcnt(0)
	s_setprio 1
	s_barrier
	v_mfma_f32_16x16x32_bf16 v[124:127], v[162:165], v[198:201], 0
	v_mfma_f32_16x16x32_bf16 v[120:123], v[174:177], v[198:201], 0
	v_mfma_f32_16x16x32_bf16 v[112:115], v[162:165], v[206:209], 0
	v_mfma_f32_16x16x32_bf16 v[104:107], v[174:177], v[206:209], 0
	v_mfma_f32_16x16x32_bf16 v[96:99], v[162:165], v[214:217], 0
	v_mfma_f32_16x16x32_bf16 v[88:91], v[174:177], v[214:217], 0
	v_mfma_f32_16x16x32_bf16 v[80:83], v[162:165], v[222:225], 0
	v_mfma_f32_16x16x32_bf16 v[72:75], v[174:177], v[222:225], 0
	v_mfma_f32_16x16x32_bf16 v[124:127], v[170:173], v[202:205], v[124:127]
	v_mfma_f32_16x16x32_bf16 v[120:123], v[178:181], v[202:205], v[120:123]
	v_mfma_f32_16x16x32_bf16 v[112:115], v[170:173], v[210:213], v[112:115]
	v_mfma_f32_16x16x32_bf16 v[104:107], v[178:181], v[210:213], v[104:107]
	v_mfma_f32_16x16x32_bf16 v[96:99], v[170:173], v[218:221], v[96:99]
	v_mfma_f32_16x16x32_bf16 v[88:91], v[178:181], v[218:221], v[88:91]
	v_mfma_f32_16x16x32_bf16 v[80:83], v[170:173], v[226:229], v[80:83]
	v_mfma_f32_16x16x32_bf16 v[72:75], v[178:181], v[226:229], v[72:75]
	v_mfma_f32_16x16x32_bf16 v[116:119], v[182:185], v[198:201], 0
	v_mfma_f32_16x16x32_bf16 v[108:111], v[190:193], v[198:201], 0
	v_mfma_f32_16x16x32_bf16 v[100:103], v[182:185], v[206:209], 0
	v_mfma_f32_16x16x32_bf16 v[92:95], v[190:193], v[206:209], 0
	v_mfma_f32_16x16x32_bf16 v[84:87], v[182:185], v[214:217], 0
	v_mfma_f32_16x16x32_bf16 v[76:79], v[190:193], v[214:217], 0
	v_mfma_f32_16x16x32_bf16 v[68:71], v[182:185], v[222:225], 0
	v_mfma_f32_16x16x32_bf16 v[64:67], v[190:193], v[222:225], 0
	v_mfma_f32_16x16x32_bf16 v[116:119], v[186:189], v[202:205], v[116:119]
	v_mfma_f32_16x16x32_bf16 v[108:111], v[194:197], v[202:205], v[108:111]
	v_mfma_f32_16x16x32_bf16 v[100:103], v[186:189], v[210:213], v[100:103]
	v_mfma_f32_16x16x32_bf16 v[92:95], v[194:197], v[210:213], v[92:95]
	v_mfma_f32_16x16x32_bf16 v[84:87], v[186:189], v[218:221], v[84:87]
	v_mfma_f32_16x16x32_bf16 v[76:79], v[194:197], v[218:221], v[76:79]
	v_mfma_f32_16x16x32_bf16 v[68:71], v[186:189], v[226:229], v[68:71]
	v_mfma_f32_16x16x32_bf16 v[64:67], v[194:197], v[226:229], v[64:67]
	s_barrier
	s_setprio 0
	s_add_i32 s0, s51, s41
	v_lshl_add_u64 v[166:167], s[28:29], 0, v[130:131]
	s_mov_b32 m0, s0
	ds_read_b128 v[198:201], v159 offset:16384
	ds_read_b128 v[202:205], v159 offset:17408
	ds_read_b128 v[206:209], v159 offset:18432
	ds_read_b128 v[210:213], v159 offset:19456
	ds_read_b128 v[214:217], v159 offset:20480
	ds_read_b128 v[218:221], v159 offset:21504
	ds_read_b128 v[222:225], v159 offset:22528
	ds_read_b128 v[226:229], v159 offset:23552
	global_load_lds_dwordx4 v[166:167], off
	s_add_i32 m0, s0, 0x2000
	s_add_u32 s0, s28, 0x40000
	v_lshl_add_u64 v[230:231], s[28:29], 0, v[134:135]
	s_addc_u32 s1, s29, 0
	s_add_i32 s24, s52, s41
	global_load_lds_dwordx4 v[230:231], off
	s_mov_b32 m0, s24
	v_lshl_add_u64 v[234:235], s[30:31], 0, v[132:133]
	global_load_lds_dwordx4 v130, s[0:1]
	s_add_i32 m0, s24, 0x2000
	s_nop 0
	global_load_lds_dwordx4 v134, s[0:1]
	v_lshl_add_u64 v[232:233], s[30:31], 0, v[128:129]
	s_nop 0
	s_waitcnt lgkmcnt(0)
	s_setprio 1
	s_barrier
	v_mfma_f32_16x16x32_bf16 v[60:63], v[162:165], v[198:201], 0
	v_mfma_f32_16x16x32_bf16 v[56:59], v[174:177], v[198:201], 0
	v_mfma_f32_16x16x32_bf16 v[48:51], v[162:165], v[206:209], 0
	v_mfma_f32_16x16x32_bf16 v[40:43], v[174:177], v[206:209], 0
	v_mfma_f32_16x16x32_bf16 v[32:35], v[162:165], v[214:217], 0
	v_mfma_f32_16x16x32_bf16 v[24:27], v[174:177], v[214:217], 0
	v_mfma_f32_16x16x32_bf16 v[16:19], v[162:165], v[222:225], 0
	v_mfma_f32_16x16x32_bf16 v[8:11], v[174:177], v[222:225], 0
	v_mfma_f32_16x16x32_bf16 v[60:63], v[170:173], v[202:205], v[60:63]
	v_mfma_f32_16x16x32_bf16 v[56:59], v[178:181], v[202:205], v[56:59]
	v_mfma_f32_16x16x32_bf16 v[48:51], v[170:173], v[210:213], v[48:51]
	v_mfma_f32_16x16x32_bf16 v[40:43], v[178:181], v[210:213], v[40:43]
	v_mfma_f32_16x16x32_bf16 v[32:35], v[170:173], v[218:221], v[32:35]
	v_mfma_f32_16x16x32_bf16 v[24:27], v[178:181], v[218:221], v[24:27]
	v_mfma_f32_16x16x32_bf16 v[16:19], v[170:173], v[226:229], v[16:19]
	v_mfma_f32_16x16x32_bf16 v[8:11], v[178:181], v[226:229], v[8:11]
	v_mfma_f32_16x16x32_bf16 v[52:55], v[182:185], v[198:201], 0
	v_mfma_f32_16x16x32_bf16 v[44:47], v[190:193], v[198:201], 0
	v_mfma_f32_16x16x32_bf16 v[36:39], v[182:185], v[206:209], 0
	v_mfma_f32_16x16x32_bf16 v[28:31], v[190:193], v[206:209], 0
	v_mfma_f32_16x16x32_bf16 v[20:23], v[182:185], v[214:217], 0
	v_mfma_f32_16x16x32_bf16 v[12:15], v[190:193], v[214:217], 0
	v_mfma_f32_16x16x32_bf16 v[4:7], v[182:185], v[222:225], 0
	v_mfma_f32_16x16x32_bf16 v[0:3], v[190:193], v[222:225], 0
	v_mfma_f32_16x16x32_bf16 v[52:55], v[186:189], v[202:205], v[52:55]
	v_mfma_f32_16x16x32_bf16 v[44:47], v[194:197], v[202:205], v[44:47]
	v_mfma_f32_16x16x32_bf16 v[36:39], v[186:189], v[210:213], v[36:39]
	v_mfma_f32_16x16x32_bf16 v[28:31], v[194:197], v[210:213], v[28:31]
	v_mfma_f32_16x16x32_bf16 v[20:23], v[186:189], v[218:221], v[20:23]
	v_mfma_f32_16x16x32_bf16 v[12:15], v[194:197], v[218:221], v[12:15]
	v_mfma_f32_16x16x32_bf16 v[4:7], v[186:189], v[226:229], v[4:7]
	v_mfma_f32_16x16x32_bf16 v[0:3], v[194:197], v[226:229], v[0:3]
	s_barrier
	s_setprio 0
	s_add_i32 s24, 0, 0x18000
	v_add_u32_e32 v150, s24, v153
	s_add_i32 s25, 0, 0x1c000
	ds_read_b128 v[162:165], v150
	ds_read_b128 v[170:173], v150 offset:1024
	ds_read_b128 v[174:177], v150 offset:2048
	ds_read_b128 v[178:181], v150 offset:3072
	v_add_u32_e32 v150, s25, v153
	ds_read_b128 v[182:185], v150
	ds_read_b128 v[186:189], v150 offset:1024
	ds_read_b128 v[190:193], v150 offset:2048
	ds_read_b128 v[194:197], v150 offset:3072
	s_add_u32 s0, s30, 0x40000
	s_addc_u32 s1, s31, 0
	s_mov_b32 m0, s43
	ds_read_b128 v[198:201], v159 offset:32768
	ds_read_b128 v[202:205], v159 offset:33792
	ds_read_b128 v[206:209], v159 offset:34816
	ds_read_b128 v[210:213], v159 offset:35840
	ds_read_b128 v[214:217], v159 offset:36864
	ds_read_b128 v[218:221], v159 offset:37888
	ds_read_b128 v[222:225], v159 offset:38912
	ds_read_b128 v[226:229], v159 offset:39936
	global_load_lds_dwordx4 v128, s[0:1]
	s_mov_b32 m0, s44
	s_nop 0
	global_load_lds_dwordx4 v132, s[0:1]
	s_mov_b32 m0, s23
	s_nop 0
	global_load_lds_dwordx4 v[232:233], off
	s_mov_b32 m0, s42
	s_nop 0
	global_load_lds_dwordx4 v[234:235], off
	s_waitcnt vmcnt(8)
	s_waitcnt lgkmcnt(0)
	s_setprio 1
	s_barrier
	v_mfma_f32_16x16x32_bf16 v[124:127], v[162:165], v[198:201], v[124:127]
	v_mfma_f32_16x16x32_bf16 v[120:123], v[174:177], v[198:201], v[120:123]
	v_mfma_f32_16x16x32_bf16 v[112:115], v[162:165], v[206:209], v[112:115]
	v_mfma_f32_16x16x32_bf16 v[104:107], v[174:177], v[206:209], v[104:107]
	v_mfma_f32_16x16x32_bf16 v[96:99], v[162:165], v[214:217], v[96:99]
	v_mfma_f32_16x16x32_bf16 v[88:91], v[174:177], v[214:217], v[88:91]
	v_mfma_f32_16x16x32_bf16 v[80:83], v[162:165], v[222:225], v[80:83]
	v_mfma_f32_16x16x32_bf16 v[72:75], v[174:177], v[222:225], v[72:75]
	v_mfma_f32_16x16x32_bf16 v[124:127], v[170:173], v[202:205], v[124:127]
	v_mfma_f32_16x16x32_bf16 v[120:123], v[178:181], v[202:205], v[120:123]
	v_mfma_f32_16x16x32_bf16 v[112:115], v[170:173], v[210:213], v[112:115]
	v_mfma_f32_16x16x32_bf16 v[104:107], v[178:181], v[210:213], v[104:107]
	v_mfma_f32_16x16x32_bf16 v[96:99], v[170:173], v[218:221], v[96:99]
	v_mfma_f32_16x16x32_bf16 v[88:91], v[178:181], v[218:221], v[88:91]
	v_mfma_f32_16x16x32_bf16 v[80:83], v[170:173], v[226:229], v[80:83]
	v_mfma_f32_16x16x32_bf16 v[72:75], v[178:181], v[226:229], v[72:75]
	v_mfma_f32_16x16x32_bf16 v[116:119], v[182:185], v[198:201], v[116:119]
	v_mfma_f32_16x16x32_bf16 v[108:111], v[190:193], v[198:201], v[108:111]
	v_mfma_f32_16x16x32_bf16 v[100:103], v[182:185], v[206:209], v[100:103]
	v_mfma_f32_16x16x32_bf16 v[92:95], v[190:193], v[206:209], v[92:95]
	v_mfma_f32_16x16x32_bf16 v[84:87], v[182:185], v[214:217], v[84:87]
	v_mfma_f32_16x16x32_bf16 v[76:79], v[190:193], v[214:217], v[76:79]
	v_mfma_f32_16x16x32_bf16 v[68:71], v[182:185], v[222:225], v[68:71]
	v_mfma_f32_16x16x32_bf16 v[64:67], v[190:193], v[222:225], v[64:67]
	v_mfma_f32_16x16x32_bf16 v[116:119], v[186:189], v[202:205], v[116:119]
	v_mfma_f32_16x16x32_bf16 v[108:111], v[194:197], v[202:205], v[108:111]
	v_mfma_f32_16x16x32_bf16 v[100:103], v[186:189], v[210:213], v[100:103]
	v_mfma_f32_16x16x32_bf16 v[92:95], v[194:197], v[210:213], v[92:95]
	v_mfma_f32_16x16x32_bf16 v[84:87], v[186:189], v[218:221], v[84:87]
	v_mfma_f32_16x16x32_bf16 v[76:79], v[194:197], v[218:221], v[76:79]
	v_mfma_f32_16x16x32_bf16 v[68:71], v[186:189], v[226:229], v[68:71]
	v_mfma_f32_16x16x32_bf16 v[64:67], v[194:197], v[226:229], v[64:67]
	s_barrier
	s_setprio 0
	s_add_i32 s0, s24, s41
	v_lshl_add_u64 v[166:167], v[166:167], 0, s[8:9]
	s_mov_b32 m0, s0
	ds_read_b128 v[198:201], v159 offset:49152
	ds_read_b128 v[202:205], v159 offset:50176
	ds_read_b128 v[206:209], v159 offset:51200
	ds_read_b128 v[210:213], v159 offset:52224
	ds_read_b128 v[214:217], v159 offset:53248
	ds_read_b128 v[218:221], v159 offset:54272
	ds_read_b128 v[222:225], v159 offset:55296
	ds_read_b128 v[226:229], v159 offset:56320
	global_load_lds_dwordx4 v[166:167], off
	s_add_i32 m0, s0, 0x2000
	s_add_u32 s0, s28, 0x40080
	v_lshl_add_u64 v[166:167], v[230:231], 0, s[8:9]
	s_addc_u32 s1, s29, 0
	s_add_i32 s24, s25, s41
	global_load_lds_dwordx4 v[166:167], off
	s_mov_b32 m0, s24
	s_nop 0
	global_load_lds_dwordx4 v130, s[0:1]
	s_add_i32 m0, s24, 0x2000
	s_nop 0
	global_load_lds_dwordx4 v134, s[0:1]
	v_lshl_add_u64 v[166:167], v[232:233], 0, s[8:9]
	s_mov_b32 m0, s47
	s_nop 0
	global_load_lds_dwordx4 v[166:167], off
	v_lshl_add_u64 v[166:167], v[234:235], 0, s[8:9]
	s_mov_b32 m0, s48
	s_nop 0
	global_load_lds_dwordx4 v[166:167], off
	s_waitcnt vmcnt(6)
	s_waitcnt lgkmcnt(0)
	s_setprio 1
	s_barrier
	v_mfma_f32_16x16x32_bf16 v[60:63], v[162:165], v[198:201], v[60:63]
	v_mfma_f32_16x16x32_bf16 v[56:59], v[174:177], v[198:201], v[56:59]
	v_mfma_f32_16x16x32_bf16 v[48:51], v[162:165], v[206:209], v[48:51]
	v_mfma_f32_16x16x32_bf16 v[40:43], v[174:177], v[206:209], v[40:43]
	v_mfma_f32_16x16x32_bf16 v[32:35], v[162:165], v[214:217], v[32:35]
	v_mfma_f32_16x16x32_bf16 v[24:27], v[174:177], v[214:217], v[24:27]
	v_mfma_f32_16x16x32_bf16 v[16:19], v[162:165], v[222:225], v[16:19]
	v_mfma_f32_16x16x32_bf16 v[8:11], v[174:177], v[222:225], v[8:11]
	v_mfma_f32_16x16x32_bf16 v[60:63], v[170:173], v[202:205], v[60:63]
	v_mfma_f32_16x16x32_bf16 v[56:59], v[178:181], v[202:205], v[56:59]
	v_mfma_f32_16x16x32_bf16 v[48:51], v[170:173], v[210:213], v[48:51]
	v_mfma_f32_16x16x32_bf16 v[40:43], v[178:181], v[210:213], v[40:43]
	v_mfma_f32_16x16x32_bf16 v[32:35], v[170:173], v[218:221], v[32:35]
	v_mfma_f32_16x16x32_bf16 v[24:27], v[178:181], v[218:221], v[24:27]
	v_mfma_f32_16x16x32_bf16 v[16:19], v[170:173], v[226:229], v[16:19]
	v_mfma_f32_16x16x32_bf16 v[8:11], v[178:181], v[226:229], v[8:11]
	v_mfma_f32_16x16x32_bf16 v[52:55], v[182:185], v[198:201], v[52:55]
	v_mfma_f32_16x16x32_bf16 v[44:47], v[190:193], v[198:201], v[44:47]
	v_mfma_f32_16x16x32_bf16 v[36:39], v[182:185], v[206:209], v[36:39]
	v_mfma_f32_16x16x32_bf16 v[28:31], v[190:193], v[206:209], v[28:31]
	v_mfma_f32_16x16x32_bf16 v[20:23], v[182:185], v[214:217], v[20:23]
	v_mfma_f32_16x16x32_bf16 v[12:15], v[190:193], v[214:217], v[12:15]
	v_mfma_f32_16x16x32_bf16 v[4:7], v[182:185], v[222:225], v[4:7]
	v_mfma_f32_16x16x32_bf16 v[0:3], v[190:193], v[222:225], v[0:3]
	v_mfma_f32_16x16x32_bf16 v[52:55], v[186:189], v[202:205], v[52:55]
	v_mfma_f32_16x16x32_bf16 v[44:47], v[194:197], v[202:205], v[44:47]
	v_mfma_f32_16x16x32_bf16 v[36:39], v[186:189], v[210:213], v[36:39]
	v_mfma_f32_16x16x32_bf16 v[28:31], v[194:197], v[210:213], v[28:31]
	v_mfma_f32_16x16x32_bf16 v[20:23], v[186:189], v[218:221], v[20:23]
	v_mfma_f32_16x16x32_bf16 v[12:15], v[194:197], v[218:221], v[12:15]
	v_mfma_f32_16x16x32_bf16 v[4:7], v[186:189], v[226:229], v[4:7]
	v_mfma_f32_16x16x32_bf16 v[0:3], v[194:197], v[226:229], v[0:3]
	s_barrier
	s_setprio 0
	s_add_i32 s59, s59, 2
	s_add_u32 s57, s57, 0x100
	s_addc_u32 s58, s58, 0
	s_cmp_gt_u32 s59, 13
	s_mov_b64 s[24:25], s[26:27]
.LBB0_187:
	ds_read_b128 v[162:165], v157
	ds_read_b128 v[170:173], v157 offset:1024
	ds_read_b128 v[174:177], v157 offset:2048
	ds_read_b128 v[178:181], v157 offset:3072
	ds_read_b128 v[182:185], v158
	ds_read_b128 v[186:189], v158 offset:1024
	ds_read_b128 v[190:193], v158 offset:2048
	ds_read_b128 v[194:197], v158 offset:3072
	s_add_u32 s26, s24, 0x100
	s_addc_u32 s27, s25, 0
	s_cmp_eq_u32 s59, 12
	s_cselect_b32 s31, s17, s27
	s_cselect_b32 s30, s55, s26
	s_cselect_b32 s29, s15, s58
	s_cselect_b32 s28, s56, s57
	s_add_i32 m0, s23, 0xc000
	ds_read_b128 v[198:201], v159
	ds_read_b128 v[202:205], v159 offset:1024
	ds_read_b128 v[206:209], v159 offset:2048
	ds_read_b128 v[210:213], v159 offset:3072
	ds_read_b128 v[214:217], v159 offset:4096
	ds_read_b128 v[218:221], v159 offset:5120
	ds_read_b128 v[222:225], v159 offset:6144
	ds_read_b128 v[226:229], v159 offset:7168
	global_load_lds_dwordx4 v142, s[24:25]
	s_add_i32 m0, s23, 0xe000
	s_nop 0
	global_load_lds_dwordx4 v144, s[24:25]
	s_waitcnt vmcnt(8)
	s_waitcnt lgkmcnt(0)
	s_setprio 1
	s_barrier
	v_mfma_f32_16x16x32_bf16 v[124:127], v[162:165], v[198:201], v[124:127]
	v_mfma_f32_16x16x32_bf16 v[120:123], v[174:177], v[198:201], v[120:123]
	v_mfma_f32_16x16x32_bf16 v[112:115], v[162:165], v[206:209], v[112:115]
	v_mfma_f32_16x16x32_bf16 v[104:107], v[174:177], v[206:209], v[104:107]
	v_mfma_f32_16x16x32_bf16 v[96:99], v[162:165], v[214:217], v[96:99]
	v_mfma_f32_16x16x32_bf16 v[88:91], v[174:177], v[214:217], v[88:91]
	v_mfma_f32_16x16x32_bf16 v[80:83], v[162:165], v[222:225], v[80:83]
	v_mfma_f32_16x16x32_bf16 v[72:75], v[174:177], v[222:225], v[72:75]
	v_mfma_f32_16x16x32_bf16 v[124:127], v[170:173], v[202:205], v[124:127]
	v_mfma_f32_16x16x32_bf16 v[120:123], v[178:181], v[202:205], v[120:123]
	v_mfma_f32_16x16x32_bf16 v[112:115], v[170:173], v[210:213], v[112:115]
	v_mfma_f32_16x16x32_bf16 v[104:107], v[178:181], v[210:213], v[104:107]
	v_mfma_f32_16x16x32_bf16 v[96:99], v[170:173], v[218:221], v[96:99]
	v_mfma_f32_16x16x32_bf16 v[88:91], v[178:181], v[218:221], v[88:91]
	v_mfma_f32_16x16x32_bf16 v[80:83], v[170:173], v[226:229], v[80:83]
	v_mfma_f32_16x16x32_bf16 v[72:75], v[178:181], v[226:229], v[72:75]
	v_mfma_f32_16x16x32_bf16 v[116:119], v[182:185], v[198:201], v[116:119]
	v_mfma_f32_16x16x32_bf16 v[108:111], v[190:193], v[198:201], v[108:111]
	v_mfma_f32_16x16x32_bf16 v[100:103], v[182:185], v[206:209], v[100:103]
	v_mfma_f32_16x16x32_bf16 v[92:95], v[190:193], v[206:209], v[92:95]
	v_mfma_f32_16x16x32_bf16 v[84:87], v[182:185], v[214:217], v[84:87]
	v_mfma_f32_16x16x32_bf16 v[76:79], v[190:193], v[214:217], v[76:79]
	v_mfma_f32_16x16x32_bf16 v[68:71], v[182:185], v[222:225], v[68:71]
	v_mfma_f32_16x16x32_bf16 v[64:67], v[190:193], v[222:225], v[64:67]
	v_mfma_f32_16x16x32_bf16 v[116:119], v[186:189], v[202:205], v[116:119]
	v_mfma_f32_16x16x32_bf16 v[108:111], v[194:197], v[202:205], v[108:111]
	v_mfma_f32_16x16x32_bf16 v[100:103], v[186:189], v[210:213], v[100:103]
	v_mfma_f32_16x16x32_bf16 v[92:95], v[194:197], v[210:213], v[92:95]
	v_mfma_f32_16x16x32_bf16 v[84:87], v[186:189], v[218:221], v[84:87]
	v_mfma_f32_16x16x32_bf16 v[76:79], v[194:197], v[218:221], v[76:79]
	v_mfma_f32_16x16x32_bf16 v[68:71], v[186:189], v[226:229], v[68:71]
	v_mfma_f32_16x16x32_bf16 v[64:67], v[194:197], v[226:229], v[64:67]
	s_barrier
	s_setprio 0
	s_add_i32 s0, s51, s41
	v_lshl_add_u64 v[166:167], s[28:29], 0, v[130:131]
	s_mov_b32 m0, s0
	ds_read_b128 v[198:201], v159 offset:16384
	ds_read_b128 v[202:205], v159 offset:17408
	ds_read_b128 v[206:209], v159 offset:18432
	ds_read_b128 v[210:213], v159 offset:19456
	ds_read_b128 v[214:217], v159 offset:20480
	ds_read_b128 v[218:221], v159 offset:21504
	ds_read_b128 v[222:225], v159 offset:22528
	ds_read_b128 v[226:229], v159 offset:23552
	global_load_lds_dwordx4 v[166:167], off
	s_add_i32 m0, s0, 0x2000
	s_add_u32 s0, s28, 0x40000
	v_lshl_add_u64 v[230:231], s[28:29], 0, v[134:135]
	s_addc_u32 s1, s29, 0
	s_add_i32 s24, s52, s41
	global_load_lds_dwordx4 v[230:231], off
	s_mov_b32 m0, s24
	v_lshl_add_u64 v[234:235], s[30:31], 0, v[132:133]
	global_load_lds_dwordx4 v130, s[0:1]
	s_add_i32 m0, s24, 0x2000
	s_nop 0
	global_load_lds_dwordx4 v134, s[0:1]
	v_lshl_add_u64 v[232:233], s[30:31], 0, v[128:129]
	s_waitcnt vmcnt(6)
	s_waitcnt lgkmcnt(0)
	s_setprio 1
	s_barrier
	v_mfma_f32_16x16x32_bf16 v[60:63], v[162:165], v[198:201], v[60:63]
	v_mfma_f32_16x16x32_bf16 v[56:59], v[174:177], v[198:201], v[56:59]
	v_mfma_f32_16x16x32_bf16 v[48:51], v[162:165], v[206:209], v[48:51]
	v_mfma_f32_16x16x32_bf16 v[40:43], v[174:177], v[206:209], v[40:43]
	v_mfma_f32_16x16x32_bf16 v[32:35], v[162:165], v[214:217], v[32:35]
	v_mfma_f32_16x16x32_bf16 v[24:27], v[174:177], v[214:217], v[24:27]
	v_mfma_f32_16x16x32_bf16 v[16:19], v[162:165], v[222:225], v[16:19]
	v_mfma_f32_16x16x32_bf16 v[8:11], v[174:177], v[222:225], v[8:11]
	v_mfma_f32_16x16x32_bf16 v[60:63], v[170:173], v[202:205], v[60:63]
	v_mfma_f32_16x16x32_bf16 v[56:59], v[178:181], v[202:205], v[56:59]
	v_mfma_f32_16x16x32_bf16 v[48:51], v[170:173], v[210:213], v[48:51]
	v_mfma_f32_16x16x32_bf16 v[40:43], v[178:181], v[210:213], v[40:43]
	v_mfma_f32_16x16x32_bf16 v[32:35], v[170:173], v[218:221], v[32:35]
	v_mfma_f32_16x16x32_bf16 v[24:27], v[178:181], v[218:221], v[24:27]
	v_mfma_f32_16x16x32_bf16 v[16:19], v[170:173], v[226:229], v[16:19]
	v_mfma_f32_16x16x32_bf16 v[8:11], v[178:181], v[226:229], v[8:11]
	v_mfma_f32_16x16x32_bf16 v[52:55], v[182:185], v[198:201], v[52:55]
	v_mfma_f32_16x16x32_bf16 v[44:47], v[190:193], v[198:201], v[44:47]
	v_mfma_f32_16x16x32_bf16 v[36:39], v[182:185], v[206:209], v[36:39]
	v_mfma_f32_16x16x32_bf16 v[28:31], v[190:193], v[206:209], v[28:31]
	v_mfma_f32_16x16x32_bf16 v[20:23], v[182:185], v[214:217], v[20:23]
	v_mfma_f32_16x16x32_bf16 v[12:15], v[190:193], v[214:217], v[12:15]
	v_mfma_f32_16x16x32_bf16 v[4:7], v[182:185], v[222:225], v[4:7]
	v_mfma_f32_16x16x32_bf16 v[0:3], v[190:193], v[222:225], v[0:3]
	v_mfma_f32_16x16x32_bf16 v[52:55], v[186:189], v[202:205], v[52:55]
	v_mfma_f32_16x16x32_bf16 v[44:47], v[194:197], v[202:205], v[44:47]
	v_mfma_f32_16x16x32_bf16 v[36:39], v[186:189], v[210:213], v[36:39]
	v_mfma_f32_16x16x32_bf16 v[28:31], v[194:197], v[210:213], v[28:31]
	v_mfma_f32_16x16x32_bf16 v[20:23], v[186:189], v[218:221], v[20:23]
	v_mfma_f32_16x16x32_bf16 v[12:15], v[194:197], v[218:221], v[12:15]
	v_mfma_f32_16x16x32_bf16 v[4:7], v[186:189], v[226:229], v[4:7]
	v_mfma_f32_16x16x32_bf16 v[0:3], v[194:197], v[226:229], v[0:3]
	s_barrier
	s_setprio 0
	s_add_i32 s24, 0, 0x18000
	v_add_u32_e32 v150, s24, v153
	s_add_i32 s25, 0, 0x1c000
	ds_read_b128 v[162:165], v150
	ds_read_b128 v[170:173], v150 offset:1024
	ds_read_b128 v[174:177], v150 offset:2048
	ds_read_b128 v[178:181], v150 offset:3072
	v_add_u32_e32 v150, s25, v153
	ds_read_b128 v[182:185], v150
	ds_read_b128 v[186:189], v150 offset:1024
	ds_read_b128 v[190:193], v150 offset:2048
	ds_read_b128 v[194:197], v150 offset:3072
	s_add_u32 s0, s30, 0x40000
	s_addc_u32 s1, s31, 0
	s_mov_b32 m0, s43
	ds_read_b128 v[198:201], v159 offset:32768
	ds_read_b128 v[202:205], v159 offset:33792
	ds_read_b128 v[206:209], v159 offset:34816
	ds_read_b128 v[210:213], v159 offset:35840
	ds_read_b128 v[214:217], v159 offset:36864
	ds_read_b128 v[218:221], v159 offset:37888
	ds_read_b128 v[222:225], v159 offset:38912
	ds_read_b128 v[226:229], v159 offset:39936
	global_load_lds_dwordx4 v128, s[0:1]
	s_mov_b32 m0, s44
	s_nop 0
	global_load_lds_dwordx4 v132, s[0:1]
	s_mov_b32 m0, s23
	s_nop 0
	global_load_lds_dwordx4 v[232:233], off
	s_mov_b32 m0, s42
	s_nop 0
	global_load_lds_dwordx4 v[234:235], off
	s_waitcnt vmcnt(8)
	s_waitcnt lgkmcnt(0)
	s_setprio 1
	s_barrier
	v_mfma_f32_16x16x32_bf16 v[124:127], v[162:165], v[198:201], v[124:127]
	v_mfma_f32_16x16x32_bf16 v[120:123], v[174:177], v[198:201], v[120:123]
	v_mfma_f32_16x16x32_bf16 v[112:115], v[162:165], v[206:209], v[112:115]
	v_mfma_f32_16x16x32_bf16 v[104:107], v[174:177], v[206:209], v[104:107]
	v_mfma_f32_16x16x32_bf16 v[96:99], v[162:165], v[214:217], v[96:99]
	v_mfma_f32_16x16x32_bf16 v[88:91], v[174:177], v[214:217], v[88:91]
	v_mfma_f32_16x16x32_bf16 v[80:83], v[162:165], v[222:225], v[80:83]
	v_mfma_f32_16x16x32_bf16 v[72:75], v[174:177], v[222:225], v[72:75]
	v_mfma_f32_16x16x32_bf16 v[124:127], v[170:173], v[202:205], v[124:127]
	v_mfma_f32_16x16x32_bf16 v[120:123], v[178:181], v[202:205], v[120:123]
	v_mfma_f32_16x16x32_bf16 v[112:115], v[170:173], v[210:213], v[112:115]
	v_mfma_f32_16x16x32_bf16 v[104:107], v[178:181], v[210:213], v[104:107]
	v_mfma_f32_16x16x32_bf16 v[96:99], v[170:173], v[218:221], v[96:99]
	v_mfma_f32_16x16x32_bf16 v[88:91], v[178:181], v[218:221], v[88:91]
	v_mfma_f32_16x16x32_bf16 v[80:83], v[170:173], v[226:229], v[80:83]
	v_mfma_f32_16x16x32_bf16 v[72:75], v[178:181], v[226:229], v[72:75]
	v_mfma_f32_16x16x32_bf16 v[116:119], v[182:185], v[198:201], v[116:119]
	v_mfma_f32_16x16x32_bf16 v[108:111], v[190:193], v[198:201], v[108:111]
	v_mfma_f32_16x16x32_bf16 v[100:103], v[182:185], v[206:209], v[100:103]
	v_mfma_f32_16x16x32_bf16 v[92:95], v[190:193], v[206:209], v[92:95]
	v_mfma_f32_16x16x32_bf16 v[84:87], v[182:185], v[214:217], v[84:87]
	v_mfma_f32_16x16x32_bf16 v[76:79], v[190:193], v[214:217], v[76:79]
	v_mfma_f32_16x16x32_bf16 v[68:71], v[182:185], v[222:225], v[68:71]
	v_mfma_f32_16x16x32_bf16 v[64:67], v[190:193], v[222:225], v[64:67]
	v_mfma_f32_16x16x32_bf16 v[116:119], v[186:189], v[202:205], v[116:119]
	v_mfma_f32_16x16x32_bf16 v[108:111], v[194:197], v[202:205], v[108:111]
	v_mfma_f32_16x16x32_bf16 v[100:103], v[186:189], v[210:213], v[100:103]
	v_mfma_f32_16x16x32_bf16 v[92:95], v[194:197], v[210:213], v[92:95]
	v_mfma_f32_16x16x32_bf16 v[84:87], v[186:189], v[218:221], v[84:87]
	v_mfma_f32_16x16x32_bf16 v[76:79], v[194:197], v[218:221], v[76:79]
	v_mfma_f32_16x16x32_bf16 v[68:71], v[186:189], v[226:229], v[68:71]
	v_mfma_f32_16x16x32_bf16 v[64:67], v[194:197], v[226:229], v[64:67]
	s_barrier
	s_setprio 0
	s_add_i32 s0, s24, s41
	v_lshl_add_u64 v[166:167], v[166:167], 0, s[8:9]
	s_mov_b32 m0, s0
	ds_read_b128 v[198:201], v159 offset:49152
	ds_read_b128 v[202:205], v159 offset:50176
	ds_read_b128 v[206:209], v159 offset:51200
	ds_read_b128 v[210:213], v159 offset:52224
	ds_read_b128 v[214:217], v159 offset:53248
	ds_read_b128 v[218:221], v159 offset:54272
	ds_read_b128 v[222:225], v159 offset:55296
	ds_read_b128 v[226:229], v159 offset:56320
	global_load_lds_dwordx4 v[166:167], off
	s_add_i32 m0, s0, 0x2000
	s_add_u32 s0, s28, 0x40080
	v_lshl_add_u64 v[166:167], v[230:231], 0, s[8:9]
	s_addc_u32 s1, s29, 0
	s_add_i32 s24, s25, s41
	global_load_lds_dwordx4 v[166:167], off
	s_mov_b32 m0, s24
	s_nop 0
	global_load_lds_dwordx4 v130, s[0:1]
	s_add_i32 m0, s24, 0x2000
	s_nop 0
	global_load_lds_dwordx4 v134, s[0:1]
	v_lshl_add_u64 v[166:167], v[232:233], 0, s[8:9]
	s_mov_b32 m0, s47
	s_nop 0
	global_load_lds_dwordx4 v[166:167], off
	v_lshl_add_u64 v[166:167], v[234:235], 0, s[8:9]
	s_mov_b32 m0, s48
	s_nop 0
	global_load_lds_dwordx4 v[166:167], off
	s_waitcnt vmcnt(6)
	s_waitcnt lgkmcnt(0)
	s_setprio 1
	s_barrier
	v_mfma_f32_16x16x32_bf16 v[60:63], v[162:165], v[198:201], v[60:63]
	v_mfma_f32_16x16x32_bf16 v[56:59], v[174:177], v[198:201], v[56:59]
	v_mfma_f32_16x16x32_bf16 v[48:51], v[162:165], v[206:209], v[48:51]
	v_mfma_f32_16x16x32_bf16 v[40:43], v[174:177], v[206:209], v[40:43]
	v_mfma_f32_16x16x32_bf16 v[32:35], v[162:165], v[214:217], v[32:35]
	v_mfma_f32_16x16x32_bf16 v[24:27], v[174:177], v[214:217], v[24:27]
	v_mfma_f32_16x16x32_bf16 v[16:19], v[162:165], v[222:225], v[16:19]
	v_mfma_f32_16x16x32_bf16 v[8:11], v[174:177], v[222:225], v[8:11]
	v_mfma_f32_16x16x32_bf16 v[60:63], v[170:173], v[202:205], v[60:63]
	v_mfma_f32_16x16x32_bf16 v[56:59], v[178:181], v[202:205], v[56:59]
	v_mfma_f32_16x16x32_bf16 v[48:51], v[170:173], v[210:213], v[48:51]
	v_mfma_f32_16x16x32_bf16 v[40:43], v[178:181], v[210:213], v[40:43]
	v_mfma_f32_16x16x32_bf16 v[32:35], v[170:173], v[218:221], v[32:35]
	v_mfma_f32_16x16x32_bf16 v[24:27], v[178:181], v[218:221], v[24:27]
	v_mfma_f32_16x16x32_bf16 v[16:19], v[170:173], v[226:229], v[16:19]
	v_mfma_f32_16x16x32_bf16 v[8:11], v[178:181], v[226:229], v[8:11]
	v_mfma_f32_16x16x32_bf16 v[52:55], v[182:185], v[198:201], v[52:55]
	v_mfma_f32_16x16x32_bf16 v[44:47], v[190:193], v[198:201], v[44:47]
	v_mfma_f32_16x16x32_bf16 v[36:39], v[182:185], v[206:209], v[36:39]
	v_mfma_f32_16x16x32_bf16 v[28:31], v[190:193], v[206:209], v[28:31]
	v_mfma_f32_16x16x32_bf16 v[20:23], v[182:185], v[214:217], v[20:23]
	v_mfma_f32_16x16x32_bf16 v[12:15], v[190:193], v[214:217], v[12:15]
	v_mfma_f32_16x16x32_bf16 v[4:7], v[182:185], v[222:225], v[4:7]
	v_mfma_f32_16x16x32_bf16 v[0:3], v[190:193], v[222:225], v[0:3]
	v_mfma_f32_16x16x32_bf16 v[52:55], v[186:189], v[202:205], v[52:55]
	v_mfma_f32_16x16x32_bf16 v[44:47], v[194:197], v[202:205], v[44:47]
	v_mfma_f32_16x16x32_bf16 v[36:39], v[186:189], v[210:213], v[36:39]
	v_mfma_f32_16x16x32_bf16 v[28:31], v[194:197], v[210:213], v[28:31]
	v_mfma_f32_16x16x32_bf16 v[20:23], v[186:189], v[218:221], v[20:23]
	v_mfma_f32_16x16x32_bf16 v[12:15], v[194:197], v[218:221], v[12:15]
	v_mfma_f32_16x16x32_bf16 v[4:7], v[186:189], v[226:229], v[4:7]
	v_mfma_f32_16x16x32_bf16 v[0:3], v[194:197], v[226:229], v[0:3]
	s_barrier
	s_setprio 0
	s_add_i32 s59, s59, 2
	s_add_u32 s57, s57, 0x100
	s_addc_u32 s58, s58, 0
	s_cmp_gt_u32 s59, 13
	s_mov_b64 s[24:25], s[26:27]
	s_cbranch_scc0 .LBB0_187
	s_and_b64 vcc, exec, s[12:13]
	s_cbranch_vccz .LBB0_190
	s_barrier

.Lrestag_265:
	ds_read_b128 v[86:89], v84
	ds_read_b128 v[90:93], v84 offset:1024
	ds_read_b128 v[94:97], v84 offset:2048
	ds_read_b128 v[98:101], v84 offset:3072
	s_add_u32 s6, s20, 0x100
	s_addc_u32 s7, s21, 0
	s_cmp_eq_u32 s53, 4
	s_cselect_b32 s25, s17, s7
	s_cselect_b32 s24, s16, s6
	s_cselect_b32 s23, s15, s52
	s_cselect_b32 s22, s50, s51
	s_add_i32 m0, s34, 0xc000
	ds_read_b128 v[102:105], v85
	ds_read_b128 v[106:109], v85 offset:1024
	ds_read_b128 v[110:113], v85 offset:2048
	ds_read_b128 v[114:117], v85 offset:3072
	ds_read_b128 v[118:121], v85 offset:4096
	ds_read_b128 v[122:125], v85 offset:5120
	ds_read_b128 v[126:129], v85 offset:6144
	ds_read_b128 v[130:133], v85 offset:7168
	global_load_lds_dwordx4 v74, s[20:21]
	s_add_i32 m0, s34, 0xe000
	s_nop 0
	global_load_lds_dwordx4 v76, s[20:21]
	s_waitcnt vmcnt(8)
	s_waitcnt lgkmcnt(0)
	s_setprio 1
	s_barrier
	v_mfma_f32_16x16x32_bf16 v[60:63], v[86:89], v[102:105], 0
	v_mfma_f32_16x16x32_bf16 v[56:59], v[94:97], v[102:105], 0
	v_mfma_f32_16x16x32_bf16 v[52:55], v[86:89], v[110:113], 0
	v_mfma_f32_16x16x32_bf16 v[48:51], v[94:97], v[110:113], 0
	v_mfma_f32_16x16x32_bf16 v[44:47], v[86:89], v[118:121], 0
	v_mfma_f32_16x16x32_bf16 v[40:43], v[94:97], v[118:121], 0
	v_mfma_f32_16x16x32_bf16 v[36:39], v[86:89], v[126:129], 0
	v_mfma_f32_16x16x32_bf16 v[32:35], v[94:97], v[126:129], 0
	v_mfma_f32_16x16x32_bf16 v[60:63], v[90:93], v[106:109], v[60:63]
	v_mfma_f32_16x16x32_bf16 v[56:59], v[98:101], v[106:109], v[56:59]
	v_mfma_f32_16x16x32_bf16 v[52:55], v[90:93], v[114:117], v[52:55]
	v_mfma_f32_16x16x32_bf16 v[48:51], v[98:101], v[114:117], v[48:51]
	v_mfma_f32_16x16x32_bf16 v[44:47], v[90:93], v[122:125], v[44:47]
	v_mfma_f32_16x16x32_bf16 v[40:43], v[98:101], v[122:125], v[40:43]
	v_mfma_f32_16x16x32_bf16 v[36:39], v[90:93], v[130:133], v[36:39]
	v_mfma_f32_16x16x32_bf16 v[32:35], v[98:101], v[130:133], v[32:35]
	s_setprio 0
	s_setprio 1
	s_setprio 0
	s_barrier
	s_add_i32 s20, s48, s33
	v_lshl_add_u64 v[134:135], s[22:23], 0, v[66:67]
	s_mov_b32 m0, s20
	ds_read_b128 v[102:105], v85 offset:16384
	ds_read_b128 v[106:109], v85 offset:17408
	ds_read_b128 v[110:113], v85 offset:18432
	ds_read_b128 v[114:117], v85 offset:19456
	ds_read_b128 v[118:121], v85 offset:20480
	ds_read_b128 v[122:125], v85 offset:21504
	ds_read_b128 v[126:129], v85 offset:22528
	ds_read_b128 v[130:133], v85 offset:23552
	global_load_lds_dwordx4 v[134:135], off
	s_add_i32 m0, s20, 0x2000
	s_add_u32 s20, s22, 0x20000
	v_lshl_add_u64 v[136:137], s[22:23], 0, v[70:71]
	s_addc_u32 s21, s23, 0
	global_load_lds_dwordx4 v[136:137], off
	s_mov_b32 m0, s35
	v_lshl_add_u64 v[140:141], s[24:25], 0, v[68:69]
	global_load_lds_dwordx4 v66, s[20:21]
	s_mov_b32 m0, s36
	s_nop 0
	global_load_lds_dwordx4 v70, s[20:21]
	v_lshl_add_u64 v[138:139], s[24:25], 0, v[64:65]
	s_mov_b32 m0, s34
	s_nop 0
	global_load_lds_dwordx4 v[138:139], off
	s_mov_b32 m0, s0
	s_nop 0
	global_load_lds_dwordx4 v[140:141], off
	s_waitcnt vmcnt(8)
	s_waitcnt lgkmcnt(0)
	s_setprio 1
	s_barrier
	v_mfma_f32_16x16x32_bf16 v[28:31], v[86:89], v[102:105], 0
	v_mfma_f32_16x16x32_bf16 v[24:27], v[94:97], v[102:105], 0
	v_mfma_f32_16x16x32_bf16 v[20:23], v[86:89], v[110:113], 0
	v_mfma_f32_16x16x32_bf16 v[16:19], v[94:97], v[110:113], 0
	v_mfma_f32_16x16x32_bf16 v[12:15], v[86:89], v[118:121], 0
	v_mfma_f32_16x16x32_bf16 v[8:11], v[94:97], v[118:121], 0
	v_mfma_f32_16x16x32_bf16 v[4:7], v[86:89], v[126:129], 0
	v_mfma_f32_16x16x32_bf16 v[0:3], v[94:97], v[126:129], 0
	v_mfma_f32_16x16x32_bf16 v[28:31], v[90:93], v[106:109], v[28:31]
	v_mfma_f32_16x16x32_bf16 v[24:27], v[98:101], v[106:109], v[24:27]
	v_mfma_f32_16x16x32_bf16 v[20:23], v[90:93], v[114:117], v[20:23]
	v_mfma_f32_16x16x32_bf16 v[16:19], v[98:101], v[114:117], v[16:19]
	v_mfma_f32_16x16x32_bf16 v[12:15], v[90:93], v[122:125], v[12:15]
	v_mfma_f32_16x16x32_bf16 v[8:11], v[98:101], v[122:125], v[8:11]
	v_mfma_f32_16x16x32_bf16 v[4:7], v[90:93], v[130:133], v[4:7]
	v_mfma_f32_16x16x32_bf16 v[0:3], v[98:101], v[130:133], v[0:3]
	s_setprio 0
	s_setprio 1
	s_setprio 0
	s_barrier
	s_add_i32 s54, 0, 0x18000
	v_add_u32_e32 v98, s54, v83
	ds_read_b128 v[86:89], v98
	ds_read_b128 v[90:93], v98 offset:1024
	ds_read_b128 v[94:97], v98 offset:2048
	ds_read_b128 v[98:101], v98 offset:3072
	s_add_u32 s20, s24, 0x28000
	s_addc_u32 s21, s25, 0
	s_mov_b32 m0, s1
	ds_read_b128 v[102:105], v85 offset:32768
	ds_read_b128 v[106:109], v85 offset:33792
	ds_read_b128 v[110:113], v85 offset:34816
	ds_read_b128 v[114:117], v85 offset:35840
	ds_read_b128 v[118:121], v85 offset:36864
	ds_read_b128 v[122:125], v85 offset:37888
	ds_read_b128 v[126:129], v85 offset:38912
	ds_read_b128 v[130:133], v85 offset:39936
	global_load_lds_dwordx4 v64, s[20:21]
	s_mov_b32 m0, s37
	s_nop 0
	global_load_lds_dwordx4 v68, s[20:21]
	s_waitcnt vmcnt(8)
	s_waitcnt lgkmcnt(0)
	s_setprio 1
	s_barrier
	v_mfma_f32_16x16x32_bf16 v[60:63], v[86:89], v[102:105], v[60:63]
	v_mfma_f32_16x16x32_bf16 v[56:59], v[94:97], v[102:105], v[56:59]
	v_mfma_f32_16x16x32_bf16 v[52:55], v[86:89], v[110:113], v[52:55]
	v_mfma_f32_16x16x32_bf16 v[48:51], v[94:97], v[110:113], v[48:51]
	v_mfma_f32_16x16x32_bf16 v[44:47], v[86:89], v[118:121], v[44:47]
	v_mfma_f32_16x16x32_bf16 v[40:43], v[94:97], v[118:121], v[40:43]
	v_mfma_f32_16x16x32_bf16 v[36:39], v[86:89], v[126:129], v[36:39]
	v_mfma_f32_16x16x32_bf16 v[32:35], v[94:97], v[126:129], v[32:35]
	v_mfma_f32_16x16x32_bf16 v[60:63], v[90:93], v[106:109], v[60:63]
	v_mfma_f32_16x16x32_bf16 v[56:59], v[98:101], v[106:109], v[56:59]
	v_mfma_f32_16x16x32_bf16 v[52:55], v[90:93], v[114:117], v[52:55]
	v_mfma_f32_16x16x32_bf16 v[48:51], v[98:101], v[114:117], v[48:51]
	v_mfma_f32_16x16x32_bf16 v[44:47], v[90:93], v[122:125], v[44:47]
	v_mfma_f32_16x16x32_bf16 v[40:43], v[98:101], v[122:125], v[40:43]
	v_mfma_f32_16x16x32_bf16 v[36:39], v[90:93], v[130:133], v[36:39]
	v_mfma_f32_16x16x32_bf16 v[32:35], v[98:101], v[130:133], v[32:35]
	s_setprio 0
	s_setprio 1
	s_setprio 0
	s_barrier
	s_add_i32 s20, s54, s33
	v_lshl_add_u64 v[134:135], v[134:135], 0, s[8:9]
	s_mov_b32 m0, s20
	ds_read_b128 v[102:105], v85 offset:49152
	ds_read_b128 v[106:109], v85 offset:50176
	ds_read_b128 v[110:113], v85 offset:51200
	ds_read_b128 v[114:117], v85 offset:52224
	ds_read_b128 v[118:121], v85 offset:53248
	ds_read_b128 v[122:125], v85 offset:54272
	ds_read_b128 v[126:129], v85 offset:55296
	ds_read_b128 v[130:133], v85 offset:56320
	global_load_lds_dwordx4 v[134:135], off
	s_add_i32 m0, s20, 0x2000
	s_add_u32 s20, s22, 0x20080
	v_lshl_add_u64 v[134:135], v[136:137], 0, s[8:9]
	s_addc_u32 s21, s23, 0
	global_load_lds_dwordx4 v[134:135], off
	s_mov_b32 m0, s44
	s_nop 0
	global_load_lds_dwordx4 v66, s[20:21]
	s_mov_b32 m0, s45
	s_nop 0
	global_load_lds_dwordx4 v70, s[20:21]
	v_lshl_add_u64 v[134:135], v[138:139], 0, s[8:9]
	s_mov_b32 m0, s42
	s_nop 0
	global_load_lds_dwordx4 v[134:135], off
	v_lshl_add_u64 v[134:135], v[140:141], 0, s[8:9]
	s_mov_b32 m0, s43
	s_nop 0
	global_load_lds_dwordx4 v[134:135], off
	s_waitcnt vmcnt(8)
	s_waitcnt lgkmcnt(0)
	s_setprio 1
	s_barrier
	v_mfma_f32_16x16x32_bf16 v[28:31], v[86:89], v[102:105], v[28:31]
	v_mfma_f32_16x16x32_bf16 v[24:27], v[94:97], v[102:105], v[24:27]
	v_mfma_f32_16x16x32_bf16 v[20:23], v[86:89], v[110:113], v[20:23]
	v_mfma_f32_16x16x32_bf16 v[16:19], v[94:97], v[110:113], v[16:19]
	v_mfma_f32_16x16x32_bf16 v[12:15], v[86:89], v[118:121], v[12:15]
	v_mfma_f32_16x16x32_bf16 v[8:11], v[94:97], v[118:121], v[8:11]
	v_mfma_f32_16x16x32_bf16 v[4:7], v[86:89], v[126:129], v[4:7]
	v_mfma_f32_16x16x32_bf16 v[0:3], v[94:97], v[126:129], v[0:3]
	v_mfma_f32_16x16x32_bf16 v[28:31], v[90:93], v[106:109], v[28:31]
	v_mfma_f32_16x16x32_bf16 v[24:27], v[98:101], v[106:109], v[24:27]
	v_mfma_f32_16x16x32_bf16 v[20:23], v[90:93], v[114:117], v[20:23]
	v_mfma_f32_16x16x32_bf16 v[16:19], v[98:101], v[114:117], v[16:19]
	v_mfma_f32_16x16x32_bf16 v[12:15], v[90:93], v[122:125], v[12:15]
	v_mfma_f32_16x16x32_bf16 v[8:11], v[98:101], v[122:125], v[8:11]
	v_mfma_f32_16x16x32_bf16 v[4:7], v[90:93], v[130:133], v[4:7]
	v_mfma_f32_16x16x32_bf16 v[0:3], v[98:101], v[130:133], v[0:3]
	s_setprio 0
	s_setprio 1
	s_setprio 0
	s_barrier
	s_add_i32 s53, s53, 2
	s_add_u32 s51, s51, 0x100
	s_addc_u32 s52, s52, 0
	s_cmp_gt_u32 s53, 5
	s_mov_b64 s[20:21], s[6:7]
.LBB0_265:
	ds_read_b128 v[86:89], v84
	ds_read_b128 v[90:93], v84 offset:1024
	ds_read_b128 v[94:97], v84 offset:2048
	ds_read_b128 v[98:101], v84 offset:3072
	s_add_u32 s6, s20, 0x100
	s_addc_u32 s7, s21, 0
	s_cmp_eq_u32 s53, 4
	s_cselect_b32 s25, s17, s7
	s_cselect_b32 s24, s16, s6
	s_cselect_b32 s23, s15, s52
	s_cselect_b32 s22, s50, s51
	s_add_i32 m0, s34, 0xc000
	ds_read_b128 v[102:105], v85
	ds_read_b128 v[106:109], v85 offset:1024
	ds_read_b128 v[110:113], v85 offset:2048
	ds_read_b128 v[114:117], v85 offset:3072
	ds_read_b128 v[118:121], v85 offset:4096
	ds_read_b128 v[122:125], v85 offset:5120
	ds_read_b128 v[126:129], v85 offset:6144
	ds_read_b128 v[130:133], v85 offset:7168
	global_load_lds_dwordx4 v74, s[20:21]
	s_add_i32 m0, s34, 0xe000
	s_nop 0
	global_load_lds_dwordx4 v76, s[20:21]
	s_waitcnt vmcnt(8)
	s_waitcnt lgkmcnt(0)
	s_setprio 1
	s_barrier
	v_mfma_f32_16x16x32_bf16 v[60:63], v[86:89], v[102:105], v[60:63]
	v_mfma_f32_16x16x32_bf16 v[56:59], v[94:97], v[102:105], v[56:59]
	v_mfma_f32_16x16x32_bf16 v[52:55], v[86:89], v[110:113], v[52:55]
	v_mfma_f32_16x16x32_bf16 v[48:51], v[94:97], v[110:113], v[48:51]
	v_mfma_f32_16x16x32_bf16 v[44:47], v[86:89], v[118:121], v[44:47]
	v_mfma_f32_16x16x32_bf16 v[40:43], v[94:97], v[118:121], v[40:43]
	v_mfma_f32_16x16x32_bf16 v[36:39], v[86:89], v[126:129], v[36:39]
	v_mfma_f32_16x16x32_bf16 v[32:35], v[94:97], v[126:129], v[32:35]
	v_mfma_f32_16x16x32_bf16 v[60:63], v[90:93], v[106:109], v[60:63]
	v_mfma_f32_16x16x32_bf16 v[56:59], v[98:101], v[106:109], v[56:59]
	v_mfma_f32_16x16x32_bf16 v[52:55], v[90:93], v[114:117], v[52:55]
	v_mfma_f32_16x16x32_bf16 v[48:51], v[98:101], v[114:117], v[48:51]
	v_mfma_f32_16x16x32_bf16 v[44:47], v[90:93], v[122:125], v[44:47]
	v_mfma_f32_16x16x32_bf16 v[40:43], v[98:101], v[122:125], v[40:43]
	v_mfma_f32_16x16x32_bf16 v[36:39], v[90:93], v[130:133], v[36:39]
	v_mfma_f32_16x16x32_bf16 v[32:35], v[98:101], v[130:133], v[32:35]
	s_setprio 0
	s_setprio 1
	s_setprio 0
	s_barrier
	s_add_i32 s20, s48, s33
	v_lshl_add_u64 v[134:135], s[22:23], 0, v[66:67]
	s_mov_b32 m0, s20
	ds_read_b128 v[102:105], v85 offset:16384
	ds_read_b128 v[106:109], v85 offset:17408
	ds_read_b128 v[110:113], v85 offset:18432
	ds_read_b128 v[114:117], v85 offset:19456
	ds_read_b128 v[118:121], v85 offset:20480
	ds_read_b128 v[122:125], v85 offset:21504
	ds_read_b128 v[126:129], v85 offset:22528
	ds_read_b128 v[130:133], v85 offset:23552
	global_load_lds_dwordx4 v[134:135], off
	s_add_i32 m0, s20, 0x2000
	s_add_u32 s20, s22, 0x20000
	v_lshl_add_u64 v[136:137], s[22:23], 0, v[70:71]
	s_addc_u32 s21, s23, 0
	global_load_lds_dwordx4 v[136:137], off
	s_mov_b32 m0, s35
	v_lshl_add_u64 v[140:141], s[24:25], 0, v[68:69]
	global_load_lds_dwordx4 v66, s[20:21]
	s_mov_b32 m0, s36
	s_nop 0
	global_load_lds_dwordx4 v70, s[20:21]
	v_lshl_add_u64 v[138:139], s[24:25], 0, v[64:65]
	s_mov_b32 m0, s34
	s_nop 0
	global_load_lds_dwordx4 v[138:139], off
	s_mov_b32 m0, s0
	s_nop 0
	global_load_lds_dwordx4 v[140:141], off
	s_waitcnt vmcnt(8)
	s_waitcnt lgkmcnt(0)
	s_setprio 1
	s_barrier
	v_mfma_f32_16x16x32_bf16 v[28:31], v[86:89], v[102:105], v[28:31]
	v_mfma_f32_16x16x32_bf16 v[24:27], v[94:97], v[102:105], v[24:27]
	v_mfma_f32_16x16x32_bf16 v[20:23], v[86:89], v[110:113], v[20:23]
	v_mfma_f32_16x16x32_bf16 v[16:19], v[94:97], v[110:113], v[16:19]
	v_mfma_f32_16x16x32_bf16 v[12:15], v[86:89], v[118:121], v[12:15]
	v_mfma_f32_16x16x32_bf16 v[8:11], v[94:97], v[118:121], v[8:11]
	v_mfma_f32_16x16x32_bf16 v[4:7], v[86:89], v[126:129], v[4:7]
	v_mfma_f32_16x16x32_bf16 v[0:3], v[94:97], v[126:129], v[0:3]
	v_mfma_f32_16x16x32_bf16 v[28:31], v[90:93], v[106:109], v[28:31]
	v_mfma_f32_16x16x32_bf16 v[24:27], v[98:101], v[106:109], v[24:27]
	v_mfma_f32_16x16x32_bf16 v[20:23], v[90:93], v[114:117], v[20:23]
	v_mfma_f32_16x16x32_bf16 v[16:19], v[98:101], v[114:117], v[16:19]
	v_mfma_f32_16x16x32_bf16 v[12:15], v[90:93], v[122:125], v[12:15]
	v_mfma_f32_16x16x32_bf16 v[8:11], v[98:101], v[122:125], v[8:11]
	v_mfma_f32_16x16x32_bf16 v[4:7], v[90:93], v[130:133], v[4:7]
	v_mfma_f32_16x16x32_bf16 v[0:3], v[98:101], v[130:133], v[0:3]
	s_setprio 0
	s_setprio 1
	s_setprio 0
	s_barrier
	s_add_i32 s54, 0, 0x18000
	v_add_u32_e32 v98, s54, v83
	ds_read_b128 v[86:89], v98
	ds_read_b128 v[90:93], v98 offset:1024
	ds_read_b128 v[94:97], v98 offset:2048
	ds_read_b128 v[98:101], v98 offset:3072
	s_add_u32 s20, s24, 0x28000
	s_addc_u32 s21, s25, 0
	s_mov_b32 m0, s1
	ds_read_b128 v[102:105], v85 offset:32768
	ds_read_b128 v[106:109], v85 offset:33792
	ds_read_b128 v[110:113], v85 offset:34816
	ds_read_b128 v[114:117], v85 offset:35840
	ds_read_b128 v[118:121], v85 offset:36864
	ds_read_b128 v[122:125], v85 offset:37888
	ds_read_b128 v[126:129], v85 offset:38912
	ds_read_b128 v[130:133], v85 offset:39936
	global_load_lds_dwordx4 v64, s[20:21]
	s_mov_b32 m0, s37
	s_nop 0
	global_load_lds_dwordx4 v68, s[20:21]
	s_waitcnt vmcnt(8)
	s_waitcnt lgkmcnt(0)
	s_setprio 1
	s_barrier
	v_mfma_f32_16x16x32_bf16 v[60:63], v[86:89], v[102:105], v[60:63]
	v_mfma_f32_16x16x32_bf16 v[56:59], v[94:97], v[102:105], v[56:59]
	v_mfma_f32_16x16x32_bf16 v[52:55], v[86:89], v[110:113], v[52:55]
	v_mfma_f32_16x16x32_bf16 v[48:51], v[94:97], v[110:113], v[48:51]
	v_mfma_f32_16x16x32_bf16 v[44:47], v[86:89], v[118:121], v[44:47]
	v_mfma_f32_16x16x32_bf16 v[40:43], v[94:97], v[118:121], v[40:43]
	v_mfma_f32_16x16x32_bf16 v[36:39], v[86:89], v[126:129], v[36:39]
	v_mfma_f32_16x16x32_bf16 v[32:35], v[94:97], v[126:129], v[32:35]
	v_mfma_f32_16x16x32_bf16 v[60:63], v[90:93], v[106:109], v[60:63]
	v_mfma_f32_16x16x32_bf16 v[56:59], v[98:101], v[106:109], v[56:59]
	v_mfma_f32_16x16x32_bf16 v[52:55], v[90:93], v[114:117], v[52:55]
	v_mfma_f32_16x16x32_bf16 v[48:51], v[98:101], v[114:117], v[48:51]
	v_mfma_f32_16x16x32_bf16 v[44:47], v[90:93], v[122:125], v[44:47]
	v_mfma_f32_16x16x32_bf16 v[40:43], v[98:101], v[122:125], v[40:43]
	v_mfma_f32_16x16x32_bf16 v[36:39], v[90:93], v[130:133], v[36:39]
	v_mfma_f32_16x16x32_bf16 v[32:35], v[98:101], v[130:133], v[32:35]
	s_setprio 0
	s_setprio 1
	s_setprio 0
	s_barrier
	s_add_i32 s20, s54, s33
	v_lshl_add_u64 v[134:135], v[134:135], 0, s[8:9]
	s_mov_b32 m0, s20
	ds_read_b128 v[102:105], v85 offset:49152
	ds_read_b128 v[106:109], v85 offset:50176
	ds_read_b128 v[110:113], v85 offset:51200
	ds_read_b128 v[114:117], v85 offset:52224
	ds_read_b128 v[118:121], v85 offset:53248
	ds_read_b128 v[122:125], v85 offset:54272
	ds_read_b128 v[126:129], v85 offset:55296
	ds_read_b128 v[130:133], v85 offset:56320
	global_load_lds_dwordx4 v[134:135], off
	s_add_i32 m0, s20, 0x2000
	s_add_u32 s20, s22, 0x20080
	v_lshl_add_u64 v[134:135], v[136:137], 0, s[8:9]
	s_addc_u32 s21, s23, 0
	global_load_lds_dwordx4 v[134:135], off
	s_mov_b32 m0, s44
	s_nop 0
	global_load_lds_dwordx4 v66, s[20:21]
	s_mov_b32 m0, s45
	s_nop 0
	global_load_lds_dwordx4 v70, s[20:21]
	v_lshl_add_u64 v[134:135], v[138:139], 0, s[8:9]
	s_mov_b32 m0, s42
	s_nop 0
	global_load_lds_dwordx4 v[134:135], off
	v_lshl_add_u64 v[134:135], v[140:141], 0, s[8:9]
	s_mov_b32 m0, s43
	s_nop 0
	global_load_lds_dwordx4 v[134:135], off
	s_waitcnt vmcnt(8)
	s_waitcnt lgkmcnt(0)
	s_setprio 1
	s_barrier
	v_mfma_f32_16x16x32_bf16 v[28:31], v[86:89], v[102:105], v[28:31]
	v_mfma_f32_16x16x32_bf16 v[24:27], v[94:97], v[102:105], v[24:27]
	v_mfma_f32_16x16x32_bf16 v[20:23], v[86:89], v[110:113], v[20:23]
	v_mfma_f32_16x16x32_bf16 v[16:19], v[94:97], v[110:113], v[16:19]
	v_mfma_f32_16x16x32_bf16 v[12:15], v[86:89], v[118:121], v[12:15]
	v_mfma_f32_16x16x32_bf16 v[8:11], v[94:97], v[118:121], v[8:11]
	v_mfma_f32_16x16x32_bf16 v[4:7], v[86:89], v[126:129], v[4:7]
	v_mfma_f32_16x16x32_bf16 v[0:3], v[94:97], v[126:129], v[0:3]
	v_mfma_f32_16x16x32_bf16 v[28:31], v[90:93], v[106:109], v[28:31]
	v_mfma_f32_16x16x32_bf16 v[24:27], v[98:101], v[106:109], v[24:27]
	v_mfma_f32_16x16x32_bf16 v[20:23], v[90:93], v[114:117], v[20:23]
	v_mfma_f32_16x16x32_bf16 v[16:19], v[98:101], v[114:117], v[16:19]
	v_mfma_f32_16x16x32_bf16 v[12:15], v[90:93], v[122:125], v[12:15]
	v_mfma_f32_16x16x32_bf16 v[8:11], v[98:101], v[122:125], v[8:11]
	v_mfma_f32_16x16x32_bf16 v[4:7], v[90:93], v[130:133], v[4:7]
	v_mfma_f32_16x16x32_bf16 v[0:3], v[98:101], v[130:133], v[0:3]
	s_setprio 0
	s_setprio 1
	s_setprio 0
	s_barrier
	s_add_i32 s53, s53, 2
	s_add_u32 s51, s51, 0x100
	s_addc_u32 s52, s52, 0
	s_cmp_gt_u32 s53, 5
	s_mov_b64 s[20:21], s[6:7]
	s_cbranch_scc0 .LBB0_265
	s_and_b64 vcc, exec, s[12:13]
	s_cbranch_vccz .LBB0_268
	s_barrier

.Lrestag_402:
	ds_read_b128 v[120:123], v205
	ds_read_b128 v[124:127], v205 offset:1024
	ds_read_b128 v[132:135], v205 offset:2048
	ds_read_b128 v[140:143], v205 offset:3072
	ds_read_b128 v[144:147], v206
	ds_read_b128 v[148:151], v206 offset:1024
	ds_read_b128 v[152:155], v206 offset:2048
	ds_read_b128 v[156:159], v206 offset:3072
	s_add_u32 s22, s20, 0x100
	s_addc_u32 s23, s21, 0
	s_cmp_eq_u32 s54, 6
	s_cselect_b32 s27, s7, s23
	s_cselect_b32 s26, s6, s22
	s_cselect_b32 s25, s19, s53
	s_cselect_b32 s24, s18, s52
	s_add_i32 m0, s35, 0xc000
	ds_read_b128 v[180:183], v207
	ds_read_b128 v[184:187], v207 offset:1024
	ds_read_b128 v[188:191], v207 offset:2048
	ds_read_b128 v[192:195], v207 offset:3072
	ds_read_b128 v[196:199], v207 offset:4096
	ds_read_b128 v[208:211], v207 offset:5120
	ds_read_b128 v[212:215], v207 offset:6144
	ds_read_b128 v[216:219], v207 offset:7168
	global_load_lds_dwordx4 v172, s[20:21]
	s_add_i32 m0, s35, 0xe000
	s_nop 0
	global_load_lds_dwordx4 v174, s[20:21]
	s_nop 0
	s_waitcnt lgkmcnt(0)
	s_setprio 1
	s_barrier
	v_mfma_f32_16x16x32_bf16 v[136:139], v[120:123], v[180:183], 0
	v_mfma_f32_16x16x32_bf16 v[128:131], v[132:135], v[180:183], 0
	v_mfma_f32_16x16x32_bf16 v[116:119], v[120:123], v[188:191], 0
	v_mfma_f32_16x16x32_bf16 v[112:115], v[132:135], v[188:191], 0
	v_mfma_f32_16x16x32_bf16 v[108:111], v[120:123], v[196:199], 0
	v_mfma_f32_16x16x32_bf16 v[104:107], v[132:135], v[196:199], 0
	v_mfma_f32_16x16x32_bf16 v[100:103], v[120:123], v[212:215], 0
	v_mfma_f32_16x16x32_bf16 v[96:99], v[132:135], v[212:215], 0
	v_mfma_f32_16x16x32_bf16 v[136:139], v[124:127], v[184:187], v[136:139]
	v_mfma_f32_16x16x32_bf16 v[128:131], v[140:143], v[184:187], v[128:131]
	v_mfma_f32_16x16x32_bf16 v[116:119], v[124:127], v[192:195], v[116:119]
	v_mfma_f32_16x16x32_bf16 v[112:115], v[140:143], v[192:195], v[112:115]
	v_mfma_f32_16x16x32_bf16 v[108:111], v[124:127], v[208:211], v[108:111]
	v_mfma_f32_16x16x32_bf16 v[104:107], v[140:143], v[208:211], v[104:107]
	v_mfma_f32_16x16x32_bf16 v[100:103], v[124:127], v[216:219], v[100:103]
	v_mfma_f32_16x16x32_bf16 v[96:99], v[140:143], v[216:219], v[96:99]
	v_mfma_f32_16x16x32_bf16 v[60:63], v[144:147], v[180:183], 0
	v_mfma_f32_16x16x32_bf16 v[56:59], v[152:155], v[180:183], 0
	v_mfma_f32_16x16x32_bf16 v[52:55], v[144:147], v[188:191], 0
	v_mfma_f32_16x16x32_bf16 v[48:51], v[152:155], v[188:191], 0
	v_mfma_f32_16x16x32_bf16 v[44:47], v[144:147], v[196:199], 0
	v_mfma_f32_16x16x32_bf16 v[40:43], v[152:155], v[196:199], 0
	v_mfma_f32_16x16x32_bf16 v[36:39], v[144:147], v[212:215], 0
	v_mfma_f32_16x16x32_bf16 v[32:35], v[152:155], v[212:215], 0
	v_mfma_f32_16x16x32_bf16 v[60:63], v[148:151], v[184:187], v[60:63]
	v_mfma_f32_16x16x32_bf16 v[56:59], v[156:159], v[184:187], v[56:59]
	v_mfma_f32_16x16x32_bf16 v[52:55], v[148:151], v[192:195], v[52:55]
	v_mfma_f32_16x16x32_bf16 v[48:51], v[156:159], v[192:195], v[48:51]
	v_mfma_f32_16x16x32_bf16 v[44:47], v[148:151], v[208:211], v[44:47]
	v_mfma_f32_16x16x32_bf16 v[40:43], v[156:159], v[208:211], v[40:43]
	v_mfma_f32_16x16x32_bf16 v[36:39], v[148:151], v[216:219], v[36:39]
	v_mfma_f32_16x16x32_bf16 v[32:35], v[156:159], v[216:219], v[32:35]
	s_barrier
	s_setprio 0
	s_add_i32 s0, s46, s34
	v_lshl_add_u64 v[200:201], s[24:25], 0, v[162:163]
	s_mov_b32 m0, s0
	ds_read_b128 v[180:183], v207 offset:16384
	ds_read_b128 v[184:187], v207 offset:17408
	ds_read_b128 v[188:191], v207 offset:18432
	ds_read_b128 v[192:195], v207 offset:19456
	ds_read_b128 v[196:199], v207 offset:20480
	ds_read_b128 v[208:211], v207 offset:21504
	ds_read_b128 v[212:215], v207 offset:22528
	ds_read_b128 v[216:219], v207 offset:23552
	global_load_lds_dwordx4 v[200:201], off
	s_add_i32 m0, s0, 0x2000
	s_add_u32 s0, s24, 0x28000
	v_lshl_add_u64 v[220:221], s[24:25], 0, v[166:167]
	s_addc_u32 s1, s25, 0
	s_add_i32 s20, s47, s34
	global_load_lds_dwordx4 v[220:221], off
	s_mov_b32 m0, s20
	v_lshl_add_u64 v[224:225], s[26:27], 0, v[164:165]
	global_load_lds_dwordx4 v162, s[0:1]
	s_add_i32 m0, s20, 0x2000
	s_nop 0
	global_load_lds_dwordx4 v166, s[0:1]
	v_lshl_add_u64 v[222:223], s[26:27], 0, v[160:161]
	s_nop 0
	s_waitcnt lgkmcnt(0)
	s_setprio 1
	s_barrier
	v_mfma_f32_16x16x32_bf16 v[92:95], v[120:123], v[180:183], 0
	v_mfma_f32_16x16x32_bf16 v[88:91], v[132:135], v[180:183], 0
	v_mfma_f32_16x16x32_bf16 v[84:87], v[120:123], v[188:191], 0
	v_mfma_f32_16x16x32_bf16 v[80:83], v[132:135], v[188:191], 0
	v_mfma_f32_16x16x32_bf16 v[76:79], v[120:123], v[196:199], 0
	v_mfma_f32_16x16x32_bf16 v[72:75], v[132:135], v[196:199], 0
	v_mfma_f32_16x16x32_bf16 v[68:71], v[120:123], v[212:215], 0
	v_mfma_f32_16x16x32_bf16 v[64:67], v[132:135], v[212:215], 0
	v_mfma_f32_16x16x32_bf16 v[92:95], v[124:127], v[184:187], v[92:95]
	v_mfma_f32_16x16x32_bf16 v[88:91], v[140:143], v[184:187], v[88:91]
	v_mfma_f32_16x16x32_bf16 v[84:87], v[124:127], v[192:195], v[84:87]
	v_mfma_f32_16x16x32_bf16 v[80:83], v[140:143], v[192:195], v[80:83]
	v_mfma_f32_16x16x32_bf16 v[76:79], v[124:127], v[208:211], v[76:79]
	v_mfma_f32_16x16x32_bf16 v[72:75], v[140:143], v[208:211], v[72:75]
	v_mfma_f32_16x16x32_bf16 v[68:71], v[124:127], v[216:219], v[68:71]
	v_mfma_f32_16x16x32_bf16 v[64:67], v[140:143], v[216:219], v[64:67]
	v_mfma_f32_16x16x32_bf16 v[28:31], v[144:147], v[180:183], 0
	v_mfma_f32_16x16x32_bf16 v[24:27], v[152:155], v[180:183], 0
	v_mfma_f32_16x16x32_bf16 v[20:23], v[144:147], v[188:191], 0
	v_mfma_f32_16x16x32_bf16 v[16:19], v[152:155], v[188:191], 0
	v_mfma_f32_16x16x32_bf16 v[12:15], v[144:147], v[196:199], 0
	v_mfma_f32_16x16x32_bf16 v[8:11], v[152:155], v[196:199], 0
	v_mfma_f32_16x16x32_bf16 v[4:7], v[144:147], v[212:215], 0
	v_mfma_f32_16x16x32_bf16 v[0:3], v[152:155], v[212:215], 0
	v_mfma_f32_16x16x32_bf16 v[28:31], v[148:151], v[184:187], v[28:31]
	v_mfma_f32_16x16x32_bf16 v[24:27], v[156:159], v[184:187], v[24:27]
	v_mfma_f32_16x16x32_bf16 v[20:23], v[148:151], v[192:195], v[20:23]
	v_mfma_f32_16x16x32_bf16 v[16:19], v[156:159], v[192:195], v[16:19]
	v_mfma_f32_16x16x32_bf16 v[12:15], v[148:151], v[208:211], v[12:15]
	v_mfma_f32_16x16x32_bf16 v[8:11], v[156:159], v[208:211], v[8:11]
	v_mfma_f32_16x16x32_bf16 v[4:7], v[148:151], v[216:219], v[4:7]
	v_mfma_f32_16x16x32_bf16 v[0:3], v[156:159], v[216:219], v[0:3]
	s_barrier
	s_setprio 0
	s_add_i32 s20, 0, 0x18000
	s_add_i32 s21, 0, 0x1c000
	v_add_u32_e32 v140, s20, v203
	v_add_u32_e32 v156, s21, v203
	ds_read_b128 v[120:123], v140
	ds_read_b128 v[124:127], v140 offset:1024
	ds_read_b128 v[132:135], v140 offset:2048
	ds_read_b128 v[140:143], v140 offset:3072
	ds_read_b128 v[144:147], v156
	ds_read_b128 v[148:151], v156 offset:1024
	ds_read_b128 v[152:155], v156 offset:2048
	ds_read_b128 v[156:159], v156 offset:3072
	s_add_u32 s0, s26, 0x28000
	s_addc_u32 s1, s27, 0
	s_mov_b32 m0, s37
	ds_read_b128 v[180:183], v207 offset:32768
	ds_read_b128 v[184:187], v207 offset:33792
	ds_read_b128 v[188:191], v207 offset:34816
	ds_read_b128 v[192:195], v207 offset:35840
	ds_read_b128 v[196:199], v207 offset:36864
	ds_read_b128 v[208:211], v207 offset:37888
	ds_read_b128 v[212:215], v207 offset:38912
	ds_read_b128 v[216:219], v207 offset:39936
	global_load_lds_dwordx4 v160, s[0:1]
	s_mov_b32 m0, s40
	s_nop 0
	global_load_lds_dwordx4 v164, s[0:1]
	s_mov_b32 m0, s35
	s_nop 0
	global_load_lds_dwordx4 v[222:223], off
	s_mov_b32 m0, s36
	s_nop 0
	global_load_lds_dwordx4 v[224:225], off
	s_waitcnt vmcnt(8)
	s_waitcnt lgkmcnt(0)
	s_setprio 1
	s_barrier
	v_mfma_f32_16x16x32_bf16 v[136:139], v[120:123], v[180:183], v[136:139]
	v_mfma_f32_16x16x32_bf16 v[128:131], v[132:135], v[180:183], v[128:131]
	v_mfma_f32_16x16x32_bf16 v[116:119], v[120:123], v[188:191], v[116:119]
	v_mfma_f32_16x16x32_bf16 v[112:115], v[132:135], v[188:191], v[112:115]
	v_mfma_f32_16x16x32_bf16 v[108:111], v[120:123], v[196:199], v[108:111]
	v_mfma_f32_16x16x32_bf16 v[104:107], v[132:135], v[196:199], v[104:107]
	v_mfma_f32_16x16x32_bf16 v[100:103], v[120:123], v[212:215], v[100:103]
	v_mfma_f32_16x16x32_bf16 v[96:99], v[132:135], v[212:215], v[96:99]
	v_mfma_f32_16x16x32_bf16 v[136:139], v[124:127], v[184:187], v[136:139]
	v_mfma_f32_16x16x32_bf16 v[128:131], v[140:143], v[184:187], v[128:131]
	v_mfma_f32_16x16x32_bf16 v[116:119], v[124:127], v[192:195], v[116:119]
	v_mfma_f32_16x16x32_bf16 v[112:115], v[140:143], v[192:195], v[112:115]
	v_mfma_f32_16x16x32_bf16 v[108:111], v[124:127], v[208:211], v[108:111]
	v_mfma_f32_16x16x32_bf16 v[104:107], v[140:143], v[208:211], v[104:107]
	v_mfma_f32_16x16x32_bf16 v[100:103], v[124:127], v[216:219], v[100:103]
	v_mfma_f32_16x16x32_bf16 v[96:99], v[140:143], v[216:219], v[96:99]
	v_mfma_f32_16x16x32_bf16 v[60:63], v[144:147], v[180:183], v[60:63]
	v_mfma_f32_16x16x32_bf16 v[56:59], v[152:155], v[180:183], v[56:59]
	v_mfma_f32_16x16x32_bf16 v[52:55], v[144:147], v[188:191], v[52:55]
	v_mfma_f32_16x16x32_bf16 v[48:51], v[152:155], v[188:191], v[48:51]
	v_mfma_f32_16x16x32_bf16 v[44:47], v[144:147], v[196:199], v[44:47]
	v_mfma_f32_16x16x32_bf16 v[40:43], v[152:155], v[196:199], v[40:43]
	v_mfma_f32_16x16x32_bf16 v[36:39], v[144:147], v[212:215], v[36:39]
	v_mfma_f32_16x16x32_bf16 v[32:35], v[152:155], v[212:215], v[32:35]
	v_mfma_f32_16x16x32_bf16 v[60:63], v[148:151], v[184:187], v[60:63]
	v_mfma_f32_16x16x32_bf16 v[56:59], v[156:159], v[184:187], v[56:59]
	v_mfma_f32_16x16x32_bf16 v[52:55], v[148:151], v[192:195], v[52:55]
	v_mfma_f32_16x16x32_bf16 v[48:51], v[156:159], v[192:195], v[48:51]
	v_mfma_f32_16x16x32_bf16 v[44:47], v[148:151], v[208:211], v[44:47]
	v_mfma_f32_16x16x32_bf16 v[40:43], v[156:159], v[208:211], v[40:43]
	v_mfma_f32_16x16x32_bf16 v[36:39], v[148:151], v[216:219], v[36:39]
	v_mfma_f32_16x16x32_bf16 v[32:35], v[156:159], v[216:219], v[32:35]
	s_barrier
	s_setprio 0
	s_add_i32 s0, s20, s34
	v_lshl_add_u64 v[200:201], v[200:201], 0, s[14:15]
	s_mov_b32 m0, s0
	ds_read_b128 v[180:183], v207 offset:49152
	ds_read_b128 v[184:187], v207 offset:50176
	ds_read_b128 v[188:191], v207 offset:51200
	ds_read_b128 v[192:195], v207 offset:52224
	ds_read_b128 v[196:199], v207 offset:53248
	ds_read_b128 v[208:211], v207 offset:54272
	ds_read_b128 v[212:215], v207 offset:55296
	ds_read_b128 v[216:219], v207 offset:56320
	global_load_lds_dwordx4 v[200:201], off
	s_add_i32 m0, s0, 0x2000
	s_add_u32 s0, s24, 0x28080
	v_lshl_add_u64 v[200:201], v[220:221], 0, s[14:15]
	s_addc_u32 s1, s25, 0
	s_add_i32 s20, s21, s34
	global_load_lds_dwordx4 v[200:201], off
	s_mov_b32 m0, s20
	s_nop 0
	global_load_lds_dwordx4 v162, s[0:1]
	s_add_i32 m0, s20, 0x2000
	s_nop 0
	global_load_lds_dwordx4 v166, s[0:1]
	v_lshl_add_u64 v[200:201], v[222:223], 0, s[14:15]
	s_mov_b32 m0, s42
	s_nop 0
	global_load_lds_dwordx4 v[200:201], off
	v_lshl_add_u64 v[200:201], v[224:225], 0, s[14:15]
	s_mov_b32 m0, s43
	s_nop 0
	global_load_lds_dwordx4 v[200:201], off
	s_waitcnt vmcnt(6)
	s_waitcnt lgkmcnt(0)
	s_setprio 1
	s_barrier
	v_mfma_f32_16x16x32_bf16 v[92:95], v[120:123], v[180:183], v[92:95]
	v_mfma_f32_16x16x32_bf16 v[88:91], v[132:135], v[180:183], v[88:91]
	v_mfma_f32_16x16x32_bf16 v[84:87], v[120:123], v[188:191], v[84:87]
	v_mfma_f32_16x16x32_bf16 v[80:83], v[132:135], v[188:191], v[80:83]
	v_mfma_f32_16x16x32_bf16 v[76:79], v[120:123], v[196:199], v[76:79]
	v_mfma_f32_16x16x32_bf16 v[72:75], v[132:135], v[196:199], v[72:75]
	v_mfma_f32_16x16x32_bf16 v[68:71], v[120:123], v[212:215], v[68:71]
	v_mfma_f32_16x16x32_bf16 v[64:67], v[132:135], v[212:215], v[64:67]
	v_mfma_f32_16x16x32_bf16 v[92:95], v[124:127], v[184:187], v[92:95]
	v_mfma_f32_16x16x32_bf16 v[88:91], v[140:143], v[184:187], v[88:91]
	v_mfma_f32_16x16x32_bf16 v[84:87], v[124:127], v[192:195], v[84:87]
	v_mfma_f32_16x16x32_bf16 v[80:83], v[140:143], v[192:195], v[80:83]
	v_mfma_f32_16x16x32_bf16 v[76:79], v[124:127], v[208:211], v[76:79]
	v_mfma_f32_16x16x32_bf16 v[72:75], v[140:143], v[208:211], v[72:75]
	v_mfma_f32_16x16x32_bf16 v[68:71], v[124:127], v[216:219], v[68:71]
	v_mfma_f32_16x16x32_bf16 v[64:67], v[140:143], v[216:219], v[64:67]
	v_mfma_f32_16x16x32_bf16 v[28:31], v[144:147], v[180:183], v[28:31]
	v_mfma_f32_16x16x32_bf16 v[24:27], v[152:155], v[180:183], v[24:27]
	v_mfma_f32_16x16x32_bf16 v[20:23], v[144:147], v[188:191], v[20:23]
	v_mfma_f32_16x16x32_bf16 v[16:19], v[152:155], v[188:191], v[16:19]
	v_mfma_f32_16x16x32_bf16 v[12:15], v[144:147], v[196:199], v[12:15]
	v_mfma_f32_16x16x32_bf16 v[8:11], v[152:155], v[196:199], v[8:11]
	v_mfma_f32_16x16x32_bf16 v[4:7], v[144:147], v[212:215], v[4:7]
	v_mfma_f32_16x16x32_bf16 v[0:3], v[152:155], v[212:215], v[0:3]
	v_mfma_f32_16x16x32_bf16 v[28:31], v[148:151], v[184:187], v[28:31]
	v_mfma_f32_16x16x32_bf16 v[24:27], v[156:159], v[184:187], v[24:27]
	v_mfma_f32_16x16x32_bf16 v[20:23], v[148:151], v[192:195], v[20:23]
	v_mfma_f32_16x16x32_bf16 v[16:19], v[156:159], v[192:195], v[16:19]
	v_mfma_f32_16x16x32_bf16 v[12:15], v[148:151], v[208:211], v[12:15]
	v_mfma_f32_16x16x32_bf16 v[8:11], v[156:159], v[208:211], v[8:11]
	v_mfma_f32_16x16x32_bf16 v[4:7], v[148:151], v[216:219], v[4:7]
	v_mfma_f32_16x16x32_bf16 v[0:3], v[156:159], v[216:219], v[0:3]
	s_barrier
	s_setprio 0
	s_add_i32 s54, s54, 2
	s_add_u32 s52, s52, 0x100
	s_addc_u32 s53, s53, 0
	s_cmp_gt_u32 s54, 7
	s_mov_b64 s[20:21], s[22:23]
.LBB0_402:
	ds_read_b128 v[120:123], v205
	ds_read_b128 v[124:127], v205 offset:1024
	ds_read_b128 v[132:135], v205 offset:2048
	ds_read_b128 v[140:143], v205 offset:3072
	ds_read_b128 v[144:147], v206
	ds_read_b128 v[148:151], v206 offset:1024
	ds_read_b128 v[152:155], v206 offset:2048
	ds_read_b128 v[156:159], v206 offset:3072
	s_add_u32 s22, s20, 0x100
	s_addc_u32 s23, s21, 0
	s_cmp_eq_u32 s54, 6
	s_cselect_b32 s27, s7, s23
	s_cselect_b32 s26, s6, s22
	s_cselect_b32 s25, s19, s53
	s_cselect_b32 s24, s18, s52
	s_add_i32 m0, s35, 0xc000
	ds_read_b128 v[180:183], v207
	ds_read_b128 v[184:187], v207 offset:1024
	ds_read_b128 v[188:191], v207 offset:2048
	ds_read_b128 v[192:195], v207 offset:3072
	ds_read_b128 v[196:199], v207 offset:4096
	ds_read_b128 v[208:211], v207 offset:5120
	ds_read_b128 v[212:215], v207 offset:6144
	ds_read_b128 v[216:219], v207 offset:7168
	global_load_lds_dwordx4 v172, s[20:21]
	s_add_i32 m0, s35, 0xe000
	s_nop 0
	global_load_lds_dwordx4 v174, s[20:21]
	s_waitcnt vmcnt(8)
	s_waitcnt lgkmcnt(0)
	s_setprio 1
	s_barrier
	v_mfma_f32_16x16x32_bf16 v[136:139], v[120:123], v[180:183], v[136:139]
	v_mfma_f32_16x16x32_bf16 v[128:131], v[132:135], v[180:183], v[128:131]
	v_mfma_f32_16x16x32_bf16 v[116:119], v[120:123], v[188:191], v[116:119]
	v_mfma_f32_16x16x32_bf16 v[112:115], v[132:135], v[188:191], v[112:115]
	v_mfma_f32_16x16x32_bf16 v[108:111], v[120:123], v[196:199], v[108:111]
	v_mfma_f32_16x16x32_bf16 v[104:107], v[132:135], v[196:199], v[104:107]
	v_mfma_f32_16x16x32_bf16 v[100:103], v[120:123], v[212:215], v[100:103]
	v_mfma_f32_16x16x32_bf16 v[96:99], v[132:135], v[212:215], v[96:99]
	v_mfma_f32_16x16x32_bf16 v[136:139], v[124:127], v[184:187], v[136:139]
	v_mfma_f32_16x16x32_bf16 v[128:131], v[140:143], v[184:187], v[128:131]
	v_mfma_f32_16x16x32_bf16 v[116:119], v[124:127], v[192:195], v[116:119]
	v_mfma_f32_16x16x32_bf16 v[112:115], v[140:143], v[192:195], v[112:115]
	v_mfma_f32_16x16x32_bf16 v[108:111], v[124:127], v[208:211], v[108:111]
	v_mfma_f32_16x16x32_bf16 v[104:107], v[140:143], v[208:211], v[104:107]
	v_mfma_f32_16x16x32_bf16 v[100:103], v[124:127], v[216:219], v[100:103]
	v_mfma_f32_16x16x32_bf16 v[96:99], v[140:143], v[216:219], v[96:99]
	v_mfma_f32_16x16x32_bf16 v[60:63], v[144:147], v[180:183], v[60:63]
	v_mfma_f32_16x16x32_bf16 v[56:59], v[152:155], v[180:183], v[56:59]
	v_mfma_f32_16x16x32_bf16 v[52:55], v[144:147], v[188:191], v[52:55]
	v_mfma_f32_16x16x32_bf16 v[48:51], v[152:155], v[188:191], v[48:51]
	v_mfma_f32_16x16x32_bf16 v[44:47], v[144:147], v[196:199], v[44:47]
	v_mfma_f32_16x16x32_bf16 v[40:43], v[152:155], v[196:199], v[40:43]
	v_mfma_f32_16x16x32_bf16 v[36:39], v[144:147], v[212:215], v[36:39]
	v_mfma_f32_16x16x32_bf16 v[32:35], v[152:155], v[212:215], v[32:35]
	v_mfma_f32_16x16x32_bf16 v[60:63], v[148:151], v[184:187], v[60:63]
	v_mfma_f32_16x16x32_bf16 v[56:59], v[156:159], v[184:187], v[56:59]
	v_mfma_f32_16x16x32_bf16 v[52:55], v[148:151], v[192:195], v[52:55]
	v_mfma_f32_16x16x32_bf16 v[48:51], v[156:159], v[192:195], v[48:51]
	v_mfma_f32_16x16x32_bf16 v[44:47], v[148:151], v[208:211], v[44:47]
	v_mfma_f32_16x16x32_bf16 v[40:43], v[156:159], v[208:211], v[40:43]
	v_mfma_f32_16x16x32_bf16 v[36:39], v[148:151], v[216:219], v[36:39]
	v_mfma_f32_16x16x32_bf16 v[32:35], v[156:159], v[216:219], v[32:35]
	s_barrier
	s_setprio 0
	s_add_i32 s0, s46, s34
	v_lshl_add_u64 v[200:201], s[24:25], 0, v[162:163]
	s_mov_b32 m0, s0
	ds_read_b128 v[180:183], v207 offset:16384
	ds_read_b128 v[184:187], v207 offset:17408
	ds_read_b128 v[188:191], v207 offset:18432
	ds_read_b128 v[192:195], v207 offset:19456
	ds_read_b128 v[196:199], v207 offset:20480
	ds_read_b128 v[208:211], v207 offset:21504
	ds_read_b128 v[212:215], v207 offset:22528
	ds_read_b128 v[216:219], v207 offset:23552
	global_load_lds_dwordx4 v[200:201], off
	s_add_i32 m0, s0, 0x2000
	s_add_u32 s0, s24, 0x28000
	v_lshl_add_u64 v[220:221], s[24:25], 0, v[166:167]
	s_addc_u32 s1, s25, 0
	s_add_i32 s20, s47, s34
	global_load_lds_dwordx4 v[220:221], off
	s_mov_b32 m0, s20
	v_lshl_add_u64 v[224:225], s[26:27], 0, v[164:165]
	global_load_lds_dwordx4 v162, s[0:1]
	s_add_i32 m0, s20, 0x2000
	s_nop 0
	global_load_lds_dwordx4 v166, s[0:1]
	v_lshl_add_u64 v[222:223], s[26:27], 0, v[160:161]
	s_waitcnt vmcnt(6)
	s_waitcnt lgkmcnt(0)
	s_setprio 1
	s_barrier
	v_mfma_f32_16x16x32_bf16 v[92:95], v[120:123], v[180:183], v[92:95]
	v_mfma_f32_16x16x32_bf16 v[88:91], v[132:135], v[180:183], v[88:91]
	v_mfma_f32_16x16x32_bf16 v[84:87], v[120:123], v[188:191], v[84:87]
	v_mfma_f32_16x16x32_bf16 v[80:83], v[132:135], v[188:191], v[80:83]
	v_mfma_f32_16x16x32_bf16 v[76:79], v[120:123], v[196:199], v[76:79]
	v_mfma_f32_16x16x32_bf16 v[72:75], v[132:135], v[196:199], v[72:75]
	v_mfma_f32_16x16x32_bf16 v[68:71], v[120:123], v[212:215], v[68:71]
	v_mfma_f32_16x16x32_bf16 v[64:67], v[132:135], v[212:215], v[64:67]
	v_mfma_f32_16x16x32_bf16 v[92:95], v[124:127], v[184:187], v[92:95]
	v_mfma_f32_16x16x32_bf16 v[88:91], v[140:143], v[184:187], v[88:91]
	v_mfma_f32_16x16x32_bf16 v[84:87], v[124:127], v[192:195], v[84:87]
	v_mfma_f32_16x16x32_bf16 v[80:83], v[140:143], v[192:195], v[80:83]
	v_mfma_f32_16x16x32_bf16 v[76:79], v[124:127], v[208:211], v[76:79]
	v_mfma_f32_16x16x32_bf16 v[72:75], v[140:143], v[208:211], v[72:75]
	v_mfma_f32_16x16x32_bf16 v[68:71], v[124:127], v[216:219], v[68:71]
	v_mfma_f32_16x16x32_bf16 v[64:67], v[140:143], v[216:219], v[64:67]
	v_mfma_f32_16x16x32_bf16 v[28:31], v[144:147], v[180:183], v[28:31]
	v_mfma_f32_16x16x32_bf16 v[24:27], v[152:155], v[180:183], v[24:27]
	v_mfma_f32_16x16x32_bf16 v[20:23], v[144:147], v[188:191], v[20:23]
	v_mfma_f32_16x16x32_bf16 v[16:19], v[152:155], v[188:191], v[16:19]
	v_mfma_f32_16x16x32_bf16 v[12:15], v[144:147], v[196:199], v[12:15]
	v_mfma_f32_16x16x32_bf16 v[8:11], v[152:155], v[196:199], v[8:11]
	v_mfma_f32_16x16x32_bf16 v[4:7], v[144:147], v[212:215], v[4:7]
	v_mfma_f32_16x16x32_bf16 v[0:3], v[152:155], v[212:215], v[0:3]
	v_mfma_f32_16x16x32_bf16 v[28:31], v[148:151], v[184:187], v[28:31]
	v_mfma_f32_16x16x32_bf16 v[24:27], v[156:159], v[184:187], v[24:27]
	v_mfma_f32_16x16x32_bf16 v[20:23], v[148:151], v[192:195], v[20:23]
	v_mfma_f32_16x16x32_bf16 v[16:19], v[156:159], v[192:195], v[16:19]
	v_mfma_f32_16x16x32_bf16 v[12:15], v[148:151], v[208:211], v[12:15]
	v_mfma_f32_16x16x32_bf16 v[8:11], v[156:159], v[208:211], v[8:11]
	v_mfma_f32_16x16x32_bf16 v[4:7], v[148:151], v[216:219], v[4:7]
	v_mfma_f32_16x16x32_bf16 v[0:3], v[156:159], v[216:219], v[0:3]
	s_barrier
	s_setprio 0
	s_add_i32 s20, 0, 0x18000
	s_add_i32 s21, 0, 0x1c000
	v_add_u32_e32 v140, s20, v203
	v_add_u32_e32 v156, s21, v203
	ds_read_b128 v[120:123], v140
	ds_read_b128 v[124:127], v140 offset:1024
	ds_read_b128 v[132:135], v140 offset:2048
	ds_read_b128 v[140:143], v140 offset:3072
	ds_read_b128 v[144:147], v156
	ds_read_b128 v[148:151], v156 offset:1024
	ds_read_b128 v[152:155], v156 offset:2048
	ds_read_b128 v[156:159], v156 offset:3072
	s_add_u32 s0, s26, 0x28000
	s_addc_u32 s1, s27, 0
	s_mov_b32 m0, s37
	ds_read_b128 v[180:183], v207 offset:32768
	ds_read_b128 v[184:187], v207 offset:33792
	ds_read_b128 v[188:191], v207 offset:34816
	ds_read_b128 v[192:195], v207 offset:35840
	ds_read_b128 v[196:199], v207 offset:36864
	ds_read_b128 v[208:211], v207 offset:37888
	ds_read_b128 v[212:215], v207 offset:38912
	ds_read_b128 v[216:219], v207 offset:39936
	global_load_lds_dwordx4 v160, s[0:1]
	s_mov_b32 m0, s40
	s_nop 0
	global_load_lds_dwordx4 v164, s[0:1]
	s_mov_b32 m0, s35
	s_nop 0
	global_load_lds_dwordx4 v[222:223], off
	s_mov_b32 m0, s36
	s_nop 0
	global_load_lds_dwordx4 v[224:225], off
	s_waitcnt vmcnt(8)
	s_waitcnt lgkmcnt(0)
	s_setprio 1
	s_barrier
	v_mfma_f32_16x16x32_bf16 v[136:139], v[120:123], v[180:183], v[136:139]
	v_mfma_f32_16x16x32_bf16 v[128:131], v[132:135], v[180:183], v[128:131]
	v_mfma_f32_16x16x32_bf16 v[116:119], v[120:123], v[188:191], v[116:119]
	v_mfma_f32_16x16x32_bf16 v[112:115], v[132:135], v[188:191], v[112:115]
	v_mfma_f32_16x16x32_bf16 v[108:111], v[120:123], v[196:199], v[108:111]
	v_mfma_f32_16x16x32_bf16 v[104:107], v[132:135], v[196:199], v[104:107]
	v_mfma_f32_16x16x32_bf16 v[100:103], v[120:123], v[212:215], v[100:103]
	v_mfma_f32_16x16x32_bf16 v[96:99], v[132:135], v[212:215], v[96:99]
	v_mfma_f32_16x16x32_bf16 v[136:139], v[124:127], v[184:187], v[136:139]
	v_mfma_f32_16x16x32_bf16 v[128:131], v[140:143], v[184:187], v[128:131]
	v_mfma_f32_16x16x32_bf16 v[116:119], v[124:127], v[192:195], v[116:119]
	v_mfma_f32_16x16x32_bf16 v[112:115], v[140:143], v[192:195], v[112:115]
	v_mfma_f32_16x16x32_bf16 v[108:111], v[124:127], v[208:211], v[108:111]
	v_mfma_f32_16x16x32_bf16 v[104:107], v[140:143], v[208:211], v[104:107]
	v_mfma_f32_16x16x32_bf16 v[100:103], v[124:127], v[216:219], v[100:103]
	v_mfma_f32_16x16x32_bf16 v[96:99], v[140:143], v[216:219], v[96:99]
	v_mfma_f32_16x16x32_bf16 v[60:63], v[144:147], v[180:183], v[60:63]
	v_mfma_f32_16x16x32_bf16 v[56:59], v[152:155], v[180:183], v[56:59]
	v_mfma_f32_16x16x32_bf16 v[52:55], v[144:147], v[188:191], v[52:55]
	v_mfma_f32_16x16x32_bf16 v[48:51], v[152:155], v[188:191], v[48:51]
	v_mfma_f32_16x16x32_bf16 v[44:47], v[144:147], v[196:199], v[44:47]
	v_mfma_f32_16x16x32_bf16 v[40:43], v[152:155], v[196:199], v[40:43]
	v_mfma_f32_16x16x32_bf16 v[36:39], v[144:147], v[212:215], v[36:39]
	v_mfma_f32_16x16x32_bf16 v[32:35], v[152:155], v[212:215], v[32:35]
	v_mfma_f32_16x16x32_bf16 v[60:63], v[148:151], v[184:187], v[60:63]
	v_mfma_f32_16x16x32_bf16 v[56:59], v[156:159], v[184:187], v[56:59]
	v_mfma_f32_16x16x32_bf16 v[52:55], v[148:151], v[192:195], v[52:55]
	v_mfma_f32_16x16x32_bf16 v[48:51], v[156:159], v[192:195], v[48:51]
	v_mfma_f32_16x16x32_bf16 v[44:47], v[148:151], v[208:211], v[44:47]
	v_mfma_f32_16x16x32_bf16 v[40:43], v[156:159], v[208:211], v[40:43]
	v_mfma_f32_16x16x32_bf16 v[36:39], v[148:151], v[216:219], v[36:39]
	v_mfma_f32_16x16x32_bf16 v[32:35], v[156:159], v[216:219], v[32:35]
	s_barrier
	s_setprio 0
	s_add_i32 s0, s20, s34
	v_lshl_add_u64 v[200:201], v[200:201], 0, s[14:15]
	s_mov_b32 m0, s0
	ds_read_b128 v[180:183], v207 offset:49152
	ds_read_b128 v[184:187], v207 offset:50176
	ds_read_b128 v[188:191], v207 offset:51200
	ds_read_b128 v[192:195], v207 offset:52224
	ds_read_b128 v[196:199], v207 offset:53248
	ds_read_b128 v[208:211], v207 offset:54272
	ds_read_b128 v[212:215], v207 offset:55296
	ds_read_b128 v[216:219], v207 offset:56320
	global_load_lds_dwordx4 v[200:201], off
	s_add_i32 m0, s0, 0x2000
	s_add_u32 s0, s24, 0x28080
	v_lshl_add_u64 v[200:201], v[220:221], 0, s[14:15]
	s_addc_u32 s1, s25, 0
	s_add_i32 s20, s21, s34
	global_load_lds_dwordx4 v[200:201], off
	s_mov_b32 m0, s20
	s_nop 0
	global_load_lds_dwordx4 v162, s[0:1]
	s_add_i32 m0, s20, 0x2000
	s_nop 0
	global_load_lds_dwordx4 v166, s[0:1]
	v_lshl_add_u64 v[200:201], v[222:223], 0, s[14:15]
	s_mov_b32 m0, s42
	s_nop 0
	global_load_lds_dwordx4 v[200:201], off
	v_lshl_add_u64 v[200:201], v[224:225], 0, s[14:15]
	s_mov_b32 m0, s43
	s_nop 0
	global_load_lds_dwordx4 v[200:201], off
	s_waitcnt vmcnt(6)
	s_waitcnt lgkmcnt(0)
	s_setprio 1
	s_barrier
	v_mfma_f32_16x16x32_bf16 v[92:95], v[120:123], v[180:183], v[92:95]
	v_mfma_f32_16x16x32_bf16 v[88:91], v[132:135], v[180:183], v[88:91]
	v_mfma_f32_16x16x32_bf16 v[84:87], v[120:123], v[188:191], v[84:87]
	v_mfma_f32_16x16x32_bf16 v[80:83], v[132:135], v[188:191], v[80:83]
	v_mfma_f32_16x16x32_bf16 v[76:79], v[120:123], v[196:199], v[76:79]
	v_mfma_f32_16x16x32_bf16 v[72:75], v[132:135], v[196:199], v[72:75]
	v_mfma_f32_16x16x32_bf16 v[68:71], v[120:123], v[212:215], v[68:71]
	v_mfma_f32_16x16x32_bf16 v[64:67], v[132:135], v[212:215], v[64:67]
	v_mfma_f32_16x16x32_bf16 v[92:95], v[124:127], v[184:187], v[92:95]
	v_mfma_f32_16x16x32_bf16 v[88:91], v[140:143], v[184:187], v[88:91]
	v_mfma_f32_16x16x32_bf16 v[84:87], v[124:127], v[192:195], v[84:87]
	v_mfma_f32_16x16x32_bf16 v[80:83], v[140:143], v[192:195], v[80:83]
	v_mfma_f32_16x16x32_bf16 v[76:79], v[124:127], v[208:211], v[76:79]
	v_mfma_f32_16x16x32_bf16 v[72:75], v[140:143], v[208:211], v[72:75]
	v_mfma_f32_16x16x32_bf16 v[68:71], v[124:127], v[216:219], v[68:71]
	v_mfma_f32_16x16x32_bf16 v[64:67], v[140:143], v[216:219], v[64:67]
	v_mfma_f32_16x16x32_bf16 v[28:31], v[144:147], v[180:183], v[28:31]
	v_mfma_f32_16x16x32_bf16 v[24:27], v[152:155], v[180:183], v[24:27]
	v_mfma_f32_16x16x32_bf16 v[20:23], v[144:147], v[188:191], v[20:23]
	v_mfma_f32_16x16x32_bf16 v[16:19], v[152:155], v[188:191], v[16:19]
	v_mfma_f32_16x16x32_bf16 v[12:15], v[144:147], v[196:199], v[12:15]
	v_mfma_f32_16x16x32_bf16 v[8:11], v[152:155], v[196:199], v[8:11]
	v_mfma_f32_16x16x32_bf16 v[4:7], v[144:147], v[212:215], v[4:7]
	v_mfma_f32_16x16x32_bf16 v[0:3], v[152:155], v[212:215], v[0:3]
	v_mfma_f32_16x16x32_bf16 v[28:31], v[148:151], v[184:187], v[28:31]
	v_mfma_f32_16x16x32_bf16 v[24:27], v[156:159], v[184:187], v[24:27]
	v_mfma_f32_16x16x32_bf16 v[20:23], v[148:151], v[192:195], v[20:23]
	v_mfma_f32_16x16x32_bf16 v[16:19], v[156:159], v[192:195], v[16:19]
	v_mfma_f32_16x16x32_bf16 v[12:15], v[148:151], v[208:211], v[12:15]
	v_mfma_f32_16x16x32_bf16 v[8:11], v[156:159], v[208:211], v[8:11]
	v_mfma_f32_16x16x32_bf16 v[4:7], v[148:151], v[216:219], v[4:7]
	v_mfma_f32_16x16x32_bf16 v[0:3], v[156:159], v[216:219], v[0:3]
	s_barrier
	s_setprio 0
	s_add_i32 s54, s54, 2
	s_add_u32 s52, s52, 0x100
	s_addc_u32 s53, s53, 0
	s_cmp_gt_u32 s54, 7
	s_mov_b64 s[20:21], s[22:23]
	s_cbranch_scc0 .LBB0_402
	s_and_b64 vcc, exec, s[16:17]
	s_cbranch_vccz .LBB0_405
	s_barrier

.Lrestag_480:
	ds_read_b128 v[100:103], v210
	ds_read_b128 v[116:119], v210 offset:1024
	ds_read_b128 v[136:139], v210 offset:2048
	ds_read_b128 v[140:143], v210 offset:3072
	ds_read_b128 v[144:147], v211
	ds_read_b128 v[148:151], v211 offset:1024
	ds_read_b128 v[152:155], v211 offset:2048
	ds_read_b128 v[178:181], v211 offset:3072
	s_add_u32 s36, s34, 0x1000000
	s_addc_u32 s37, s35, 0
	s_cmp_eq_u32 s65, 12
	s_cselect_b32 s44, s29, s36
	s_cselect_b32 s45, s23, s37
	s_cselect_b32 s42, s31, s63
	s_cselect_b32 s43, s21, s64
	s_add_u32 s40, s44, 0x800000
	s_addc_u32 s41, s45, 0
	s_add_i32 m0, s52, 0xc000
	ds_read_b128 v[182:185], v212
	ds_read_b128 v[186:189], v212 offset:1024
	ds_read_b128 v[190:193], v212 offset:2048
	ds_read_b128 v[194:197], v212 offset:3072
	ds_read_b128 v[198:201], v212 offset:4096
	ds_read_b128 v[202:205], v212 offset:5120
	ds_read_b128 v[214:217], v212 offset:6144
	ds_read_b128 v[218:221], v212 offset:7168
	global_load_lds_dwordx4 v170, s[34:35]
	s_add_i32 m0, s52, 0xe000
	s_nop 0
	global_load_lds_dwordx4 v172, s[34:35]
	s_nop 0
	s_waitcnt lgkmcnt(0)
	s_setprio 1
	s_barrier
	v_mfma_f32_16x16x32_bf16 v[132:135], v[100:103], v[182:185], 0
	v_mfma_f32_16x16x32_bf16 v[124:127], v[136:139], v[182:185], 0
	v_mfma_f32_16x16x32_bf16 v[112:115], v[100:103], v[190:193], 0
	v_mfma_f32_16x16x32_bf16 v[104:107], v[136:139], v[190:193], 0
	v_mfma_f32_16x16x32_bf16 v[92:95], v[100:103], v[198:201], 0
	v_mfma_f32_16x16x32_bf16 v[84:87], v[136:139], v[198:201], 0
	v_mfma_f32_16x16x32_bf16 v[76:79], v[100:103], v[214:217], 0
	v_mfma_f32_16x16x32_bf16 v[68:71], v[136:139], v[214:217], 0
	v_mfma_f32_16x16x32_bf16 v[132:135], v[116:119], v[186:189], v[132:135]
	v_mfma_f32_16x16x32_bf16 v[124:127], v[140:143], v[186:189], v[124:127]
	v_mfma_f32_16x16x32_bf16 v[112:115], v[116:119], v[194:197], v[112:115]
	v_mfma_f32_16x16x32_bf16 v[104:107], v[140:143], v[194:197], v[104:107]
	v_mfma_f32_16x16x32_bf16 v[92:95], v[116:119], v[202:205], v[92:95]
	v_mfma_f32_16x16x32_bf16 v[84:87], v[140:143], v[202:205], v[84:87]
	v_mfma_f32_16x16x32_bf16 v[76:79], v[116:119], v[218:221], v[76:79]
	v_mfma_f32_16x16x32_bf16 v[68:71], v[140:143], v[218:221], v[68:71]
	v_mfma_f32_16x16x32_bf16 v[128:131], v[144:147], v[182:185], 0
	v_mfma_f32_16x16x32_bf16 v[120:123], v[152:155], v[182:185], 0
	v_mfma_f32_16x16x32_bf16 v[108:111], v[144:147], v[190:193], 0
	v_mfma_f32_16x16x32_bf16 v[96:99], v[152:155], v[190:193], 0
	v_mfma_f32_16x16x32_bf16 v[88:91], v[144:147], v[198:201], 0
	v_mfma_f32_16x16x32_bf16 v[80:83], v[152:155], v[198:201], 0
	v_mfma_f32_16x16x32_bf16 v[72:75], v[144:147], v[214:217], 0
	v_mfma_f32_16x16x32_bf16 v[64:67], v[152:155], v[214:217], 0
	v_mfma_f32_16x16x32_bf16 v[128:131], v[148:151], v[186:189], v[128:131]
	v_mfma_f32_16x16x32_bf16 v[120:123], v[178:181], v[186:189], v[120:123]
	v_mfma_f32_16x16x32_bf16 v[108:111], v[148:151], v[194:197], v[108:111]
	v_mfma_f32_16x16x32_bf16 v[96:99], v[178:181], v[194:197], v[96:99]
	v_mfma_f32_16x16x32_bf16 v[88:91], v[148:151], v[202:205], v[88:91]
	v_mfma_f32_16x16x32_bf16 v[80:83], v[178:181], v[202:205], v[80:83]
	v_mfma_f32_16x16x32_bf16 v[72:75], v[148:151], v[218:221], v[72:75]
	v_mfma_f32_16x16x32_bf16 v[64:67], v[178:181], v[218:221], v[64:67]
	s_barrier
	s_setprio 0
	s_add_i32 s0, s60, s51
	v_lshl_add_u64 v[206:207], s[42:43], 0, v[158:159]
	s_mov_b32 m0, s0
	ds_read_b128 v[182:185], v212 offset:16384
	ds_read_b128 v[186:189], v212 offset:17408
	ds_read_b128 v[190:193], v212 offset:18432
	ds_read_b128 v[194:197], v212 offset:19456
	ds_read_b128 v[198:201], v212 offset:20480
	ds_read_b128 v[202:205], v212 offset:21504
	ds_read_b128 v[214:217], v212 offset:22528
	ds_read_b128 v[218:221], v212 offset:23552
	global_load_lds_dwordx4 v[206:207], off
	s_add_i32 m0, s0, 0x2000
	s_add_u32 s0, s42, 0x40000
	v_lshl_add_u64 v[222:223], s[42:43], 0, v[162:163]
	s_addc_u32 s1, s43, 0
	s_add_i32 s34, s61, s51
	global_load_lds_dwordx4 v[222:223], off
	s_mov_b32 m0, s34
	s_nop 0
	global_load_lds_dwordx4 v158, s[0:1]
	s_add_i32 m0, s34, 0x2000
	s_nop 0
	global_load_lds_dwordx4 v162, s[0:1]
	s_nop 0
	s_waitcnt lgkmcnt(0)
	s_setprio 1
	s_barrier
	v_mfma_f32_16x16x32_bf16 v[60:63], v[100:103], v[182:185], 0
	v_mfma_f32_16x16x32_bf16 v[52:55], v[136:139], v[182:185], 0
	v_mfma_f32_16x16x32_bf16 v[44:47], v[100:103], v[190:193], 0
	v_mfma_f32_16x16x32_bf16 v[36:39], v[136:139], v[190:193], 0
	v_mfma_f32_16x16x32_bf16 v[28:31], v[100:103], v[198:201], 0
	v_mfma_f32_16x16x32_bf16 v[20:23], v[136:139], v[198:201], 0
	v_mfma_f32_16x16x32_bf16 v[12:15], v[100:103], v[214:217], 0
	v_mfma_f32_16x16x32_bf16 v[4:7], v[136:139], v[214:217], 0
	v_mfma_f32_16x16x32_bf16 v[60:63], v[116:119], v[186:189], v[60:63]
	v_mfma_f32_16x16x32_bf16 v[52:55], v[140:143], v[186:189], v[52:55]
	v_mfma_f32_16x16x32_bf16 v[44:47], v[116:119], v[194:197], v[44:47]
	v_mfma_f32_16x16x32_bf16 v[36:39], v[140:143], v[194:197], v[36:39]
	v_mfma_f32_16x16x32_bf16 v[28:31], v[116:119], v[202:205], v[28:31]
	v_mfma_f32_16x16x32_bf16 v[20:23], v[140:143], v[202:205], v[20:23]
	v_mfma_f32_16x16x32_bf16 v[12:15], v[116:119], v[218:221], v[12:15]
	v_mfma_f32_16x16x32_bf16 v[4:7], v[140:143], v[218:221], v[4:7]
	v_mfma_f32_16x16x32_bf16 v[56:59], v[144:147], v[182:185], 0
	v_mfma_f32_16x16x32_bf16 v[48:51], v[152:155], v[182:185], 0
	v_mfma_f32_16x16x32_bf16 v[40:43], v[144:147], v[190:193], 0
	v_mfma_f32_16x16x32_bf16 v[32:35], v[152:155], v[190:193], 0
	v_mfma_f32_16x16x32_bf16 v[24:27], v[144:147], v[198:201], 0
	v_mfma_f32_16x16x32_bf16 v[16:19], v[152:155], v[198:201], 0
	v_mfma_f32_16x16x32_bf16 v[8:11], v[144:147], v[214:217], 0
	v_mfma_f32_16x16x32_bf16 v[0:3], v[152:155], v[214:217], 0
	v_mfma_f32_16x16x32_bf16 v[56:59], v[148:151], v[186:189], v[56:59]
	v_mfma_f32_16x16x32_bf16 v[48:51], v[178:181], v[186:189], v[48:51]
	v_mfma_f32_16x16x32_bf16 v[40:43], v[148:151], v[194:197], v[40:43]
	v_mfma_f32_16x16x32_bf16 v[32:35], v[178:181], v[194:197], v[32:35]
	v_mfma_f32_16x16x32_bf16 v[24:27], v[148:151], v[202:205], v[24:27]
	v_mfma_f32_16x16x32_bf16 v[16:19], v[178:181], v[202:205], v[16:19]
	v_mfma_f32_16x16x32_bf16 v[8:11], v[148:151], v[218:221], v[8:11]
	v_mfma_f32_16x16x32_bf16 v[0:3], v[178:181], v[218:221], v[0:3]
	s_barrier
	s_setprio 0
	s_add_i32 s34, 0, 0x18000
	s_add_i32 s35, 0, 0x1c000
	v_add_u32_e32 v140, s34, v209
	v_add_u32_e32 v178, s35, v209
	ds_read_b128 v[100:103], v140
	ds_read_b128 v[116:119], v140 offset:1024
	ds_read_b128 v[136:139], v140 offset:2048
	ds_read_b128 v[140:143], v140 offset:3072
	ds_read_b128 v[144:147], v178
	ds_read_b128 v[148:151], v178 offset:1024
	ds_read_b128 v[152:155], v178 offset:2048
	ds_read_b128 v[178:181], v178 offset:3072
	s_add_u32 s0, s44, 0x1000
	s_addc_u32 s1, s45, 0
	s_mov_b32 m0, s54
	ds_read_b128 v[182:185], v212 offset:32768
	ds_read_b128 v[186:189], v212 offset:33792
	ds_read_b128 v[190:193], v212 offset:34816
	ds_read_b128 v[194:197], v212 offset:35840
	ds_read_b128 v[198:201], v212 offset:36864
	ds_read_b128 v[202:205], v212 offset:37888
	ds_read_b128 v[214:217], v212 offset:38912
	ds_read_b128 v[218:221], v212 offset:39936
	global_load_lds_dwordx4 v156, s[0:1]
	s_mov_b32 m0, s55
	s_nop 0
	global_load_lds_dwordx4 v160, s[0:1]
	s_mov_b32 m0, s52
	s_nop 0
	global_load_lds_dwordx4 v156, s[44:45]
	s_mov_b32 m0, s53
	s_nop 0
	global_load_lds_dwordx4 v160, s[44:45]
	s_waitcnt vmcnt(8)
	s_waitcnt lgkmcnt(0)
	s_setprio 1
	s_barrier
	v_mfma_f32_16x16x32_bf16 v[132:135], v[100:103], v[182:185], v[132:135]
	v_mfma_f32_16x16x32_bf16 v[124:127], v[136:139], v[182:185], v[124:127]
	v_mfma_f32_16x16x32_bf16 v[112:115], v[100:103], v[190:193], v[112:115]
	v_mfma_f32_16x16x32_bf16 v[104:107], v[136:139], v[190:193], v[104:107]
	v_mfma_f32_16x16x32_bf16 v[92:95], v[100:103], v[198:201], v[92:95]
	v_mfma_f32_16x16x32_bf16 v[84:87], v[136:139], v[198:201], v[84:87]
	v_mfma_f32_16x16x32_bf16 v[76:79], v[100:103], v[214:217], v[76:79]
	v_mfma_f32_16x16x32_bf16 v[68:71], v[136:139], v[214:217], v[68:71]
	v_mfma_f32_16x16x32_bf16 v[132:135], v[116:119], v[186:189], v[132:135]
	v_mfma_f32_16x16x32_bf16 v[124:127], v[140:143], v[186:189], v[124:127]
	v_mfma_f32_16x16x32_bf16 v[112:115], v[116:119], v[194:197], v[112:115]
	v_mfma_f32_16x16x32_bf16 v[104:107], v[140:143], v[194:197], v[104:107]
	v_mfma_f32_16x16x32_bf16 v[92:95], v[116:119], v[202:205], v[92:95]
	v_mfma_f32_16x16x32_bf16 v[84:87], v[140:143], v[202:205], v[84:87]
	v_mfma_f32_16x16x32_bf16 v[76:79], v[116:119], v[218:221], v[76:79]
	v_mfma_f32_16x16x32_bf16 v[68:71], v[140:143], v[218:221], v[68:71]
	v_mfma_f32_16x16x32_bf16 v[128:131], v[144:147], v[182:185], v[128:131]
	v_mfma_f32_16x16x32_bf16 v[120:123], v[152:155], v[182:185], v[120:123]
	v_mfma_f32_16x16x32_bf16 v[108:111], v[144:147], v[190:193], v[108:111]
	v_mfma_f32_16x16x32_bf16 v[96:99], v[152:155], v[190:193], v[96:99]
	v_mfma_f32_16x16x32_bf16 v[88:91], v[144:147], v[198:201], v[88:91]
	v_mfma_f32_16x16x32_bf16 v[80:83], v[152:155], v[198:201], v[80:83]
	v_mfma_f32_16x16x32_bf16 v[72:75], v[144:147], v[214:217], v[72:75]
	v_mfma_f32_16x16x32_bf16 v[64:67], v[152:155], v[214:217], v[64:67]
	v_mfma_f32_16x16x32_bf16 v[128:131], v[148:151], v[186:189], v[128:131]
	v_mfma_f32_16x16x32_bf16 v[120:123], v[178:181], v[186:189], v[120:123]
	v_mfma_f32_16x16x32_bf16 v[108:111], v[148:151], v[194:197], v[108:111]
	v_mfma_f32_16x16x32_bf16 v[96:99], v[178:181], v[194:197], v[96:99]
	v_mfma_f32_16x16x32_bf16 v[88:91], v[148:151], v[202:205], v[88:91]
	v_mfma_f32_16x16x32_bf16 v[80:83], v[178:181], v[202:205], v[80:83]
	v_mfma_f32_16x16x32_bf16 v[72:75], v[148:151], v[218:221], v[72:75]
	v_mfma_f32_16x16x32_bf16 v[64:67], v[178:181], v[218:221], v[64:67]
	s_barrier
	s_setprio 0
	s_add_i32 s0, s34, s51
	v_lshl_add_u64 v[206:207], v[206:207], 0, s[16:17]
	s_mov_b32 m0, s0
	ds_read_b128 v[182:185], v212 offset:49152
	ds_read_b128 v[186:189], v212 offset:50176
	ds_read_b128 v[190:193], v212 offset:51200
	ds_read_b128 v[194:197], v212 offset:52224
	ds_read_b128 v[198:201], v212 offset:53248
	ds_read_b128 v[202:205], v212 offset:54272
	ds_read_b128 v[214:217], v212 offset:55296
	ds_read_b128 v[218:221], v212 offset:56320
	global_load_lds_dwordx4 v[206:207], off
	s_add_i32 m0, s0, 0x2000
	s_add_u32 s0, s42, 0x40080
	v_lshl_add_u64 v[206:207], v[222:223], 0, s[16:17]
	s_addc_u32 s1, s43, 0
	s_add_i32 s34, s35, s51
	global_load_lds_dwordx4 v[206:207], off
	s_mov_b32 m0, s34
	s_nop 0
	global_load_lds_dwordx4 v158, s[0:1]
	s_add_i32 m0, s34, 0x2000
	s_nop 0
	global_load_lds_dwordx4 v162, s[0:1]
	s_mov_b32 m0, s56
	s_nop 0
	global_load_lds_dwordx4 v156, s[40:41]
	s_mov_b32 m0, s57
	s_nop 0
	global_load_lds_dwordx4 v160, s[40:41]
	s_waitcnt vmcnt(6)
	s_waitcnt lgkmcnt(0)
	s_setprio 1
	s_barrier
	v_mfma_f32_16x16x32_bf16 v[60:63], v[100:103], v[182:185], v[60:63]
	v_mfma_f32_16x16x32_bf16 v[52:55], v[136:139], v[182:185], v[52:55]
	v_mfma_f32_16x16x32_bf16 v[44:47], v[100:103], v[190:193], v[44:47]
	v_mfma_f32_16x16x32_bf16 v[36:39], v[136:139], v[190:193], v[36:39]
	v_mfma_f32_16x16x32_bf16 v[28:31], v[100:103], v[198:201], v[28:31]
	v_mfma_f32_16x16x32_bf16 v[20:23], v[136:139], v[198:201], v[20:23]
	v_mfma_f32_16x16x32_bf16 v[12:15], v[100:103], v[214:217], v[12:15]
	v_mfma_f32_16x16x32_bf16 v[4:7], v[136:139], v[214:217], v[4:7]
	v_mfma_f32_16x16x32_bf16 v[60:63], v[116:119], v[186:189], v[60:63]
	v_mfma_f32_16x16x32_bf16 v[52:55], v[140:143], v[186:189], v[52:55]
	v_mfma_f32_16x16x32_bf16 v[44:47], v[116:119], v[194:197], v[44:47]
	v_mfma_f32_16x16x32_bf16 v[36:39], v[140:143], v[194:197], v[36:39]
	v_mfma_f32_16x16x32_bf16 v[28:31], v[116:119], v[202:205], v[28:31]
	v_mfma_f32_16x16x32_bf16 v[20:23], v[140:143], v[202:205], v[20:23]
	v_mfma_f32_16x16x32_bf16 v[12:15], v[116:119], v[218:221], v[12:15]
	v_mfma_f32_16x16x32_bf16 v[4:7], v[140:143], v[218:221], v[4:7]
	v_mfma_f32_16x16x32_bf16 v[56:59], v[144:147], v[182:185], v[56:59]
	v_mfma_f32_16x16x32_bf16 v[48:51], v[152:155], v[182:185], v[48:51]
	v_mfma_f32_16x16x32_bf16 v[40:43], v[144:147], v[190:193], v[40:43]
	v_mfma_f32_16x16x32_bf16 v[32:35], v[152:155], v[190:193], v[32:35]
	v_mfma_f32_16x16x32_bf16 v[24:27], v[144:147], v[198:201], v[24:27]
	v_mfma_f32_16x16x32_bf16 v[16:19], v[152:155], v[198:201], v[16:19]
	v_mfma_f32_16x16x32_bf16 v[8:11], v[144:147], v[214:217], v[8:11]
	v_mfma_f32_16x16x32_bf16 v[0:3], v[152:155], v[214:217], v[0:3]
	v_mfma_f32_16x16x32_bf16 v[56:59], v[148:151], v[186:189], v[56:59]
	v_mfma_f32_16x16x32_bf16 v[48:51], v[178:181], v[186:189], v[48:51]
	v_mfma_f32_16x16x32_bf16 v[40:43], v[148:151], v[194:197], v[40:43]
	v_mfma_f32_16x16x32_bf16 v[32:35], v[178:181], v[194:197], v[32:35]
	v_mfma_f32_16x16x32_bf16 v[24:27], v[148:151], v[202:205], v[24:27]
	v_mfma_f32_16x16x32_bf16 v[16:19], v[178:181], v[202:205], v[16:19]
	v_mfma_f32_16x16x32_bf16 v[8:11], v[148:151], v[218:221], v[8:11]
	v_mfma_f32_16x16x32_bf16 v[0:3], v[178:181], v[218:221], v[0:3]
	s_barrier
	s_setprio 0
	s_add_i32 s65, s65, 2
	s_add_u32 s63, s63, 0x100
	s_addc_u32 s64, s64, 0
	s_cmp_gt_u32 s65, 13
	s_mov_b64 s[34:35], s[36:37]
.LBB0_480:
	ds_read_b128 v[100:103], v210
	ds_read_b128 v[116:119], v210 offset:1024
	ds_read_b128 v[136:139], v210 offset:2048
	ds_read_b128 v[140:143], v210 offset:3072
	ds_read_b128 v[144:147], v211
	ds_read_b128 v[148:151], v211 offset:1024
	ds_read_b128 v[152:155], v211 offset:2048
	ds_read_b128 v[178:181], v211 offset:3072
	s_add_u32 s36, s34, 0x1000000
	s_addc_u32 s37, s35, 0
	s_cmp_eq_u32 s65, 12
	s_cselect_b32 s44, s29, s36
	s_cselect_b32 s45, s23, s37
	s_cselect_b32 s42, s31, s63
	s_cselect_b32 s43, s21, s64
	s_add_u32 s40, s44, 0x800000
	s_addc_u32 s41, s45, 0
	s_add_i32 m0, s52, 0xc000
	ds_read_b128 v[182:185], v212
	ds_read_b128 v[186:189], v212 offset:1024
	ds_read_b128 v[190:193], v212 offset:2048
	ds_read_b128 v[194:197], v212 offset:3072
	ds_read_b128 v[198:201], v212 offset:4096
	ds_read_b128 v[202:205], v212 offset:5120
	ds_read_b128 v[214:217], v212 offset:6144
	ds_read_b128 v[218:221], v212 offset:7168
	global_load_lds_dwordx4 v170, s[34:35]
	s_add_i32 m0, s52, 0xe000
	s_nop 0
	global_load_lds_dwordx4 v172, s[34:35]
	s_waitcnt vmcnt(8)
	s_waitcnt lgkmcnt(0)
	s_setprio 1
	s_barrier
	v_mfma_f32_16x16x32_bf16 v[132:135], v[100:103], v[182:185], v[132:135]
	v_mfma_f32_16x16x32_bf16 v[124:127], v[136:139], v[182:185], v[124:127]
	v_mfma_f32_16x16x32_bf16 v[112:115], v[100:103], v[190:193], v[112:115]
	v_mfma_f32_16x16x32_bf16 v[104:107], v[136:139], v[190:193], v[104:107]
	v_mfma_f32_16x16x32_bf16 v[92:95], v[100:103], v[198:201], v[92:95]
	v_mfma_f32_16x16x32_bf16 v[84:87], v[136:139], v[198:201], v[84:87]
	v_mfma_f32_16x16x32_bf16 v[76:79], v[100:103], v[214:217], v[76:79]
	v_mfma_f32_16x16x32_bf16 v[68:71], v[136:139], v[214:217], v[68:71]
	v_mfma_f32_16x16x32_bf16 v[132:135], v[116:119], v[186:189], v[132:135]
	v_mfma_f32_16x16x32_bf16 v[124:127], v[140:143], v[186:189], v[124:127]
	v_mfma_f32_16x16x32_bf16 v[112:115], v[116:119], v[194:197], v[112:115]
	v_mfma_f32_16x16x32_bf16 v[104:107], v[140:143], v[194:197], v[104:107]
	v_mfma_f32_16x16x32_bf16 v[92:95], v[116:119], v[202:205], v[92:95]
	v_mfma_f32_16x16x32_bf16 v[84:87], v[140:143], v[202:205], v[84:87]
	v_mfma_f32_16x16x32_bf16 v[76:79], v[116:119], v[218:221], v[76:79]
	v_mfma_f32_16x16x32_bf16 v[68:71], v[140:143], v[218:221], v[68:71]
	v_mfma_f32_16x16x32_bf16 v[128:131], v[144:147], v[182:185], v[128:131]
	v_mfma_f32_16x16x32_bf16 v[120:123], v[152:155], v[182:185], v[120:123]
	v_mfma_f32_16x16x32_bf16 v[108:111], v[144:147], v[190:193], v[108:111]
	v_mfma_f32_16x16x32_bf16 v[96:99], v[152:155], v[190:193], v[96:99]
	v_mfma_f32_16x16x32_bf16 v[88:91], v[144:147], v[198:201], v[88:91]
	v_mfma_f32_16x16x32_bf16 v[80:83], v[152:155], v[198:201], v[80:83]
	v_mfma_f32_16x16x32_bf16 v[72:75], v[144:147], v[214:217], v[72:75]
	v_mfma_f32_16x16x32_bf16 v[64:67], v[152:155], v[214:217], v[64:67]
	v_mfma_f32_16x16x32_bf16 v[128:131], v[148:151], v[186:189], v[128:131]
	v_mfma_f32_16x16x32_bf16 v[120:123], v[178:181], v[186:189], v[120:123]
	v_mfma_f32_16x16x32_bf16 v[108:111], v[148:151], v[194:197], v[108:111]
	v_mfma_f32_16x16x32_bf16 v[96:99], v[178:181], v[194:197], v[96:99]
	v_mfma_f32_16x16x32_bf16 v[88:91], v[148:151], v[202:205], v[88:91]
	v_mfma_f32_16x16x32_bf16 v[80:83], v[178:181], v[202:205], v[80:83]
	v_mfma_f32_16x16x32_bf16 v[72:75], v[148:151], v[218:221], v[72:75]
	v_mfma_f32_16x16x32_bf16 v[64:67], v[178:181], v[218:221], v[64:67]
	s_barrier
	s_setprio 0
	s_add_i32 s0, s60, s51
	v_lshl_add_u64 v[206:207], s[42:43], 0, v[158:159]
	s_mov_b32 m0, s0
	ds_read_b128 v[182:185], v212 offset:16384
	ds_read_b128 v[186:189], v212 offset:17408
	ds_read_b128 v[190:193], v212 offset:18432
	ds_read_b128 v[194:197], v212 offset:19456
	ds_read_b128 v[198:201], v212 offset:20480
	ds_read_b128 v[202:205], v212 offset:21504
	ds_read_b128 v[214:217], v212 offset:22528
	ds_read_b128 v[218:221], v212 offset:23552
	global_load_lds_dwordx4 v[206:207], off
	s_add_i32 m0, s0, 0x2000
	s_add_u32 s0, s42, 0x40000
	v_lshl_add_u64 v[222:223], s[42:43], 0, v[162:163]
	s_addc_u32 s1, s43, 0
	s_add_i32 s34, s61, s51
	global_load_lds_dwordx4 v[222:223], off
	s_mov_b32 m0, s34
	s_nop 0
	global_load_lds_dwordx4 v158, s[0:1]
	s_add_i32 m0, s34, 0x2000
	s_nop 0
	global_load_lds_dwordx4 v162, s[0:1]
	s_waitcnt vmcnt(6)
	s_waitcnt lgkmcnt(0)
	s_setprio 1
	s_barrier
	v_mfma_f32_16x16x32_bf16 v[60:63], v[100:103], v[182:185], v[60:63]
	v_mfma_f32_16x16x32_bf16 v[52:55], v[136:139], v[182:185], v[52:55]
	v_mfma_f32_16x16x32_bf16 v[44:47], v[100:103], v[190:193], v[44:47]
	v_mfma_f32_16x16x32_bf16 v[36:39], v[136:139], v[190:193], v[36:39]
	v_mfma_f32_16x16x32_bf16 v[28:31], v[100:103], v[198:201], v[28:31]
	v_mfma_f32_16x16x32_bf16 v[20:23], v[136:139], v[198:201], v[20:23]
	v_mfma_f32_16x16x32_bf16 v[12:15], v[100:103], v[214:217], v[12:15]
	v_mfma_f32_16x16x32_bf16 v[4:7], v[136:139], v[214:217], v[4:7]
	v_mfma_f32_16x16x32_bf16 v[60:63], v[116:119], v[186:189], v[60:63]
	v_mfma_f32_16x16x32_bf16 v[52:55], v[140:143], v[186:189], v[52:55]
	v_mfma_f32_16x16x32_bf16 v[44:47], v[116:119], v[194:197], v[44:47]
	v_mfma_f32_16x16x32_bf16 v[36:39], v[140:143], v[194:197], v[36:39]
	v_mfma_f32_16x16x32_bf16 v[28:31], v[116:119], v[202:205], v[28:31]
	v_mfma_f32_16x16x32_bf16 v[20:23], v[140:143], v[202:205], v[20:23]
	v_mfma_f32_16x16x32_bf16 v[12:15], v[116:119], v[218:221], v[12:15]
	v_mfma_f32_16x16x32_bf16 v[4:7], v[140:143], v[218:221], v[4:7]
	v_mfma_f32_16x16x32_bf16 v[56:59], v[144:147], v[182:185], v[56:59]
	v_mfma_f32_16x16x32_bf16 v[48:51], v[152:155], v[182:185], v[48:51]
	v_mfma_f32_16x16x32_bf16 v[40:43], v[144:147], v[190:193], v[40:43]
	v_mfma_f32_16x16x32_bf16 v[32:35], v[152:155], v[190:193], v[32:35]
	v_mfma_f32_16x16x32_bf16 v[24:27], v[144:147], v[198:201], v[24:27]
	v_mfma_f32_16x16x32_bf16 v[16:19], v[152:155], v[198:201], v[16:19]
	v_mfma_f32_16x16x32_bf16 v[8:11], v[144:147], v[214:217], v[8:11]
	v_mfma_f32_16x16x32_bf16 v[0:3], v[152:155], v[214:217], v[0:3]
	v_mfma_f32_16x16x32_bf16 v[56:59], v[148:151], v[186:189], v[56:59]
	v_mfma_f32_16x16x32_bf16 v[48:51], v[178:181], v[186:189], v[48:51]
	v_mfma_f32_16x16x32_bf16 v[40:43], v[148:151], v[194:197], v[40:43]
	v_mfma_f32_16x16x32_bf16 v[32:35], v[178:181], v[194:197], v[32:35]
	v_mfma_f32_16x16x32_bf16 v[24:27], v[148:151], v[202:205], v[24:27]
	v_mfma_f32_16x16x32_bf16 v[16:19], v[178:181], v[202:205], v[16:19]
	v_mfma_f32_16x16x32_bf16 v[8:11], v[148:151], v[218:221], v[8:11]
	v_mfma_f32_16x16x32_bf16 v[0:3], v[178:181], v[218:221], v[0:3]
	s_barrier
	s_setprio 0
	s_add_i32 s34, 0, 0x18000
	s_add_i32 s35, 0, 0x1c000
	v_add_u32_e32 v140, s34, v209
	v_add_u32_e32 v178, s35, v209
	ds_read_b128 v[100:103], v140
	ds_read_b128 v[116:119], v140 offset:1024
	ds_read_b128 v[136:139], v140 offset:2048
	ds_read_b128 v[140:143], v140 offset:3072
	ds_read_b128 v[144:147], v178
	ds_read_b128 v[148:151], v178 offset:1024
	ds_read_b128 v[152:155], v178 offset:2048
	ds_read_b128 v[178:181], v178 offset:3072
	s_add_u32 s0, s44, 0x1000
	s_addc_u32 s1, s45, 0
	s_mov_b32 m0, s54
	ds_read_b128 v[182:185], v212 offset:32768
	ds_read_b128 v[186:189], v212 offset:33792
	ds_read_b128 v[190:193], v212 offset:34816
	ds_read_b128 v[194:197], v212 offset:35840
	ds_read_b128 v[198:201], v212 offset:36864
	ds_read_b128 v[202:205], v212 offset:37888
	ds_read_b128 v[214:217], v212 offset:38912
	ds_read_b128 v[218:221], v212 offset:39936
	global_load_lds_dwordx4 v156, s[0:1]
	s_mov_b32 m0, s55
	s_nop 0
	global_load_lds_dwordx4 v160, s[0:1]
	s_mov_b32 m0, s52
	s_nop 0
	global_load_lds_dwordx4 v156, s[44:45]
	s_mov_b32 m0, s53
	s_nop 0
	global_load_lds_dwordx4 v160, s[44:45]
	s_waitcnt vmcnt(8)
	s_waitcnt lgkmcnt(0)
	s_setprio 1
	s_barrier
	v_mfma_f32_16x16x32_bf16 v[132:135], v[100:103], v[182:185], v[132:135]
	v_mfma_f32_16x16x32_bf16 v[124:127], v[136:139], v[182:185], v[124:127]
	v_mfma_f32_16x16x32_bf16 v[112:115], v[100:103], v[190:193], v[112:115]
	v_mfma_f32_16x16x32_bf16 v[104:107], v[136:139], v[190:193], v[104:107]
	v_mfma_f32_16x16x32_bf16 v[92:95], v[100:103], v[198:201], v[92:95]
	v_mfma_f32_16x16x32_bf16 v[84:87], v[136:139], v[198:201], v[84:87]
	v_mfma_f32_16x16x32_bf16 v[76:79], v[100:103], v[214:217], v[76:79]
	v_mfma_f32_16x16x32_bf16 v[68:71], v[136:139], v[214:217], v[68:71]
	v_mfma_f32_16x16x32_bf16 v[132:135], v[116:119], v[186:189], v[132:135]
	v_mfma_f32_16x16x32_bf16 v[124:127], v[140:143], v[186:189], v[124:127]
	v_mfma_f32_16x16x32_bf16 v[112:115], v[116:119], v[194:197], v[112:115]
	v_mfma_f32_16x16x32_bf16 v[104:107], v[140:143], v[194:197], v[104:107]
	v_mfma_f32_16x16x32_bf16 v[92:95], v[116:119], v[202:205], v[92:95]
	v_mfma_f32_16x16x32_bf16 v[84:87], v[140:143], v[202:205], v[84:87]
	v_mfma_f32_16x16x32_bf16 v[76:79], v[116:119], v[218:221], v[76:79]
	v_mfma_f32_16x16x32_bf16 v[68:71], v[140:143], v[218:221], v[68:71]
	v_mfma_f32_16x16x32_bf16 v[128:131], v[144:147], v[182:185], v[128:131]
	v_mfma_f32_16x16x32_bf16 v[120:123], v[152:155], v[182:185], v[120:123]
	v_mfma_f32_16x16x32_bf16 v[108:111], v[144:147], v[190:193], v[108:111]
	v_mfma_f32_16x16x32_bf16 v[96:99], v[152:155], v[190:193], v[96:99]
	v_mfma_f32_16x16x32_bf16 v[88:91], v[144:147], v[198:201], v[88:91]
	v_mfma_f32_16x16x32_bf16 v[80:83], v[152:155], v[198:201], v[80:83]
	v_mfma_f32_16x16x32_bf16 v[72:75], v[144:147], v[214:217], v[72:75]
	v_mfma_f32_16x16x32_bf16 v[64:67], v[152:155], v[214:217], v[64:67]
	v_mfma_f32_16x16x32_bf16 v[128:131], v[148:151], v[186:189], v[128:131]
	v_mfma_f32_16x16x32_bf16 v[120:123], v[178:181], v[186:189], v[120:123]
	v_mfma_f32_16x16x32_bf16 v[108:111], v[148:151], v[194:197], v[108:111]
	v_mfma_f32_16x16x32_bf16 v[96:99], v[178:181], v[194:197], v[96:99]
	v_mfma_f32_16x16x32_bf16 v[88:91], v[148:151], v[202:205], v[88:91]
	v_mfma_f32_16x16x32_bf16 v[80:83], v[178:181], v[202:205], v[80:83]
	v_mfma_f32_16x16x32_bf16 v[72:75], v[148:151], v[218:221], v[72:75]
	v_mfma_f32_16x16x32_bf16 v[64:67], v[178:181], v[218:221], v[64:67]
	s_barrier
	s_setprio 0
	s_add_i32 s0, s34, s51
	v_lshl_add_u64 v[206:207], v[206:207], 0, s[16:17]
	s_mov_b32 m0, s0
	ds_read_b128 v[182:185], v212 offset:49152
	ds_read_b128 v[186:189], v212 offset:50176
	ds_read_b128 v[190:193], v212 offset:51200
	ds_read_b128 v[194:197], v212 offset:52224
	ds_read_b128 v[198:201], v212 offset:53248
	ds_read_b128 v[202:205], v212 offset:54272
	ds_read_b128 v[214:217], v212 offset:55296
	ds_read_b128 v[218:221], v212 offset:56320
	global_load_lds_dwordx4 v[206:207], off
	s_add_i32 m0, s0, 0x2000
	s_add_u32 s0, s42, 0x40080
	v_lshl_add_u64 v[206:207], v[222:223], 0, s[16:17]
	s_addc_u32 s1, s43, 0
	s_add_i32 s34, s35, s51
	global_load_lds_dwordx4 v[206:207], off
	s_mov_b32 m0, s34
	s_nop 0
	global_load_lds_dwordx4 v158, s[0:1]
	s_add_i32 m0, s34, 0x2000
	s_nop 0
	global_load_lds_dwordx4 v162, s[0:1]
	s_mov_b32 m0, s56
	s_nop 0
	global_load_lds_dwordx4 v156, s[40:41]
	s_mov_b32 m0, s57
	s_nop 0
	global_load_lds_dwordx4 v160, s[40:41]
	s_waitcnt vmcnt(6)
	s_waitcnt lgkmcnt(0)
	s_setprio 1
	s_barrier
	v_mfma_f32_16x16x32_bf16 v[60:63], v[100:103], v[182:185], v[60:63]
	v_mfma_f32_16x16x32_bf16 v[52:55], v[136:139], v[182:185], v[52:55]
	v_mfma_f32_16x16x32_bf16 v[44:47], v[100:103], v[190:193], v[44:47]
	v_mfma_f32_16x16x32_bf16 v[36:39], v[136:139], v[190:193], v[36:39]
	v_mfma_f32_16x16x32_bf16 v[28:31], v[100:103], v[198:201], v[28:31]
	v_mfma_f32_16x16x32_bf16 v[20:23], v[136:139], v[198:201], v[20:23]
	v_mfma_f32_16x16x32_bf16 v[12:15], v[100:103], v[214:217], v[12:15]
	v_mfma_f32_16x16x32_bf16 v[4:7], v[136:139], v[214:217], v[4:7]
	v_mfma_f32_16x16x32_bf16 v[60:63], v[116:119], v[186:189], v[60:63]
	v_mfma_f32_16x16x32_bf16 v[52:55], v[140:143], v[186:189], v[52:55]
	v_mfma_f32_16x16x32_bf16 v[44:47], v[116:119], v[194:197], v[44:47]
	v_mfma_f32_16x16x32_bf16 v[36:39], v[140:143], v[194:197], v[36:39]
	v_mfma_f32_16x16x32_bf16 v[28:31], v[116:119], v[202:205], v[28:31]
	v_mfma_f32_16x16x32_bf16 v[20:23], v[140:143], v[202:205], v[20:23]
	v_mfma_f32_16x16x32_bf16 v[12:15], v[116:119], v[218:221], v[12:15]
	v_mfma_f32_16x16x32_bf16 v[4:7], v[140:143], v[218:221], v[4:7]
	v_mfma_f32_16x16x32_bf16 v[56:59], v[144:147], v[182:185], v[56:59]
	v_mfma_f32_16x16x32_bf16 v[48:51], v[152:155], v[182:185], v[48:51]
	v_mfma_f32_16x16x32_bf16 v[40:43], v[144:147], v[190:193], v[40:43]
	v_mfma_f32_16x16x32_bf16 v[32:35], v[152:155], v[190:193], v[32:35]
	v_mfma_f32_16x16x32_bf16 v[24:27], v[144:147], v[198:201], v[24:27]
	v_mfma_f32_16x16x32_bf16 v[16:19], v[152:155], v[198:201], v[16:19]
	v_mfma_f32_16x16x32_bf16 v[8:11], v[144:147], v[214:217], v[8:11]
	v_mfma_f32_16x16x32_bf16 v[0:3], v[152:155], v[214:217], v[0:3]
	v_mfma_f32_16x16x32_bf16 v[56:59], v[148:151], v[186:189], v[56:59]
	v_mfma_f32_16x16x32_bf16 v[48:51], v[178:181], v[186:189], v[48:51]
	v_mfma_f32_16x16x32_bf16 v[40:43], v[148:151], v[194:197], v[40:43]
	v_mfma_f32_16x16x32_bf16 v[32:35], v[178:181], v[194:197], v[32:35]
	v_mfma_f32_16x16x32_bf16 v[24:27], v[148:151], v[202:205], v[24:27]
	v_mfma_f32_16x16x32_bf16 v[16:19], v[178:181], v[202:205], v[16:19]
	v_mfma_f32_16x16x32_bf16 v[8:11], v[148:151], v[218:221], v[8:11]
	v_mfma_f32_16x16x32_bf16 v[0:3], v[178:181], v[218:221], v[0:3]
	s_barrier
	s_setprio 0
	s_add_i32 s65, s65, 2
	s_add_u32 s63, s63, 0x100
	s_addc_u32 s64, s64, 0
	s_cmp_gt_u32 s65, 13
	s_mov_b64 s[34:35], s[36:37]
	s_cbranch_scc0 .LBB0_480
	s_and_b64 vcc, exec, s[18:19]
	s_cbranch_vccz .LBB0_483
	s_barrier

.Lrestag_577:
	s_add_u32 s52, s50, 0x100
	s_addc_u32 s53, s51, 0
	s_add_i32 s0, 0, 0x10000
	s_cmp_eq_u32 s76, 12
	s_cselect_b32 s57, s43, s53
	s_cselect_b32 s56, s67, s52
	s_cselect_b32 s55, s41, s75
	s_cselect_b32 s54, s68, s69
	s_add_i32 s12, 0, 0x14000
	v_add_u32_e32 v154, s0, v188
	v_add_u32_e32 v166, s12, v188
	ds_read_b128 v[142:145], v154
	ds_read_b128 v[146:149], v154 offset:1024
	ds_read_b128 v[150:153], v154 offset:2048
	ds_read_b128 v[154:157], v154 offset:3072
	ds_read_b128 v[158:161], v166
	ds_read_b128 v[162:165], v166 offset:1024
	ds_read_b128 v[184:187], v166 offset:2048
	ds_read_b128 v[190:193], v166 offset:3072
	s_add_i32 m0, s49, 0xc000
	ds_read_b128 v[194:197], v189
	ds_read_b128 v[198:201], v189 offset:1024
	ds_read_b128 v[202:205], v189 offset:2048
	ds_read_b128 v[206:209], v189 offset:3072
	ds_read_b128 v[210:213], v189 offset:4096
	ds_read_b128 v[214:217], v189 offset:5120
	ds_read_b128 v[228:231], v189 offset:6144
	ds_read_b128 v[232:235], v189 offset:7168
	global_load_lds_dwordx4 v138, s[50:51]
	s_add_i32 m0, s49, 0xe000
	s_nop 0
	global_load_lds_dwordx4 v140, s[50:51]
	s_nop 0
	s_waitcnt lgkmcnt(0)
	s_setprio 1
	s_barrier
	v_mfma_f32_16x16x32_bf16 v[124:127], v[142:145], v[194:197], 0
	v_mfma_f32_16x16x32_bf16 v[120:123], v[150:153], v[194:197], 0
	v_mfma_f32_16x16x32_bf16 v[108:111], v[142:145], v[202:205], 0
	v_mfma_f32_16x16x32_bf16 v[104:107], v[150:153], v[202:205], 0
	v_mfma_f32_16x16x32_bf16 v[92:95], v[142:145], v[210:213], 0
	v_mfma_f32_16x16x32_bf16 v[88:91], v[150:153], v[210:213], 0
	v_mfma_f32_16x16x32_bf16 v[76:79], v[142:145], v[228:231], 0
	v_mfma_f32_16x16x32_bf16 v[72:75], v[150:153], v[228:231], 0
	v_mfma_f32_16x16x32_bf16 v[124:127], v[146:149], v[198:201], v[124:127]
	v_mfma_f32_16x16x32_bf16 v[120:123], v[154:157], v[198:201], v[120:123]
	v_mfma_f32_16x16x32_bf16 v[108:111], v[146:149], v[206:209], v[108:111]
	v_mfma_f32_16x16x32_bf16 v[104:107], v[154:157], v[206:209], v[104:107]
	v_mfma_f32_16x16x32_bf16 v[92:95], v[146:149], v[214:217], v[92:95]
	v_mfma_f32_16x16x32_bf16 v[88:91], v[154:157], v[214:217], v[88:91]
	v_mfma_f32_16x16x32_bf16 v[76:79], v[146:149], v[232:235], v[76:79]
	v_mfma_f32_16x16x32_bf16 v[72:75], v[154:157], v[232:235], v[72:75]
	v_mfma_f32_16x16x32_bf16 v[116:119], v[158:161], v[194:197], 0
	v_mfma_f32_16x16x32_bf16 v[112:115], v[184:187], v[194:197], 0
	v_mfma_f32_16x16x32_bf16 v[100:103], v[158:161], v[202:205], 0
	v_mfma_f32_16x16x32_bf16 v[96:99], v[184:187], v[202:205], 0
	v_mfma_f32_16x16x32_bf16 v[84:87], v[158:161], v[210:213], 0
	v_mfma_f32_16x16x32_bf16 v[80:83], v[184:187], v[210:213], 0
	v_mfma_f32_16x16x32_bf16 v[68:71], v[158:161], v[228:231], 0
	v_mfma_f32_16x16x32_bf16 v[64:67], v[184:187], v[228:231], 0
	v_mfma_f32_16x16x32_bf16 v[116:119], v[162:165], v[198:201], v[116:119]
	v_mfma_f32_16x16x32_bf16 v[112:115], v[190:193], v[198:201], v[112:115]
	v_mfma_f32_16x16x32_bf16 v[100:103], v[162:165], v[206:209], v[100:103]
	v_mfma_f32_16x16x32_bf16 v[96:99], v[190:193], v[206:209], v[96:99]
	v_mfma_f32_16x16x32_bf16 v[84:87], v[162:165], v[214:217], v[84:87]
	v_mfma_f32_16x16x32_bf16 v[80:83], v[190:193], v[214:217], v[80:83]
	v_mfma_f32_16x16x32_bf16 v[68:71], v[162:165], v[232:235], v[68:71]
	v_mfma_f32_16x16x32_bf16 v[64:67], v[190:193], v[232:235], v[64:67]
	s_barrier
	s_setprio 0
	s_add_i32 s0, s0, s59
	v_lshl_add_u64 v[166:167], s[54:55], 0, v[130:131]
	s_mov_b32 m0, s0
	ds_read_b128 v[194:197], v189 offset:16384
	ds_read_b128 v[198:201], v189 offset:17408
	ds_read_b128 v[202:205], v189 offset:18432
	ds_read_b128 v[206:209], v189 offset:19456
	ds_read_b128 v[210:213], v189 offset:20480
	ds_read_b128 v[214:217], v189 offset:21504
	ds_read_b128 v[228:231], v189 offset:22528
	ds_read_b128 v[232:235], v189 offset:23552
	global_load_lds_dwordx4 v[166:167], off
	s_add_i32 m0, s0, 0x2000
	s_add_u32 s0, s54, 0x40000
	v_lshl_add_u64 v[218:219], s[54:55], 0, v[134:135]
	s_addc_u32 s1, s55, 0
	s_add_i32 s12, s12, s59
	global_load_lds_dwordx4 v[218:219], off
	s_mov_b32 m0, s12
	v_lshl_add_u64 v[238:239], s[56:57], 0, v[132:133]
	global_load_lds_dwordx4 v130, s[0:1]
	s_add_i32 m0, s12, 0x2000
	s_nop 0
	global_load_lds_dwordx4 v134, s[0:1]
	v_lshl_add_u64 v[236:237], s[56:57], 0, v[128:129]
	s_nop 0
	s_waitcnt lgkmcnt(0)
	s_setprio 1
	s_barrier
	v_mfma_f32_16x16x32_bf16 v[60:63], v[142:145], v[194:197], 0
	v_mfma_f32_16x16x32_bf16 v[56:59], v[150:153], v[194:197], 0
	v_mfma_f32_16x16x32_bf16 v[44:47], v[142:145], v[202:205], 0
	v_mfma_f32_16x16x32_bf16 v[40:43], v[150:153], v[202:205], 0
	v_mfma_f32_16x16x32_bf16 v[28:31], v[142:145], v[210:213], 0
	v_mfma_f32_16x16x32_bf16 v[24:27], v[150:153], v[210:213], 0
	v_mfma_f32_16x16x32_bf16 v[12:15], v[142:145], v[228:231], 0
	v_mfma_f32_16x16x32_bf16 v[8:11], v[150:153], v[228:231], 0
	v_mfma_f32_16x16x32_bf16 v[60:63], v[146:149], v[198:201], v[60:63]
	v_mfma_f32_16x16x32_bf16 v[56:59], v[154:157], v[198:201], v[56:59]
	v_mfma_f32_16x16x32_bf16 v[44:47], v[146:149], v[206:209], v[44:47]
	v_mfma_f32_16x16x32_bf16 v[40:43], v[154:157], v[206:209], v[40:43]
	v_mfma_f32_16x16x32_bf16 v[28:31], v[146:149], v[214:217], v[28:31]
	v_mfma_f32_16x16x32_bf16 v[24:27], v[154:157], v[214:217], v[24:27]
	v_mfma_f32_16x16x32_bf16 v[12:15], v[146:149], v[232:235], v[12:15]
	v_mfma_f32_16x16x32_bf16 v[8:11], v[154:157], v[232:235], v[8:11]
	v_mfma_f32_16x16x32_bf16 v[52:55], v[158:161], v[194:197], 0
	v_mfma_f32_16x16x32_bf16 v[48:51], v[184:187], v[194:197], 0
	v_mfma_f32_16x16x32_bf16 v[36:39], v[158:161], v[202:205], 0
	v_mfma_f32_16x16x32_bf16 v[32:35], v[184:187], v[202:205], 0
	v_mfma_f32_16x16x32_bf16 v[20:23], v[158:161], v[210:213], 0
	v_mfma_f32_16x16x32_bf16 v[16:19], v[184:187], v[210:213], 0
	v_mfma_f32_16x16x32_bf16 v[4:7], v[158:161], v[228:231], 0
	v_mfma_f32_16x16x32_bf16 v[0:3], v[184:187], v[228:231], 0
	v_mfma_f32_16x16x32_bf16 v[52:55], v[162:165], v[198:201], v[52:55]
	v_mfma_f32_16x16x32_bf16 v[48:51], v[190:193], v[198:201], v[48:51]
	v_mfma_f32_16x16x32_bf16 v[36:39], v[162:165], v[206:209], v[36:39]
	v_mfma_f32_16x16x32_bf16 v[32:35], v[190:193], v[206:209], v[32:35]
	v_mfma_f32_16x16x32_bf16 v[20:23], v[162:165], v[214:217], v[20:23]
	v_mfma_f32_16x16x32_bf16 v[16:19], v[190:193], v[214:217], v[16:19]
	v_mfma_f32_16x16x32_bf16 v[4:7], v[162:165], v[232:235], v[4:7]
	v_mfma_f32_16x16x32_bf16 v[0:3], v[190:193], v[232:235], v[0:3]
	s_barrier
	s_setprio 0
	s_add_i32 s12, 0, 0x18000
	s_add_i32 s13, 0, 0x1c000
	v_add_u32_e32 v154, s12, v188
	v_add_u32_e32 v170, s13, v188
	ds_read_b128 v[142:145], v154
	ds_read_b128 v[146:149], v154 offset:1024
	ds_read_b128 v[150:153], v154 offset:2048
	ds_read_b128 v[154:157], v154 offset:3072
	ds_read_b128 v[158:161], v170
	ds_read_b128 v[162:165], v170 offset:1024
	ds_read_b128 v[184:187], v170 offset:2048
	ds_read_b128 v[190:193], v170 offset:3072
	s_add_u32 s0, s56, 0x40000
	s_addc_u32 s1, s57, 0
	s_mov_b32 m0, s61
	ds_read_b128 v[194:197], v189 offset:32768
	ds_read_b128 v[198:201], v189 offset:33792
	ds_read_b128 v[202:205], v189 offset:34816
	ds_read_b128 v[206:209], v189 offset:35840
	ds_read_b128 v[210:213], v189 offset:36864
	ds_read_b128 v[214:217], v189 offset:37888
	ds_read_b128 v[228:231], v189 offset:38912
	ds_read_b128 v[232:235], v189 offset:39936
	global_load_lds_dwordx4 v128, s[0:1]
	s_mov_b32 m0, s62
	s_nop 0
	global_load_lds_dwordx4 v132, s[0:1]
	s_mov_b32 m0, s49
	s_nop 0
	global_load_lds_dwordx4 v[236:237], off
	s_mov_b32 m0, s60
	s_nop 0
	global_load_lds_dwordx4 v[238:239], off
	s_waitcnt vmcnt(8)
	s_waitcnt lgkmcnt(0)
	s_setprio 1
	s_barrier
	v_mfma_f32_16x16x32_bf16 v[124:127], v[142:145], v[194:197], v[124:127]
	v_mfma_f32_16x16x32_bf16 v[120:123], v[150:153], v[194:197], v[120:123]
	v_mfma_f32_16x16x32_bf16 v[108:111], v[142:145], v[202:205], v[108:111]
	v_mfma_f32_16x16x32_bf16 v[104:107], v[150:153], v[202:205], v[104:107]
	v_mfma_f32_16x16x32_bf16 v[92:95], v[142:145], v[210:213], v[92:95]
	v_mfma_f32_16x16x32_bf16 v[88:91], v[150:153], v[210:213], v[88:91]
	v_mfma_f32_16x16x32_bf16 v[76:79], v[142:145], v[228:231], v[76:79]
	v_mfma_f32_16x16x32_bf16 v[72:75], v[150:153], v[228:231], v[72:75]
	v_mfma_f32_16x16x32_bf16 v[124:127], v[146:149], v[198:201], v[124:127]
	v_mfma_f32_16x16x32_bf16 v[120:123], v[154:157], v[198:201], v[120:123]
	v_mfma_f32_16x16x32_bf16 v[108:111], v[146:149], v[206:209], v[108:111]
	v_mfma_f32_16x16x32_bf16 v[104:107], v[154:157], v[206:209], v[104:107]
	v_mfma_f32_16x16x32_bf16 v[92:95], v[146:149], v[214:217], v[92:95]
	v_mfma_f32_16x16x32_bf16 v[88:91], v[154:157], v[214:217], v[88:91]
	v_mfma_f32_16x16x32_bf16 v[76:79], v[146:149], v[232:235], v[76:79]
	v_mfma_f32_16x16x32_bf16 v[72:75], v[154:157], v[232:235], v[72:75]
	v_mfma_f32_16x16x32_bf16 v[116:119], v[158:161], v[194:197], v[116:119]
	v_mfma_f32_16x16x32_bf16 v[112:115], v[184:187], v[194:197], v[112:115]
	v_mfma_f32_16x16x32_bf16 v[100:103], v[158:161], v[202:205], v[100:103]
	v_mfma_f32_16x16x32_bf16 v[96:99], v[184:187], v[202:205], v[96:99]
	v_mfma_f32_16x16x32_bf16 v[84:87], v[158:161], v[210:213], v[84:87]
	v_mfma_f32_16x16x32_bf16 v[80:83], v[184:187], v[210:213], v[80:83]
	v_mfma_f32_16x16x32_bf16 v[68:71], v[158:161], v[228:231], v[68:71]
	v_mfma_f32_16x16x32_bf16 v[64:67], v[184:187], v[228:231], v[64:67]
	v_mfma_f32_16x16x32_bf16 v[116:119], v[162:165], v[198:201], v[116:119]
	v_mfma_f32_16x16x32_bf16 v[112:115], v[190:193], v[198:201], v[112:115]
	v_mfma_f32_16x16x32_bf16 v[100:103], v[162:165], v[206:209], v[100:103]
	v_mfma_f32_16x16x32_bf16 v[96:99], v[190:193], v[206:209], v[96:99]
	v_mfma_f32_16x16x32_bf16 v[84:87], v[162:165], v[214:217], v[84:87]
	v_mfma_f32_16x16x32_bf16 v[80:83], v[190:193], v[214:217], v[80:83]
	v_mfma_f32_16x16x32_bf16 v[68:71], v[162:165], v[232:235], v[68:71]
	v_mfma_f32_16x16x32_bf16 v[64:67], v[190:193], v[232:235], v[64:67]
	s_barrier
	s_setprio 0
	s_add_i32 s0, s12, s59
	v_lshl_add_u64 v[166:167], v[166:167], 0, s[16:17]
	s_mov_b32 m0, s0
	ds_read_b128 v[194:197], v189 offset:49152
	ds_read_b128 v[198:201], v189 offset:50176
	ds_read_b128 v[202:205], v189 offset:51200
	ds_read_b128 v[206:209], v189 offset:52224
	ds_read_b128 v[210:213], v189 offset:53248
	ds_read_b128 v[214:217], v189 offset:54272
	ds_read_b128 v[228:231], v189 offset:55296
	ds_read_b128 v[232:235], v189 offset:56320
	global_load_lds_dwordx4 v[166:167], off
	s_add_i32 m0, s0, 0x2000
	s_add_u32 s0, s54, 0x40080
	v_lshl_add_u64 v[166:167], v[218:219], 0, s[16:17]
	s_addc_u32 s1, s55, 0
	s_add_i32 s12, s13, s59
	global_load_lds_dwordx4 v[166:167], off
	s_mov_b32 m0, s12
	s_nop 0
	global_load_lds_dwordx4 v130, s[0:1]
	s_add_i32 m0, s12, 0x2000
	s_nop 0
	global_load_lds_dwordx4 v134, s[0:1]
	v_lshl_add_u64 v[166:167], v[236:237], 0, s[16:17]
	s_mov_b32 m0, s64
	s_nop 0
	global_load_lds_dwordx4 v[166:167], off
	v_lshl_add_u64 v[166:167], v[238:239], 0, s[16:17]
	s_mov_b32 m0, s65
	s_nop 0
	global_load_lds_dwordx4 v[166:167], off
	s_waitcnt vmcnt(6)
	s_waitcnt lgkmcnt(0)
	s_setprio 1
	s_barrier
	v_mfma_f32_16x16x32_bf16 v[60:63], v[142:145], v[194:197], v[60:63]
	v_mfma_f32_16x16x32_bf16 v[56:59], v[150:153], v[194:197], v[56:59]
	v_mfma_f32_16x16x32_bf16 v[44:47], v[142:145], v[202:205], v[44:47]
	v_mfma_f32_16x16x32_bf16 v[40:43], v[150:153], v[202:205], v[40:43]
	v_mfma_f32_16x16x32_bf16 v[28:31], v[142:145], v[210:213], v[28:31]
	v_mfma_f32_16x16x32_bf16 v[24:27], v[150:153], v[210:213], v[24:27]
	v_mfma_f32_16x16x32_bf16 v[12:15], v[142:145], v[228:231], v[12:15]
	v_mfma_f32_16x16x32_bf16 v[8:11], v[150:153], v[228:231], v[8:11]
	v_mfma_f32_16x16x32_bf16 v[60:63], v[146:149], v[198:201], v[60:63]
	v_mfma_f32_16x16x32_bf16 v[56:59], v[154:157], v[198:201], v[56:59]
	v_mfma_f32_16x16x32_bf16 v[44:47], v[146:149], v[206:209], v[44:47]
	v_mfma_f32_16x16x32_bf16 v[40:43], v[154:157], v[206:209], v[40:43]
	v_mfma_f32_16x16x32_bf16 v[28:31], v[146:149], v[214:217], v[28:31]
	v_mfma_f32_16x16x32_bf16 v[24:27], v[154:157], v[214:217], v[24:27]
	v_mfma_f32_16x16x32_bf16 v[12:15], v[146:149], v[232:235], v[12:15]
	v_mfma_f32_16x16x32_bf16 v[8:11], v[154:157], v[232:235], v[8:11]
	v_mfma_f32_16x16x32_bf16 v[52:55], v[158:161], v[194:197], v[52:55]
	v_mfma_f32_16x16x32_bf16 v[48:51], v[184:187], v[194:197], v[48:51]
	v_mfma_f32_16x16x32_bf16 v[36:39], v[158:161], v[202:205], v[36:39]
	v_mfma_f32_16x16x32_bf16 v[32:35], v[184:187], v[202:205], v[32:35]
	v_mfma_f32_16x16x32_bf16 v[20:23], v[158:161], v[210:213], v[20:23]
	v_mfma_f32_16x16x32_bf16 v[16:19], v[184:187], v[210:213], v[16:19]
	v_mfma_f32_16x16x32_bf16 v[4:7], v[158:161], v[228:231], v[4:7]
	v_mfma_f32_16x16x32_bf16 v[0:3], v[184:187], v[228:231], v[0:3]
	v_mfma_f32_16x16x32_bf16 v[52:55], v[162:165], v[198:201], v[52:55]
	v_mfma_f32_16x16x32_bf16 v[48:51], v[190:193], v[198:201], v[48:51]
	v_mfma_f32_16x16x32_bf16 v[36:39], v[162:165], v[206:209], v[36:39]
	v_mfma_f32_16x16x32_bf16 v[32:35], v[190:193], v[206:209], v[32:35]
	v_mfma_f32_16x16x32_bf16 v[20:23], v[162:165], v[214:217], v[20:23]
	v_mfma_f32_16x16x32_bf16 v[16:19], v[190:193], v[214:217], v[16:19]
	v_mfma_f32_16x16x32_bf16 v[4:7], v[162:165], v[232:235], v[4:7]
	v_mfma_f32_16x16x32_bf16 v[0:3], v[190:193], v[232:235], v[0:3]
	s_barrier
	s_setprio 0
	s_add_i32 s76, s76, 2
	s_add_u32 s69, s69, 0x100
	s_addc_u32 s75, s75, 0
	s_cmp_gt_u32 s76, 13
	s_mov_b64 s[50:51], s[52:53]
.LBB0_577:
	s_add_u32 s52, s50, 0x100
	s_addc_u32 s53, s51, 0
	s_add_i32 s0, 0, 0x10000
	s_cmp_eq_u32 s76, 12
	s_cselect_b32 s57, s43, s53
	s_cselect_b32 s56, s67, s52
	s_cselect_b32 s55, s41, s75
	s_cselect_b32 s54, s68, s69
	s_add_i32 s12, 0, 0x14000
	v_add_u32_e32 v154, s0, v188
	v_add_u32_e32 v166, s12, v188
	ds_read_b128 v[142:145], v154
	ds_read_b128 v[146:149], v154 offset:1024
	ds_read_b128 v[150:153], v154 offset:2048
	ds_read_b128 v[154:157], v154 offset:3072
	ds_read_b128 v[158:161], v166
	ds_read_b128 v[162:165], v166 offset:1024
	ds_read_b128 v[184:187], v166 offset:2048
	ds_read_b128 v[190:193], v166 offset:3072
	s_add_i32 m0, s49, 0xc000
	ds_read_b128 v[194:197], v189
	ds_read_b128 v[198:201], v189 offset:1024
	ds_read_b128 v[202:205], v189 offset:2048
	ds_read_b128 v[206:209], v189 offset:3072
	ds_read_b128 v[210:213], v189 offset:4096
	ds_read_b128 v[214:217], v189 offset:5120
	ds_read_b128 v[228:231], v189 offset:6144
	ds_read_b128 v[232:235], v189 offset:7168
	global_load_lds_dwordx4 v138, s[50:51]
	s_add_i32 m0, s49, 0xe000
	s_nop 0
	global_load_lds_dwordx4 v140, s[50:51]
	s_waitcnt vmcnt(8)
	s_waitcnt lgkmcnt(0)
	s_setprio 1
	s_barrier
	v_mfma_f32_16x16x32_bf16 v[124:127], v[142:145], v[194:197], v[124:127]
	v_mfma_f32_16x16x32_bf16 v[120:123], v[150:153], v[194:197], v[120:123]
	v_mfma_f32_16x16x32_bf16 v[108:111], v[142:145], v[202:205], v[108:111]
	v_mfma_f32_16x16x32_bf16 v[104:107], v[150:153], v[202:205], v[104:107]
	v_mfma_f32_16x16x32_bf16 v[92:95], v[142:145], v[210:213], v[92:95]
	v_mfma_f32_16x16x32_bf16 v[88:91], v[150:153], v[210:213], v[88:91]
	v_mfma_f32_16x16x32_bf16 v[76:79], v[142:145], v[228:231], v[76:79]
	v_mfma_f32_16x16x32_bf16 v[72:75], v[150:153], v[228:231], v[72:75]
	v_mfma_f32_16x16x32_bf16 v[124:127], v[146:149], v[198:201], v[124:127]
	v_mfma_f32_16x16x32_bf16 v[120:123], v[154:157], v[198:201], v[120:123]
	v_mfma_f32_16x16x32_bf16 v[108:111], v[146:149], v[206:209], v[108:111]
	v_mfma_f32_16x16x32_bf16 v[104:107], v[154:157], v[206:209], v[104:107]
	v_mfma_f32_16x16x32_bf16 v[92:95], v[146:149], v[214:217], v[92:95]
	v_mfma_f32_16x16x32_bf16 v[88:91], v[154:157], v[214:217], v[88:91]
	v_mfma_f32_16x16x32_bf16 v[76:79], v[146:149], v[232:235], v[76:79]
	v_mfma_f32_16x16x32_bf16 v[72:75], v[154:157], v[232:235], v[72:75]
	v_mfma_f32_16x16x32_bf16 v[116:119], v[158:161], v[194:197], v[116:119]
	v_mfma_f32_16x16x32_bf16 v[112:115], v[184:187], v[194:197], v[112:115]
	v_mfma_f32_16x16x32_bf16 v[100:103], v[158:161], v[202:205], v[100:103]
	v_mfma_f32_16x16x32_bf16 v[96:99], v[184:187], v[202:205], v[96:99]
	v_mfma_f32_16x16x32_bf16 v[84:87], v[158:161], v[210:213], v[84:87]
	v_mfma_f32_16x16x32_bf16 v[80:83], v[184:187], v[210:213], v[80:83]
	v_mfma_f32_16x16x32_bf16 v[68:71], v[158:161], v[228:231], v[68:71]
	v_mfma_f32_16x16x32_bf16 v[64:67], v[184:187], v[228:231], v[64:67]
	v_mfma_f32_16x16x32_bf16 v[116:119], v[162:165], v[198:201], v[116:119]
	v_mfma_f32_16x16x32_bf16 v[112:115], v[190:193], v[198:201], v[112:115]
	v_mfma_f32_16x16x32_bf16 v[100:103], v[162:165], v[206:209], v[100:103]
	v_mfma_f32_16x16x32_bf16 v[96:99], v[190:193], v[206:209], v[96:99]
	v_mfma_f32_16x16x32_bf16 v[84:87], v[162:165], v[214:217], v[84:87]
	v_mfma_f32_16x16x32_bf16 v[80:83], v[190:193], v[214:217], v[80:83]
	v_mfma_f32_16x16x32_bf16 v[68:71], v[162:165], v[232:235], v[68:71]
	v_mfma_f32_16x16x32_bf16 v[64:67], v[190:193], v[232:235], v[64:67]
	s_barrier
	s_setprio 0
	s_add_i32 s0, s0, s59
	v_lshl_add_u64 v[166:167], s[54:55], 0, v[130:131]
	s_mov_b32 m0, s0
	ds_read_b128 v[194:197], v189 offset:16384
	ds_read_b128 v[198:201], v189 offset:17408
	ds_read_b128 v[202:205], v189 offset:18432
	ds_read_b128 v[206:209], v189 offset:19456
	ds_read_b128 v[210:213], v189 offset:20480
	ds_read_b128 v[214:217], v189 offset:21504
	ds_read_b128 v[228:231], v189 offset:22528
	ds_read_b128 v[232:235], v189 offset:23552
	global_load_lds_dwordx4 v[166:167], off
	s_add_i32 m0, s0, 0x2000
	s_add_u32 s0, s54, 0x40000
	v_lshl_add_u64 v[218:219], s[54:55], 0, v[134:135]
	s_addc_u32 s1, s55, 0
	s_add_i32 s12, s12, s59
	global_load_lds_dwordx4 v[218:219], off
	s_mov_b32 m0, s12
	v_lshl_add_u64 v[238:239], s[56:57], 0, v[132:133]
	global_load_lds_dwordx4 v130, s[0:1]
	s_add_i32 m0, s12, 0x2000
	s_nop 0
	global_load_lds_dwordx4 v134, s[0:1]
	v_lshl_add_u64 v[236:237], s[56:57], 0, v[128:129]
	s_waitcnt vmcnt(6)
	s_waitcnt lgkmcnt(0)
	s_setprio 1
	s_barrier
	v_mfma_f32_16x16x32_bf16 v[60:63], v[142:145], v[194:197], v[60:63]
	v_mfma_f32_16x16x32_bf16 v[56:59], v[150:153], v[194:197], v[56:59]
	v_mfma_f32_16x16x32_bf16 v[44:47], v[142:145], v[202:205], v[44:47]
	v_mfma_f32_16x16x32_bf16 v[40:43], v[150:153], v[202:205], v[40:43]
	v_mfma_f32_16x16x32_bf16 v[28:31], v[142:145], v[210:213], v[28:31]
	v_mfma_f32_16x16x32_bf16 v[24:27], v[150:153], v[210:213], v[24:27]
	v_mfma_f32_16x16x32_bf16 v[12:15], v[142:145], v[228:231], v[12:15]
	v_mfma_f32_16x16x32_bf16 v[8:11], v[150:153], v[228:231], v[8:11]
	v_mfma_f32_16x16x32_bf16 v[60:63], v[146:149], v[198:201], v[60:63]
	v_mfma_f32_16x16x32_bf16 v[56:59], v[154:157], v[198:201], v[56:59]
	v_mfma_f32_16x16x32_bf16 v[44:47], v[146:149], v[206:209], v[44:47]
	v_mfma_f32_16x16x32_bf16 v[40:43], v[154:157], v[206:209], v[40:43]
	v_mfma_f32_16x16x32_bf16 v[28:31], v[146:149], v[214:217], v[28:31]
	v_mfma_f32_16x16x32_bf16 v[24:27], v[154:157], v[214:217], v[24:27]
	v_mfma_f32_16x16x32_bf16 v[12:15], v[146:149], v[232:235], v[12:15]
	v_mfma_f32_16x16x32_bf16 v[8:11], v[154:157], v[232:235], v[8:11]
	v_mfma_f32_16x16x32_bf16 v[52:55], v[158:161], v[194:197], v[52:55]
	v_mfma_f32_16x16x32_bf16 v[48:51], v[184:187], v[194:197], v[48:51]
	v_mfma_f32_16x16x32_bf16 v[36:39], v[158:161], v[202:205], v[36:39]
	v_mfma_f32_16x16x32_bf16 v[32:35], v[184:187], v[202:205], v[32:35]
	v_mfma_f32_16x16x32_bf16 v[20:23], v[158:161], v[210:213], v[20:23]
	v_mfma_f32_16x16x32_bf16 v[16:19], v[184:187], v[210:213], v[16:19]
	v_mfma_f32_16x16x32_bf16 v[4:7], v[158:161], v[228:231], v[4:7]
	v_mfma_f32_16x16x32_bf16 v[0:3], v[184:187], v[228:231], v[0:3]
	v_mfma_f32_16x16x32_bf16 v[52:55], v[162:165], v[198:201], v[52:55]
	v_mfma_f32_16x16x32_bf16 v[48:51], v[190:193], v[198:201], v[48:51]
	v_mfma_f32_16x16x32_bf16 v[36:39], v[162:165], v[206:209], v[36:39]
	v_mfma_f32_16x16x32_bf16 v[32:35], v[190:193], v[206:209], v[32:35]
	v_mfma_f32_16x16x32_bf16 v[20:23], v[162:165], v[214:217], v[20:23]
	v_mfma_f32_16x16x32_bf16 v[16:19], v[190:193], v[214:217], v[16:19]
	v_mfma_f32_16x16x32_bf16 v[4:7], v[162:165], v[232:235], v[4:7]
	v_mfma_f32_16x16x32_bf16 v[0:3], v[190:193], v[232:235], v[0:3]
	s_barrier
	s_setprio 0
	s_add_i32 s12, 0, 0x18000
	s_add_i32 s13, 0, 0x1c000
	v_add_u32_e32 v154, s12, v188
	v_add_u32_e32 v170, s13, v188
	ds_read_b128 v[142:145], v154
	ds_read_b128 v[146:149], v154 offset:1024
	ds_read_b128 v[150:153], v154 offset:2048
	ds_read_b128 v[154:157], v154 offset:3072
	ds_read_b128 v[158:161], v170
	ds_read_b128 v[162:165], v170 offset:1024
	ds_read_b128 v[184:187], v170 offset:2048
	ds_read_b128 v[190:193], v170 offset:3072
	s_add_u32 s0, s56, 0x40000
	s_addc_u32 s1, s57, 0
	s_mov_b32 m0, s61
	ds_read_b128 v[194:197], v189 offset:32768
	ds_read_b128 v[198:201], v189 offset:33792
	ds_read_b128 v[202:205], v189 offset:34816
	ds_read_b128 v[206:209], v189 offset:35840
	ds_read_b128 v[210:213], v189 offset:36864
	ds_read_b128 v[214:217], v189 offset:37888
	ds_read_b128 v[228:231], v189 offset:38912
	ds_read_b128 v[232:235], v189 offset:39936
	global_load_lds_dwordx4 v128, s[0:1]
	s_mov_b32 m0, s62
	s_nop 0
	global_load_lds_dwordx4 v132, s[0:1]
	s_mov_b32 m0, s49
	s_nop 0
	global_load_lds_dwordx4 v[236:237], off
	s_mov_b32 m0, s60
	s_nop 0
	global_load_lds_dwordx4 v[238:239], off
	s_waitcnt vmcnt(8)
	s_waitcnt lgkmcnt(0)
	s_setprio 1
	s_barrier
	v_mfma_f32_16x16x32_bf16 v[124:127], v[142:145], v[194:197], v[124:127]
	v_mfma_f32_16x16x32_bf16 v[120:123], v[150:153], v[194:197], v[120:123]
	v_mfma_f32_16x16x32_bf16 v[108:111], v[142:145], v[202:205], v[108:111]
	v_mfma_f32_16x16x32_bf16 v[104:107], v[150:153], v[202:205], v[104:107]
	v_mfma_f32_16x16x32_bf16 v[92:95], v[142:145], v[210:213], v[92:95]
	v_mfma_f32_16x16x32_bf16 v[88:91], v[150:153], v[210:213], v[88:91]
	v_mfma_f32_16x16x32_bf16 v[76:79], v[142:145], v[228:231], v[76:79]
	v_mfma_f32_16x16x32_bf16 v[72:75], v[150:153], v[228:231], v[72:75]
	v_mfma_f32_16x16x32_bf16 v[124:127], v[146:149], v[198:201], v[124:127]
	v_mfma_f32_16x16x32_bf16 v[120:123], v[154:157], v[198:201], v[120:123]
	v_mfma_f32_16x16x32_bf16 v[108:111], v[146:149], v[206:209], v[108:111]
	v_mfma_f32_16x16x32_bf16 v[104:107], v[154:157], v[206:209], v[104:107]
	v_mfma_f32_16x16x32_bf16 v[92:95], v[146:149], v[214:217], v[92:95]
	v_mfma_f32_16x16x32_bf16 v[88:91], v[154:157], v[214:217], v[88:91]
	v_mfma_f32_16x16x32_bf16 v[76:79], v[146:149], v[232:235], v[76:79]
	v_mfma_f32_16x16x32_bf16 v[72:75], v[154:157], v[232:235], v[72:75]
	v_mfma_f32_16x16x32_bf16 v[116:119], v[158:161], v[194:197], v[116:119]
	v_mfma_f32_16x16x32_bf16 v[112:115], v[184:187], v[194:197], v[112:115]
	v_mfma_f32_16x16x32_bf16 v[100:103], v[158:161], v[202:205], v[100:103]
	v_mfma_f32_16x16x32_bf16 v[96:99], v[184:187], v[202:205], v[96:99]
	v_mfma_f32_16x16x32_bf16 v[84:87], v[158:161], v[210:213], v[84:87]
	v_mfma_f32_16x16x32_bf16 v[80:83], v[184:187], v[210:213], v[80:83]
	v_mfma_f32_16x16x32_bf16 v[68:71], v[158:161], v[228:231], v[68:71]
	v_mfma_f32_16x16x32_bf16 v[64:67], v[184:187], v[228:231], v[64:67]
	v_mfma_f32_16x16x32_bf16 v[116:119], v[162:165], v[198:201], v[116:119]
	v_mfma_f32_16x16x32_bf16 v[112:115], v[190:193], v[198:201], v[112:115]
	v_mfma_f32_16x16x32_bf16 v[100:103], v[162:165], v[206:209], v[100:103]
	v_mfma_f32_16x16x32_bf16 v[96:99], v[190:193], v[206:209], v[96:99]
	v_mfma_f32_16x16x32_bf16 v[84:87], v[162:165], v[214:217], v[84:87]
	v_mfma_f32_16x16x32_bf16 v[80:83], v[190:193], v[214:217], v[80:83]
	v_mfma_f32_16x16x32_bf16 v[68:71], v[162:165], v[232:235], v[68:71]
	v_mfma_f32_16x16x32_bf16 v[64:67], v[190:193], v[232:235], v[64:67]
	s_barrier
	s_setprio 0
	s_add_i32 s0, s12, s59
	v_lshl_add_u64 v[166:167], v[166:167], 0, s[16:17]
	s_mov_b32 m0, s0
	ds_read_b128 v[194:197], v189 offset:49152
	ds_read_b128 v[198:201], v189 offset:50176
	ds_read_b128 v[202:205], v189 offset:51200
	ds_read_b128 v[206:209], v189 offset:52224
	ds_read_b128 v[210:213], v189 offset:53248
	ds_read_b128 v[214:217], v189 offset:54272
	ds_read_b128 v[228:231], v189 offset:55296
	ds_read_b128 v[232:235], v189 offset:56320
	global_load_lds_dwordx4 v[166:167], off
	s_add_i32 m0, s0, 0x2000
	s_add_u32 s0, s54, 0x40080
	v_lshl_add_u64 v[166:167], v[218:219], 0, s[16:17]
	s_addc_u32 s1, s55, 0
	s_add_i32 s12, s13, s59
	global_load_lds_dwordx4 v[166:167], off
	s_mov_b32 m0, s12
	s_nop 0
	global_load_lds_dwordx4 v130, s[0:1]
	s_add_i32 m0, s12, 0x2000
	s_nop 0
	global_load_lds_dwordx4 v134, s[0:1]
	v_lshl_add_u64 v[166:167], v[236:237], 0, s[16:17]
	s_mov_b32 m0, s64
	s_nop 0
	global_load_lds_dwordx4 v[166:167], off
	v_lshl_add_u64 v[166:167], v[238:239], 0, s[16:17]
	s_mov_b32 m0, s65
	s_nop 0
	global_load_lds_dwordx4 v[166:167], off
	s_waitcnt vmcnt(6)
	s_waitcnt lgkmcnt(0)
	s_setprio 1
	s_barrier
	v_mfma_f32_16x16x32_bf16 v[60:63], v[142:145], v[194:197], v[60:63]
	v_mfma_f32_16x16x32_bf16 v[56:59], v[150:153], v[194:197], v[56:59]
	v_mfma_f32_16x16x32_bf16 v[44:47], v[142:145], v[202:205], v[44:47]
	v_mfma_f32_16x16x32_bf16 v[40:43], v[150:153], v[202:205], v[40:43]
	v_mfma_f32_16x16x32_bf16 v[28:31], v[142:145], v[210:213], v[28:31]
	v_mfma_f32_16x16x32_bf16 v[24:27], v[150:153], v[210:213], v[24:27]
	v_mfma_f32_16x16x32_bf16 v[12:15], v[142:145], v[228:231], v[12:15]
	v_mfma_f32_16x16x32_bf16 v[8:11], v[150:153], v[228:231], v[8:11]
	v_mfma_f32_16x16x32_bf16 v[60:63], v[146:149], v[198:201], v[60:63]
	v_mfma_f32_16x16x32_bf16 v[56:59], v[154:157], v[198:201], v[56:59]
	v_mfma_f32_16x16x32_bf16 v[44:47], v[146:149], v[206:209], v[44:47]
	v_mfma_f32_16x16x32_bf16 v[40:43], v[154:157], v[206:209], v[40:43]
	v_mfma_f32_16x16x32_bf16 v[28:31], v[146:149], v[214:217], v[28:31]
	v_mfma_f32_16x16x32_bf16 v[24:27], v[154:157], v[214:217], v[24:27]
	v_mfma_f32_16x16x32_bf16 v[12:15], v[146:149], v[232:235], v[12:15]
	v_mfma_f32_16x16x32_bf16 v[8:11], v[154:157], v[232:235], v[8:11]
	v_mfma_f32_16x16x32_bf16 v[52:55], v[158:161], v[194:197], v[52:55]
	v_mfma_f32_16x16x32_bf16 v[48:51], v[184:187], v[194:197], v[48:51]
	v_mfma_f32_16x16x32_bf16 v[36:39], v[158:161], v[202:205], v[36:39]
	v_mfma_f32_16x16x32_bf16 v[32:35], v[184:187], v[202:205], v[32:35]
	v_mfma_f32_16x16x32_bf16 v[20:23], v[158:161], v[210:213], v[20:23]
	v_mfma_f32_16x16x32_bf16 v[16:19], v[184:187], v[210:213], v[16:19]
	v_mfma_f32_16x16x32_bf16 v[4:7], v[158:161], v[228:231], v[4:7]
	v_mfma_f32_16x16x32_bf16 v[0:3], v[184:187], v[228:231], v[0:3]
	v_mfma_f32_16x16x32_bf16 v[52:55], v[162:165], v[198:201], v[52:55]
	v_mfma_f32_16x16x32_bf16 v[48:51], v[190:193], v[198:201], v[48:51]
	v_mfma_f32_16x16x32_bf16 v[36:39], v[162:165], v[206:209], v[36:39]
	v_mfma_f32_16x16x32_bf16 v[32:35], v[190:193], v[206:209], v[32:35]
	v_mfma_f32_16x16x32_bf16 v[20:23], v[162:165], v[214:217], v[20:23]
	v_mfma_f32_16x16x32_bf16 v[16:19], v[190:193], v[214:217], v[16:19]
	v_mfma_f32_16x16x32_bf16 v[4:7], v[162:165], v[232:235], v[4:7]
	v_mfma_f32_16x16x32_bf16 v[0:3], v[190:193], v[232:235], v[0:3]
	s_barrier
	s_setprio 0
	s_add_i32 s76, s76, 2
	s_add_u32 s69, s69, 0x100
	s_addc_u32 s75, s75, 0
	s_cmp_gt_u32 s76, 13
	s_mov_b64 s[50:51], s[52:53]
	s_cbranch_scc0 .LBB0_577
	s_and_b64 vcc, exec, s[36:37]
	s_cbranch_vccz .LBB0_580
	s_barrier

.Lrestag_601:
	s_add_u32 s48, s46, 0x100
	s_addc_u32 s49, s47, 0
	s_add_i32 s0, 0, 0x10000
	s_cmp_eq_u32 s66, 12
	s_cselect_b32 s53, s37, s49
	s_cselect_b32 s52, s62, s48
	v_add_u32_e32 v146, s0, v149
	s_cselect_b32 s51, s35, s65
	s_cselect_b32 s50, s63, s64
	s_add_i32 s12, 0, 0x14000
	ds_read_b128 v[128:131], v146
	ds_read_b128 v[132:135], v146 offset:1024
	ds_read_b128 v[152:155], v146 offset:2048
	ds_read_b128 v[156:159], v146 offset:3072
	v_add_u32_e32 v146, s12, v149
	ds_read_b128 v[160:163], v146
	ds_read_b128 v[164:167], v146 offset:1024
	ds_read_b128 v[184:187], v146 offset:2048
	ds_read_b128 v[188:191], v146 offset:3072
	s_add_i32 m0, s45, 0xc000
	ds_read_b128 v[192:195], v151
	ds_read_b128 v[196:199], v151 offset:1024
	ds_read_b128 v[200:203], v151 offset:2048
	ds_read_b128 v[204:207], v151 offset:3072
	ds_read_b128 v[208:211], v151 offset:4096
	ds_read_b128 v[212:215], v151 offset:5120
	ds_read_b128 v[216:219], v151 offset:6144
	ds_read_b128 v[228:231], v151 offset:7168
	global_load_lds_dwordx4 v142, s[46:47]
	s_add_i32 m0, s45, 0xe000
	s_nop 0
	global_load_lds_dwordx4 v144, s[46:47]
	s_nop 0
	s_waitcnt lgkmcnt(0)
	s_setprio 1
	s_barrier
	v_mfma_f32_16x16x32_bf16 v[124:127], v[128:131], v[192:195], 0
	v_mfma_f32_16x16x32_bf16 v[120:123], v[152:155], v[192:195], 0
	v_mfma_f32_16x16x32_bf16 v[116:119], v[128:131], v[200:203], 0
	v_mfma_f32_16x16x32_bf16 v[112:115], v[152:155], v[200:203], 0
	v_mfma_f32_16x16x32_bf16 v[108:111], v[128:131], v[208:211], 0
	v_mfma_f32_16x16x32_bf16 v[104:107], v[152:155], v[208:211], 0
	v_mfma_f32_16x16x32_bf16 v[100:103], v[128:131], v[216:219], 0
	v_mfma_f32_16x16x32_bf16 v[96:99], v[152:155], v[216:219], 0
	v_mfma_f32_16x16x32_bf16 v[124:127], v[132:135], v[196:199], v[124:127]
	v_mfma_f32_16x16x32_bf16 v[120:123], v[156:159], v[196:199], v[120:123]
	v_mfma_f32_16x16x32_bf16 v[116:119], v[132:135], v[204:207], v[116:119]
	v_mfma_f32_16x16x32_bf16 v[112:115], v[156:159], v[204:207], v[112:115]
	v_mfma_f32_16x16x32_bf16 v[108:111], v[132:135], v[212:215], v[108:111]
	v_mfma_f32_16x16x32_bf16 v[104:107], v[156:159], v[212:215], v[104:107]
	v_mfma_f32_16x16x32_bf16 v[100:103], v[132:135], v[228:231], v[100:103]
	v_mfma_f32_16x16x32_bf16 v[96:99], v[156:159], v[228:231], v[96:99]
	v_mfma_f32_16x16x32_bf16 v[68:71], v[160:163], v[192:195], 0
	v_mfma_f32_16x16x32_bf16 v[60:63], v[184:187], v[192:195], 0
	v_mfma_f32_16x16x32_bf16 v[52:55], v[160:163], v[200:203], 0
	v_mfma_f32_16x16x32_bf16 v[48:51], v[184:187], v[200:203], 0
	v_mfma_f32_16x16x32_bf16 v[44:47], v[160:163], v[208:211], 0
	v_mfma_f32_16x16x32_bf16 v[40:43], v[184:187], v[208:211], 0
	v_mfma_f32_16x16x32_bf16 v[36:39], v[160:163], v[216:219], 0
	v_mfma_f32_16x16x32_bf16 v[32:35], v[184:187], v[216:219], 0
	v_mfma_f32_16x16x32_bf16 v[68:71], v[164:167], v[196:199], v[68:71]
	v_mfma_f32_16x16x32_bf16 v[60:63], v[188:191], v[196:199], v[60:63]
	v_mfma_f32_16x16x32_bf16 v[52:55], v[164:167], v[204:207], v[52:55]
	v_mfma_f32_16x16x32_bf16 v[48:51], v[188:191], v[204:207], v[48:51]
	v_mfma_f32_16x16x32_bf16 v[44:47], v[164:167], v[212:215], v[44:47]
	v_mfma_f32_16x16x32_bf16 v[40:43], v[188:191], v[212:215], v[40:43]
	v_mfma_f32_16x16x32_bf16 v[36:39], v[164:167], v[228:231], v[36:39]
	v_mfma_f32_16x16x32_bf16 v[32:35], v[188:191], v[228:231], v[32:35]
	s_barrier
	s_setprio 0
	s_add_i32 s0, s0, s55
	v_lshl_add_u64 v[146:147], s[50:51], 0, v[170:171]
	s_mov_b32 m0, s0
	ds_read_b128 v[192:195], v151 offset:16384
	ds_read_b128 v[196:199], v151 offset:17408
	ds_read_b128 v[200:203], v151 offset:18432
	ds_read_b128 v[204:207], v151 offset:19456
	ds_read_b128 v[208:211], v151 offset:20480
	ds_read_b128 v[212:215], v151 offset:21504
	ds_read_b128 v[216:219], v151 offset:22528
	ds_read_b128 v[228:231], v151 offset:23552
	global_load_lds_dwordx4 v[146:147], off
	s_add_i32 m0, s0, 0x2000
	s_add_u32 s0, s50, 0x40000
	v_lshl_add_u64 v[232:233], s[50:51], 0, v[140:141]
	s_addc_u32 s1, s51, 0
	s_add_i32 s12, s12, s55
	global_load_lds_dwordx4 v[232:233], off
	s_mov_b32 m0, s12
	v_lshl_add_u64 v[236:237], s[52:53], 0, v[138:139]
	global_load_lds_dwordx4 v170, s[0:1]
	s_add_i32 m0, s12, 0x2000
	s_nop 0
	global_load_lds_dwordx4 v140, s[0:1]
	v_lshl_add_u64 v[234:235], s[52:53], 0, v[136:137]
	s_nop 0
	s_waitcnt lgkmcnt(0)
	s_setprio 1
	s_barrier
	v_mfma_f32_16x16x32_bf16 v[92:95], v[128:131], v[192:195], 0
	v_mfma_f32_16x16x32_bf16 v[88:91], v[152:155], v[192:195], 0
	v_mfma_f32_16x16x32_bf16 v[84:87], v[128:131], v[200:203], 0
	v_mfma_f32_16x16x32_bf16 v[80:83], v[152:155], v[200:203], 0
	v_mfma_f32_16x16x32_bf16 v[76:79], v[128:131], v[208:211], 0
	v_mfma_f32_16x16x32_bf16 v[72:75], v[152:155], v[208:211], 0
	v_mfma_f32_16x16x32_bf16 v[64:67], v[128:131], v[216:219], 0
	v_mfma_f32_16x16x32_bf16 v[56:59], v[152:155], v[216:219], 0
	v_mfma_f32_16x16x32_bf16 v[92:95], v[132:135], v[196:199], v[92:95]
	v_mfma_f32_16x16x32_bf16 v[88:91], v[156:159], v[196:199], v[88:91]
	v_mfma_f32_16x16x32_bf16 v[84:87], v[132:135], v[204:207], v[84:87]
	v_mfma_f32_16x16x32_bf16 v[80:83], v[156:159], v[204:207], v[80:83]
	v_mfma_f32_16x16x32_bf16 v[76:79], v[132:135], v[212:215], v[76:79]
	v_mfma_f32_16x16x32_bf16 v[72:75], v[156:159], v[212:215], v[72:75]
	v_mfma_f32_16x16x32_bf16 v[64:67], v[132:135], v[228:231], v[64:67]
	v_mfma_f32_16x16x32_bf16 v[56:59], v[156:159], v[228:231], v[56:59]
	v_mfma_f32_16x16x32_bf16 v[28:31], v[160:163], v[192:195], 0
	v_mfma_f32_16x16x32_bf16 v[24:27], v[184:187], v[192:195], 0
	v_mfma_f32_16x16x32_bf16 v[20:23], v[160:163], v[200:203], 0
	v_mfma_f32_16x16x32_bf16 v[16:19], v[184:187], v[200:203], 0
	v_mfma_f32_16x16x32_bf16 v[12:15], v[160:163], v[208:211], 0
	v_mfma_f32_16x16x32_bf16 v[8:11], v[184:187], v[208:211], 0
	v_mfma_f32_16x16x32_bf16 v[4:7], v[160:163], v[216:219], 0
	v_mfma_f32_16x16x32_bf16 v[0:3], v[184:187], v[216:219], 0
	v_mfma_f32_16x16x32_bf16 v[28:31], v[164:167], v[196:199], v[28:31]
	v_mfma_f32_16x16x32_bf16 v[24:27], v[188:191], v[196:199], v[24:27]
	v_mfma_f32_16x16x32_bf16 v[20:23], v[164:167], v[204:207], v[20:23]
	v_mfma_f32_16x16x32_bf16 v[16:19], v[188:191], v[204:207], v[16:19]
	v_mfma_f32_16x16x32_bf16 v[12:15], v[164:167], v[212:215], v[12:15]
	v_mfma_f32_16x16x32_bf16 v[8:11], v[188:191], v[212:215], v[8:11]
	v_mfma_f32_16x16x32_bf16 v[4:7], v[164:167], v[228:231], v[4:7]
	v_mfma_f32_16x16x32_bf16 v[0:3], v[188:191], v[228:231], v[0:3]
	s_barrier
	s_setprio 0
	s_add_i32 s12, 0, 0x18000
	s_add_i32 s13, 0, 0x1c000
	v_add_u32_e32 v156, s12, v149
	v_add_u32_e32 v188, s13, v149
	ds_read_b128 v[128:131], v156
	ds_read_b128 v[132:135], v156 offset:1024
	ds_read_b128 v[152:155], v156 offset:2048
	ds_read_b128 v[156:159], v156 offset:3072
	ds_read_b128 v[160:163], v188
	ds_read_b128 v[164:167], v188 offset:1024
	ds_read_b128 v[184:187], v188 offset:2048
	ds_read_b128 v[188:191], v188 offset:3072
	s_add_u32 s0, s52, 0x40000
	s_addc_u32 s1, s53, 0
	s_mov_b32 m0, s57
	ds_read_b128 v[192:195], v151 offset:32768
	ds_read_b128 v[196:199], v151 offset:33792
	ds_read_b128 v[200:203], v151 offset:34816
	ds_read_b128 v[204:207], v151 offset:35840
	ds_read_b128 v[208:211], v151 offset:36864
	ds_read_b128 v[212:215], v151 offset:37888
	ds_read_b128 v[216:219], v151 offset:38912
	ds_read_b128 v[228:231], v151 offset:39936
	global_load_lds_dwordx4 v136, s[0:1]
	s_mov_b32 m0, s58
	s_nop 0
	global_load_lds_dwordx4 v138, s[0:1]
	s_mov_b32 m0, s45
	s_nop 0
	global_load_lds_dwordx4 v[234:235], off
	s_mov_b32 m0, s56
	s_nop 0
	global_load_lds_dwordx4 v[236:237], off
	s_waitcnt vmcnt(8)
	s_waitcnt lgkmcnt(0)
	s_setprio 1
	s_barrier
	v_mfma_f32_16x16x32_bf16 v[124:127], v[128:131], v[192:195], v[124:127]
	v_mfma_f32_16x16x32_bf16 v[120:123], v[152:155], v[192:195], v[120:123]
	v_mfma_f32_16x16x32_bf16 v[116:119], v[128:131], v[200:203], v[116:119]
	v_mfma_f32_16x16x32_bf16 v[112:115], v[152:155], v[200:203], v[112:115]
	v_mfma_f32_16x16x32_bf16 v[108:111], v[128:131], v[208:211], v[108:111]
	v_mfma_f32_16x16x32_bf16 v[104:107], v[152:155], v[208:211], v[104:107]
	v_mfma_f32_16x16x32_bf16 v[100:103], v[128:131], v[216:219], v[100:103]
	v_mfma_f32_16x16x32_bf16 v[96:99], v[152:155], v[216:219], v[96:99]
	v_mfma_f32_16x16x32_bf16 v[124:127], v[132:135], v[196:199], v[124:127]
	v_mfma_f32_16x16x32_bf16 v[120:123], v[156:159], v[196:199], v[120:123]
	v_mfma_f32_16x16x32_bf16 v[116:119], v[132:135], v[204:207], v[116:119]
	v_mfma_f32_16x16x32_bf16 v[112:115], v[156:159], v[204:207], v[112:115]
	v_mfma_f32_16x16x32_bf16 v[108:111], v[132:135], v[212:215], v[108:111]
	v_mfma_f32_16x16x32_bf16 v[104:107], v[156:159], v[212:215], v[104:107]
	v_mfma_f32_16x16x32_bf16 v[100:103], v[132:135], v[228:231], v[100:103]
	v_mfma_f32_16x16x32_bf16 v[96:99], v[156:159], v[228:231], v[96:99]
	v_mfma_f32_16x16x32_bf16 v[68:71], v[160:163], v[192:195], v[68:71]
	v_mfma_f32_16x16x32_bf16 v[60:63], v[184:187], v[192:195], v[60:63]
	v_mfma_f32_16x16x32_bf16 v[52:55], v[160:163], v[200:203], v[52:55]
	v_mfma_f32_16x16x32_bf16 v[48:51], v[184:187], v[200:203], v[48:51]
	v_mfma_f32_16x16x32_bf16 v[44:47], v[160:163], v[208:211], v[44:47]
	v_mfma_f32_16x16x32_bf16 v[40:43], v[184:187], v[208:211], v[40:43]
	v_mfma_f32_16x16x32_bf16 v[36:39], v[160:163], v[216:219], v[36:39]
	v_mfma_f32_16x16x32_bf16 v[32:35], v[184:187], v[216:219], v[32:35]
	v_mfma_f32_16x16x32_bf16 v[68:71], v[164:167], v[196:199], v[68:71]
	v_mfma_f32_16x16x32_bf16 v[60:63], v[188:191], v[196:199], v[60:63]
	v_mfma_f32_16x16x32_bf16 v[52:55], v[164:167], v[204:207], v[52:55]
	v_mfma_f32_16x16x32_bf16 v[48:51], v[188:191], v[204:207], v[48:51]
	v_mfma_f32_16x16x32_bf16 v[44:47], v[164:167], v[212:215], v[44:47]
	v_mfma_f32_16x16x32_bf16 v[40:43], v[188:191], v[212:215], v[40:43]
	v_mfma_f32_16x16x32_bf16 v[36:39], v[164:167], v[228:231], v[36:39]
	v_mfma_f32_16x16x32_bf16 v[32:35], v[188:191], v[228:231], v[32:35]
	s_barrier
	s_setprio 0
	s_add_i32 s0, s12, s55
	v_lshl_add_u64 v[146:147], v[146:147], 0, s[16:17]
	s_mov_b32 m0, s0
	ds_read_b128 v[192:195], v151 offset:49152
	ds_read_b128 v[196:199], v151 offset:50176
	ds_read_b128 v[200:203], v151 offset:51200
	ds_read_b128 v[204:207], v151 offset:52224
	ds_read_b128 v[208:211], v151 offset:53248
	ds_read_b128 v[212:215], v151 offset:54272
	ds_read_b128 v[216:219], v151 offset:55296
	ds_read_b128 v[228:231], v151 offset:56320
	global_load_lds_dwordx4 v[146:147], off
	s_add_i32 m0, s0, 0x2000
	s_add_u32 s0, s50, 0x40080
	v_lshl_add_u64 v[146:147], v[232:233], 0, s[16:17]
	s_addc_u32 s1, s51, 0
	s_add_i32 s12, s13, s55
	global_load_lds_dwordx4 v[146:147], off
	s_mov_b32 m0, s12
	s_nop 0
	global_load_lds_dwordx4 v170, s[0:1]
	s_add_i32 m0, s12, 0x2000
	s_nop 0
	global_load_lds_dwordx4 v140, s[0:1]
	v_lshl_add_u64 v[146:147], v[234:235], 0, s[16:17]
	s_mov_b32 m0, s59
	s_nop 0
	global_load_lds_dwordx4 v[146:147], off
	v_lshl_add_u64 v[146:147], v[236:237], 0, s[16:17]
	s_mov_b32 m0, s60
	s_nop 0
	global_load_lds_dwordx4 v[146:147], off
	s_waitcnt vmcnt(6)
	s_waitcnt lgkmcnt(0)
	s_setprio 1
	s_barrier
	v_mfma_f32_16x16x32_bf16 v[92:95], v[128:131], v[192:195], v[92:95]
	v_mfma_f32_16x16x32_bf16 v[88:91], v[152:155], v[192:195], v[88:91]
	v_mfma_f32_16x16x32_bf16 v[84:87], v[128:131], v[200:203], v[84:87]
	v_mfma_f32_16x16x32_bf16 v[80:83], v[152:155], v[200:203], v[80:83]
	v_mfma_f32_16x16x32_bf16 v[76:79], v[128:131], v[208:211], v[76:79]
	v_mfma_f32_16x16x32_bf16 v[72:75], v[152:155], v[208:211], v[72:75]
	v_mfma_f32_16x16x32_bf16 v[64:67], v[128:131], v[216:219], v[64:67]
	v_mfma_f32_16x16x32_bf16 v[56:59], v[152:155], v[216:219], v[56:59]
	v_mfma_f32_16x16x32_bf16 v[92:95], v[132:135], v[196:199], v[92:95]
	v_mfma_f32_16x16x32_bf16 v[88:91], v[156:159], v[196:199], v[88:91]
	v_mfma_f32_16x16x32_bf16 v[84:87], v[132:135], v[204:207], v[84:87]
	v_mfma_f32_16x16x32_bf16 v[80:83], v[156:159], v[204:207], v[80:83]
	v_mfma_f32_16x16x32_bf16 v[76:79], v[132:135], v[212:215], v[76:79]
	v_mfma_f32_16x16x32_bf16 v[72:75], v[156:159], v[212:215], v[72:75]
	v_mfma_f32_16x16x32_bf16 v[64:67], v[132:135], v[228:231], v[64:67]
	v_mfma_f32_16x16x32_bf16 v[56:59], v[156:159], v[228:231], v[56:59]
	v_mfma_f32_16x16x32_bf16 v[28:31], v[160:163], v[192:195], v[28:31]
	v_mfma_f32_16x16x32_bf16 v[24:27], v[184:187], v[192:195], v[24:27]
	v_mfma_f32_16x16x32_bf16 v[20:23], v[160:163], v[200:203], v[20:23]
	v_mfma_f32_16x16x32_bf16 v[16:19], v[184:187], v[200:203], v[16:19]
	v_mfma_f32_16x16x32_bf16 v[12:15], v[160:163], v[208:211], v[12:15]
	v_mfma_f32_16x16x32_bf16 v[8:11], v[184:187], v[208:211], v[8:11]
	v_mfma_f32_16x16x32_bf16 v[4:7], v[160:163], v[216:219], v[4:7]
	v_mfma_f32_16x16x32_bf16 v[0:3], v[184:187], v[216:219], v[0:3]
	v_mfma_f32_16x16x32_bf16 v[28:31], v[164:167], v[196:199], v[28:31]
	v_mfma_f32_16x16x32_bf16 v[24:27], v[188:191], v[196:199], v[24:27]
	v_mfma_f32_16x16x32_bf16 v[20:23], v[164:167], v[204:207], v[20:23]
	v_mfma_f32_16x16x32_bf16 v[16:19], v[188:191], v[204:207], v[16:19]
	v_mfma_f32_16x16x32_bf16 v[12:15], v[164:167], v[212:215], v[12:15]
	v_mfma_f32_16x16x32_bf16 v[8:11], v[188:191], v[212:215], v[8:11]
	v_mfma_f32_16x16x32_bf16 v[4:7], v[164:167], v[228:231], v[4:7]
	v_mfma_f32_16x16x32_bf16 v[0:3], v[188:191], v[228:231], v[0:3]
	s_barrier
	s_setprio 0
	s_add_i32 s66, s66, 2
	s_add_u32 s64, s64, 0x100
	s_addc_u32 s65, s65, 0
	s_cmp_gt_u32 s66, 13
	s_mov_b64 s[46:47], s[48:49]
.LBB0_601:
	s_add_u32 s48, s46, 0x100
	s_addc_u32 s49, s47, 0
	s_add_i32 s0, 0, 0x10000
	s_cmp_eq_u32 s66, 12
	s_cselect_b32 s53, s37, s49
	s_cselect_b32 s52, s62, s48
	v_add_u32_e32 v146, s0, v149
	s_cselect_b32 s51, s35, s65
	s_cselect_b32 s50, s63, s64
	s_add_i32 s12, 0, 0x14000
	ds_read_b128 v[128:131], v146
	ds_read_b128 v[132:135], v146 offset:1024
	ds_read_b128 v[152:155], v146 offset:2048
	ds_read_b128 v[156:159], v146 offset:3072
	v_add_u32_e32 v146, s12, v149
	ds_read_b128 v[160:163], v146
	ds_read_b128 v[164:167], v146 offset:1024
	ds_read_b128 v[184:187], v146 offset:2048
	ds_read_b128 v[188:191], v146 offset:3072
	s_add_i32 m0, s45, 0xc000
	ds_read_b128 v[192:195], v151
	ds_read_b128 v[196:199], v151 offset:1024
	ds_read_b128 v[200:203], v151 offset:2048
	ds_read_b128 v[204:207], v151 offset:3072
	ds_read_b128 v[208:211], v151 offset:4096
	ds_read_b128 v[212:215], v151 offset:5120
	ds_read_b128 v[216:219], v151 offset:6144
	ds_read_b128 v[228:231], v151 offset:7168
	global_load_lds_dwordx4 v142, s[46:47]
	s_add_i32 m0, s45, 0xe000
	s_nop 0
	global_load_lds_dwordx4 v144, s[46:47]
	s_waitcnt vmcnt(8)
	s_waitcnt lgkmcnt(0)
	s_setprio 1
	s_barrier
	v_mfma_f32_16x16x32_bf16 v[124:127], v[128:131], v[192:195], v[124:127]
	v_mfma_f32_16x16x32_bf16 v[120:123], v[152:155], v[192:195], v[120:123]
	v_mfma_f32_16x16x32_bf16 v[116:119], v[128:131], v[200:203], v[116:119]
	v_mfma_f32_16x16x32_bf16 v[112:115], v[152:155], v[200:203], v[112:115]
	v_mfma_f32_16x16x32_bf16 v[108:111], v[128:131], v[208:211], v[108:111]
	v_mfma_f32_16x16x32_bf16 v[104:107], v[152:155], v[208:211], v[104:107]
	v_mfma_f32_16x16x32_bf16 v[100:103], v[128:131], v[216:219], v[100:103]
	v_mfma_f32_16x16x32_bf16 v[96:99], v[152:155], v[216:219], v[96:99]
	v_mfma_f32_16x16x32_bf16 v[124:127], v[132:135], v[196:199], v[124:127]
	v_mfma_f32_16x16x32_bf16 v[120:123], v[156:159], v[196:199], v[120:123]
	v_mfma_f32_16x16x32_bf16 v[116:119], v[132:135], v[204:207], v[116:119]
	v_mfma_f32_16x16x32_bf16 v[112:115], v[156:159], v[204:207], v[112:115]
	v_mfma_f32_16x16x32_bf16 v[108:111], v[132:135], v[212:215], v[108:111]
	v_mfma_f32_16x16x32_bf16 v[104:107], v[156:159], v[212:215], v[104:107]
	v_mfma_f32_16x16x32_bf16 v[100:103], v[132:135], v[228:231], v[100:103]
	v_mfma_f32_16x16x32_bf16 v[96:99], v[156:159], v[228:231], v[96:99]
	v_mfma_f32_16x16x32_bf16 v[68:71], v[160:163], v[192:195], v[68:71]
	v_mfma_f32_16x16x32_bf16 v[60:63], v[184:187], v[192:195], v[60:63]
	v_mfma_f32_16x16x32_bf16 v[52:55], v[160:163], v[200:203], v[52:55]
	v_mfma_f32_16x16x32_bf16 v[48:51], v[184:187], v[200:203], v[48:51]
	v_mfma_f32_16x16x32_bf16 v[44:47], v[160:163], v[208:211], v[44:47]
	v_mfma_f32_16x16x32_bf16 v[40:43], v[184:187], v[208:211], v[40:43]
	v_mfma_f32_16x16x32_bf16 v[36:39], v[160:163], v[216:219], v[36:39]
	v_mfma_f32_16x16x32_bf16 v[32:35], v[184:187], v[216:219], v[32:35]
	v_mfma_f32_16x16x32_bf16 v[68:71], v[164:167], v[196:199], v[68:71]
	v_mfma_f32_16x16x32_bf16 v[60:63], v[188:191], v[196:199], v[60:63]
	v_mfma_f32_16x16x32_bf16 v[52:55], v[164:167], v[204:207], v[52:55]
	v_mfma_f32_16x16x32_bf16 v[48:51], v[188:191], v[204:207], v[48:51]
	v_mfma_f32_16x16x32_bf16 v[44:47], v[164:167], v[212:215], v[44:47]
	v_mfma_f32_16x16x32_bf16 v[40:43], v[188:191], v[212:215], v[40:43]
	v_mfma_f32_16x16x32_bf16 v[36:39], v[164:167], v[228:231], v[36:39]
	v_mfma_f32_16x16x32_bf16 v[32:35], v[188:191], v[228:231], v[32:35]
	s_barrier
	s_setprio 0
	s_add_i32 s0, s0, s55
	v_lshl_add_u64 v[146:147], s[50:51], 0, v[170:171]
	s_mov_b32 m0, s0
	ds_read_b128 v[192:195], v151 offset:16384
	ds_read_b128 v[196:199], v151 offset:17408
	ds_read_b128 v[200:203], v151 offset:18432
	ds_read_b128 v[204:207], v151 offset:19456
	ds_read_b128 v[208:211], v151 offset:20480
	ds_read_b128 v[212:215], v151 offset:21504
	ds_read_b128 v[216:219], v151 offset:22528
	ds_read_b128 v[228:231], v151 offset:23552
	global_load_lds_dwordx4 v[146:147], off
	s_add_i32 m0, s0, 0x2000
	s_add_u32 s0, s50, 0x40000
	v_lshl_add_u64 v[232:233], s[50:51], 0, v[140:141]
	s_addc_u32 s1, s51, 0
	s_add_i32 s12, s12, s55
	global_load_lds_dwordx4 v[232:233], off
	s_mov_b32 m0, s12
	v_lshl_add_u64 v[236:237], s[52:53], 0, v[138:139]
	global_load_lds_dwordx4 v170, s[0:1]
	s_add_i32 m0, s12, 0x2000
	s_nop 0
	global_load_lds_dwordx4 v140, s[0:1]
	v_lshl_add_u64 v[234:235], s[52:53], 0, v[136:137]
	s_waitcnt vmcnt(6)
	s_waitcnt lgkmcnt(0)
	s_setprio 1
	s_barrier
	v_mfma_f32_16x16x32_bf16 v[92:95], v[128:131], v[192:195], v[92:95]
	v_mfma_f32_16x16x32_bf16 v[88:91], v[152:155], v[192:195], v[88:91]
	v_mfma_f32_16x16x32_bf16 v[84:87], v[128:131], v[200:203], v[84:87]
	v_mfma_f32_16x16x32_bf16 v[80:83], v[152:155], v[200:203], v[80:83]
	v_mfma_f32_16x16x32_bf16 v[76:79], v[128:131], v[208:211], v[76:79]
	v_mfma_f32_16x16x32_bf16 v[72:75], v[152:155], v[208:211], v[72:75]
	v_mfma_f32_16x16x32_bf16 v[64:67], v[128:131], v[216:219], v[64:67]
	v_mfma_f32_16x16x32_bf16 v[56:59], v[152:155], v[216:219], v[56:59]
	v_mfma_f32_16x16x32_bf16 v[92:95], v[132:135], v[196:199], v[92:95]
	v_mfma_f32_16x16x32_bf16 v[88:91], v[156:159], v[196:199], v[88:91]
	v_mfma_f32_16x16x32_bf16 v[84:87], v[132:135], v[204:207], v[84:87]
	v_mfma_f32_16x16x32_bf16 v[80:83], v[156:159], v[204:207], v[80:83]
	v_mfma_f32_16x16x32_bf16 v[76:79], v[132:135], v[212:215], v[76:79]
	v_mfma_f32_16x16x32_bf16 v[72:75], v[156:159], v[212:215], v[72:75]
	v_mfma_f32_16x16x32_bf16 v[64:67], v[132:135], v[228:231], v[64:67]
	v_mfma_f32_16x16x32_bf16 v[56:59], v[156:159], v[228:231], v[56:59]
	v_mfma_f32_16x16x32_bf16 v[28:31], v[160:163], v[192:195], v[28:31]
	v_mfma_f32_16x16x32_bf16 v[24:27], v[184:187], v[192:195], v[24:27]
	v_mfma_f32_16x16x32_bf16 v[20:23], v[160:163], v[200:203], v[20:23]
	v_mfma_f32_16x16x32_bf16 v[16:19], v[184:187], v[200:203], v[16:19]
	v_mfma_f32_16x16x32_bf16 v[12:15], v[160:163], v[208:211], v[12:15]
	v_mfma_f32_16x16x32_bf16 v[8:11], v[184:187], v[208:211], v[8:11]
	v_mfma_f32_16x16x32_bf16 v[4:7], v[160:163], v[216:219], v[4:7]
	v_mfma_f32_16x16x32_bf16 v[0:3], v[184:187], v[216:219], v[0:3]
	v_mfma_f32_16x16x32_bf16 v[28:31], v[164:167], v[196:199], v[28:31]
	v_mfma_f32_16x16x32_bf16 v[24:27], v[188:191], v[196:199], v[24:27]
	v_mfma_f32_16x16x32_bf16 v[20:23], v[164:167], v[204:207], v[20:23]
	v_mfma_f32_16x16x32_bf16 v[16:19], v[188:191], v[204:207], v[16:19]
	v_mfma_f32_16x16x32_bf16 v[12:15], v[164:167], v[212:215], v[12:15]
	v_mfma_f32_16x16x32_bf16 v[8:11], v[188:191], v[212:215], v[8:11]
	v_mfma_f32_16x16x32_bf16 v[4:7], v[164:167], v[228:231], v[4:7]
	v_mfma_f32_16x16x32_bf16 v[0:3], v[188:191], v[228:231], v[0:3]
	s_barrier
	s_setprio 0
	s_add_i32 s12, 0, 0x18000
	s_add_i32 s13, 0, 0x1c000
	v_add_u32_e32 v156, s12, v149
	v_add_u32_e32 v188, s13, v149
	ds_read_b128 v[128:131], v156
	ds_read_b128 v[132:135], v156 offset:1024
	ds_read_b128 v[152:155], v156 offset:2048
	ds_read_b128 v[156:159], v156 offset:3072
	ds_read_b128 v[160:163], v188
	ds_read_b128 v[164:167], v188 offset:1024
	ds_read_b128 v[184:187], v188 offset:2048
	ds_read_b128 v[188:191], v188 offset:3072
	s_add_u32 s0, s52, 0x40000
	s_addc_u32 s1, s53, 0
	s_mov_b32 m0, s57
	ds_read_b128 v[192:195], v151 offset:32768
	ds_read_b128 v[196:199], v151 offset:33792
	ds_read_b128 v[200:203], v151 offset:34816
	ds_read_b128 v[204:207], v151 offset:35840
	ds_read_b128 v[208:211], v151 offset:36864
	ds_read_b128 v[212:215], v151 offset:37888
	ds_read_b128 v[216:219], v151 offset:38912
	ds_read_b128 v[228:231], v151 offset:39936
	global_load_lds_dwordx4 v136, s[0:1]
	s_mov_b32 m0, s58
	s_nop 0
	global_load_lds_dwordx4 v138, s[0:1]
	s_mov_b32 m0, s45
	s_nop 0
	global_load_lds_dwordx4 v[234:235], off
	s_mov_b32 m0, s56
	s_nop 0
	global_load_lds_dwordx4 v[236:237], off
	s_waitcnt vmcnt(8)
	s_waitcnt lgkmcnt(0)
	s_setprio 1
	s_barrier
	v_mfma_f32_16x16x32_bf16 v[124:127], v[128:131], v[192:195], v[124:127]
	v_mfma_f32_16x16x32_bf16 v[120:123], v[152:155], v[192:195], v[120:123]
	v_mfma_f32_16x16x32_bf16 v[116:119], v[128:131], v[200:203], v[116:119]
	v_mfma_f32_16x16x32_bf16 v[112:115], v[152:155], v[200:203], v[112:115]
	v_mfma_f32_16x16x32_bf16 v[108:111], v[128:131], v[208:211], v[108:111]
	v_mfma_f32_16x16x32_bf16 v[104:107], v[152:155], v[208:211], v[104:107]
	v_mfma_f32_16x16x32_bf16 v[100:103], v[128:131], v[216:219], v[100:103]
	v_mfma_f32_16x16x32_bf16 v[96:99], v[152:155], v[216:219], v[96:99]
	v_mfma_f32_16x16x32_bf16 v[124:127], v[132:135], v[196:199], v[124:127]
	v_mfma_f32_16x16x32_bf16 v[120:123], v[156:159], v[196:199], v[120:123]
	v_mfma_f32_16x16x32_bf16 v[116:119], v[132:135], v[204:207], v[116:119]
	v_mfma_f32_16x16x32_bf16 v[112:115], v[156:159], v[204:207], v[112:115]
	v_mfma_f32_16x16x32_bf16 v[108:111], v[132:135], v[212:215], v[108:111]
	v_mfma_f32_16x16x32_bf16 v[104:107], v[156:159], v[212:215], v[104:107]
	v_mfma_f32_16x16x32_bf16 v[100:103], v[132:135], v[228:231], v[100:103]
	v_mfma_f32_16x16x32_bf16 v[96:99], v[156:159], v[228:231], v[96:99]
	v_mfma_f32_16x16x32_bf16 v[68:71], v[160:163], v[192:195], v[68:71]
	v_mfma_f32_16x16x32_bf16 v[60:63], v[184:187], v[192:195], v[60:63]
	v_mfma_f32_16x16x32_bf16 v[52:55], v[160:163], v[200:203], v[52:55]
	v_mfma_f32_16x16x32_bf16 v[48:51], v[184:187], v[200:203], v[48:51]
	v_mfma_f32_16x16x32_bf16 v[44:47], v[160:163], v[208:211], v[44:47]
	v_mfma_f32_16x16x32_bf16 v[40:43], v[184:187], v[208:211], v[40:43]
	v_mfma_f32_16x16x32_bf16 v[36:39], v[160:163], v[216:219], v[36:39]
	v_mfma_f32_16x16x32_bf16 v[32:35], v[184:187], v[216:219], v[32:35]
	v_mfma_f32_16x16x32_bf16 v[68:71], v[164:167], v[196:199], v[68:71]
	v_mfma_f32_16x16x32_bf16 v[60:63], v[188:191], v[196:199], v[60:63]
	v_mfma_f32_16x16x32_bf16 v[52:55], v[164:167], v[204:207], v[52:55]
	v_mfma_f32_16x16x32_bf16 v[48:51], v[188:191], v[204:207], v[48:51]
	v_mfma_f32_16x16x32_bf16 v[44:47], v[164:167], v[212:215], v[44:47]
	v_mfma_f32_16x16x32_bf16 v[40:43], v[188:191], v[212:215], v[40:43]
	v_mfma_f32_16x16x32_bf16 v[36:39], v[164:167], v[228:231], v[36:39]
	v_mfma_f32_16x16x32_bf16 v[32:35], v[188:191], v[228:231], v[32:35]
	s_barrier
	s_setprio 0
	s_add_i32 s0, s12, s55
	v_lshl_add_u64 v[146:147], v[146:147], 0, s[16:17]
	s_mov_b32 m0, s0
	ds_read_b128 v[192:195], v151 offset:49152
	ds_read_b128 v[196:199], v151 offset:50176
	ds_read_b128 v[200:203], v151 offset:51200
	ds_read_b128 v[204:207], v151 offset:52224
	ds_read_b128 v[208:211], v151 offset:53248
	ds_read_b128 v[212:215], v151 offset:54272
	ds_read_b128 v[216:219], v151 offset:55296
	ds_read_b128 v[228:231], v151 offset:56320
	global_load_lds_dwordx4 v[146:147], off
	s_add_i32 m0, s0, 0x2000
	s_add_u32 s0, s50, 0x40080
	v_lshl_add_u64 v[146:147], v[232:233], 0, s[16:17]
	s_addc_u32 s1, s51, 0
	s_add_i32 s12, s13, s55
	global_load_lds_dwordx4 v[146:147], off
	s_mov_b32 m0, s12
	s_nop 0
	global_load_lds_dwordx4 v170, s[0:1]
	s_add_i32 m0, s12, 0x2000
	s_nop 0
	global_load_lds_dwordx4 v140, s[0:1]
	v_lshl_add_u64 v[146:147], v[234:235], 0, s[16:17]
	s_mov_b32 m0, s59
	s_nop 0
	global_load_lds_dwordx4 v[146:147], off
	v_lshl_add_u64 v[146:147], v[236:237], 0, s[16:17]
	s_mov_b32 m0, s60
	s_nop 0
	global_load_lds_dwordx4 v[146:147], off
	s_waitcnt vmcnt(6)
	s_waitcnt lgkmcnt(0)
	s_setprio 1
	s_barrier
	v_mfma_f32_16x16x32_bf16 v[92:95], v[128:131], v[192:195], v[92:95]
	v_mfma_f32_16x16x32_bf16 v[88:91], v[152:155], v[192:195], v[88:91]
	v_mfma_f32_16x16x32_bf16 v[84:87], v[128:131], v[200:203], v[84:87]
	v_mfma_f32_16x16x32_bf16 v[80:83], v[152:155], v[200:203], v[80:83]
	v_mfma_f32_16x16x32_bf16 v[76:79], v[128:131], v[208:211], v[76:79]
	v_mfma_f32_16x16x32_bf16 v[72:75], v[152:155], v[208:211], v[72:75]
	v_mfma_f32_16x16x32_bf16 v[64:67], v[128:131], v[216:219], v[64:67]
	v_mfma_f32_16x16x32_bf16 v[56:59], v[152:155], v[216:219], v[56:59]
	v_mfma_f32_16x16x32_bf16 v[92:95], v[132:135], v[196:199], v[92:95]
	v_mfma_f32_16x16x32_bf16 v[88:91], v[156:159], v[196:199], v[88:91]
	v_mfma_f32_16x16x32_bf16 v[84:87], v[132:135], v[204:207], v[84:87]
	v_mfma_f32_16x16x32_bf16 v[80:83], v[156:159], v[204:207], v[80:83]
	v_mfma_f32_16x16x32_bf16 v[76:79], v[132:135], v[212:215], v[76:79]
	v_mfma_f32_16x16x32_bf16 v[72:75], v[156:159], v[212:215], v[72:75]
	v_mfma_f32_16x16x32_bf16 v[64:67], v[132:135], v[228:231], v[64:67]
	v_mfma_f32_16x16x32_bf16 v[56:59], v[156:159], v[228:231], v[56:59]
	v_mfma_f32_16x16x32_bf16 v[28:31], v[160:163], v[192:195], v[28:31]
	v_mfma_f32_16x16x32_bf16 v[24:27], v[184:187], v[192:195], v[24:27]
	v_mfma_f32_16x16x32_bf16 v[20:23], v[160:163], v[200:203], v[20:23]
	v_mfma_f32_16x16x32_bf16 v[16:19], v[184:187], v[200:203], v[16:19]
	v_mfma_f32_16x16x32_bf16 v[12:15], v[160:163], v[208:211], v[12:15]
	v_mfma_f32_16x16x32_bf16 v[8:11], v[184:187], v[208:211], v[8:11]
	v_mfma_f32_16x16x32_bf16 v[4:7], v[160:163], v[216:219], v[4:7]
	v_mfma_f32_16x16x32_bf16 v[0:3], v[184:187], v[216:219], v[0:3]
	v_mfma_f32_16x16x32_bf16 v[28:31], v[164:167], v[196:199], v[28:31]
	v_mfma_f32_16x16x32_bf16 v[24:27], v[188:191], v[196:199], v[24:27]
	v_mfma_f32_16x16x32_bf16 v[20:23], v[164:167], v[204:207], v[20:23]
	v_mfma_f32_16x16x32_bf16 v[16:19], v[188:191], v[204:207], v[16:19]
	v_mfma_f32_16x16x32_bf16 v[12:15], v[164:167], v[212:215], v[12:15]
	v_mfma_f32_16x16x32_bf16 v[8:11], v[188:191], v[212:215], v[8:11]
	v_mfma_f32_16x16x32_bf16 v[4:7], v[164:167], v[228:231], v[4:7]
	v_mfma_f32_16x16x32_bf16 v[0:3], v[188:191], v[228:231], v[0:3]
	s_barrier
	s_setprio 0
	s_add_i32 s66, s66, 2
	s_add_u32 s64, s64, 0x100
	s_addc_u32 s65, s65, 0
	s_cmp_gt_u32 s66, 13
	s_mov_b64 s[46:47], s[48:49]
	s_cbranch_scc0 .LBB0_601
	s_and_b64 vcc, exec, s[30:31]
	s_cbranch_vccz .LBB0_604
	s_barrier

.Lrestag_776:
	s_add_u32 s50, s48, 0x100
	s_addc_u32 s51, s49, 0
	s_add_i32 s0, 0, 0x10000
	s_cmp_eq_u32 s66, 12
	s_cselect_b32 s55, s37, s51
	s_cselect_b32 s54, s45, s50
	s_cselect_b32 s53, s35, s65
	s_cselect_b32 s52, s63, s64
	s_add_i32 s12, 0, 0x14000
	v_add_u32_e32 v140, s0, v197
	v_add_u32_e32 v184, s12, v197
	ds_read_b128 v[128:131], v140
	ds_read_b128 v[132:135], v140 offset:1024
	ds_read_b128 v[136:139], v140 offset:2048
	ds_read_b128 v[140:143], v140 offset:3072
	ds_read_b128 v[144:147], v184
	ds_read_b128 v[148:151], v184 offset:1024
	ds_read_b128 v[164:167], v184 offset:2048
	ds_read_b128 v[184:187], v184 offset:3072
	s_add_i32 m0, s47, 0xc000
	ds_read_b128 v[188:191], v198
	ds_read_b128 v[192:195], v198 offset:1024
	ds_read_b128 v[200:203], v198 offset:2048
	ds_read_b128 v[204:207], v198 offset:3072
	ds_read_b128 v[208:211], v198 offset:4096
	ds_read_b128 v[212:215], v198 offset:5120
	ds_read_b128 v[216:219], v198 offset:6144
	ds_read_b128 v[228:231], v198 offset:7168
	global_load_lds_dwordx4 v160, s[48:49]
	s_add_i32 m0, s47, 0xe000
	s_nop 0
	global_load_lds_dwordx4 v162, s[48:49]
	s_nop 0
	s_waitcnt lgkmcnt(0)
	s_setprio 1
	s_barrier
	v_mfma_f32_16x16x32_bf16 v[124:127], v[128:131], v[188:191], 0
	v_mfma_f32_16x16x32_bf16 v[120:123], v[136:139], v[188:191], 0
	v_mfma_f32_16x16x32_bf16 v[108:111], v[128:131], v[200:203], 0
	v_mfma_f32_16x16x32_bf16 v[104:107], v[136:139], v[200:203], 0
	v_mfma_f32_16x16x32_bf16 v[92:95], v[128:131], v[208:211], 0
	v_mfma_f32_16x16x32_bf16 v[88:91], v[136:139], v[208:211], 0
	v_mfma_f32_16x16x32_bf16 v[76:79], v[128:131], v[216:219], 0
	v_mfma_f32_16x16x32_bf16 v[72:75], v[136:139], v[216:219], 0
	v_mfma_f32_16x16x32_bf16 v[124:127], v[132:135], v[192:195], v[124:127]
	v_mfma_f32_16x16x32_bf16 v[120:123], v[140:143], v[192:195], v[120:123]
	v_mfma_f32_16x16x32_bf16 v[108:111], v[132:135], v[204:207], v[108:111]
	v_mfma_f32_16x16x32_bf16 v[104:107], v[140:143], v[204:207], v[104:107]
	v_mfma_f32_16x16x32_bf16 v[92:95], v[132:135], v[212:215], v[92:95]
	v_mfma_f32_16x16x32_bf16 v[88:91], v[140:143], v[212:215], v[88:91]
	v_mfma_f32_16x16x32_bf16 v[76:79], v[132:135], v[228:231], v[76:79]
	v_mfma_f32_16x16x32_bf16 v[72:75], v[140:143], v[228:231], v[72:75]
	v_mfma_f32_16x16x32_bf16 v[116:119], v[144:147], v[188:191], 0
	v_mfma_f32_16x16x32_bf16 v[112:115], v[164:167], v[188:191], 0
	v_mfma_f32_16x16x32_bf16 v[100:103], v[144:147], v[200:203], 0
	v_mfma_f32_16x16x32_bf16 v[96:99], v[164:167], v[200:203], 0
	v_mfma_f32_16x16x32_bf16 v[84:87], v[144:147], v[208:211], 0
	v_mfma_f32_16x16x32_bf16 v[80:83], v[164:167], v[208:211], 0
	v_mfma_f32_16x16x32_bf16 v[68:71], v[144:147], v[216:219], 0
	v_mfma_f32_16x16x32_bf16 v[64:67], v[164:167], v[216:219], 0
	v_mfma_f32_16x16x32_bf16 v[116:119], v[148:151], v[192:195], v[116:119]
	v_mfma_f32_16x16x32_bf16 v[112:115], v[184:187], v[192:195], v[112:115]
	v_mfma_f32_16x16x32_bf16 v[100:103], v[148:151], v[204:207], v[100:103]
	v_mfma_f32_16x16x32_bf16 v[96:99], v[184:187], v[204:207], v[96:99]
	v_mfma_f32_16x16x32_bf16 v[84:87], v[148:151], v[212:215], v[84:87]
	v_mfma_f32_16x16x32_bf16 v[80:83], v[184:187], v[212:215], v[80:83]
	v_mfma_f32_16x16x32_bf16 v[68:71], v[148:151], v[228:231], v[68:71]
	v_mfma_f32_16x16x32_bf16 v[64:67], v[184:187], v[228:231], v[64:67]
	s_barrier
	s_setprio 0
	s_add_i32 s0, s0, s56
	v_lshl_add_u64 v[232:233], s[52:53], 0, v[170:171]
	s_mov_b32 m0, s0
	ds_read_b128 v[188:191], v198 offset:16384
	ds_read_b128 v[192:195], v198 offset:17408
	ds_read_b128 v[200:203], v198 offset:18432
	ds_read_b128 v[204:207], v198 offset:19456
	ds_read_b128 v[208:211], v198 offset:20480
	ds_read_b128 v[212:215], v198 offset:21504
	ds_read_b128 v[216:219], v198 offset:22528
	ds_read_b128 v[228:231], v198 offset:23552
	global_load_lds_dwordx4 v[232:233], off
	s_add_i32 m0, s0, 0x2000
	s_add_u32 s0, s52, 0x40000
	v_lshl_add_u64 v[234:235], s[52:53], 0, v[156:157]
	s_addc_u32 s1, s53, 0
	s_add_i32 s12, s12, s56
	global_load_lds_dwordx4 v[234:235], off
	s_mov_b32 m0, s12
	v_lshl_add_u64 v[238:239], s[54:55], 0, v[154:155]
	global_load_lds_dwordx4 v170, s[0:1]
	s_add_i32 m0, s12, 0x2000
	s_nop 0
	global_load_lds_dwordx4 v156, s[0:1]
	v_lshl_add_u64 v[236:237], s[54:55], 0, v[152:153]
	s_nop 0
	s_waitcnt lgkmcnt(0)
	s_setprio 1
	s_barrier
	v_mfma_f32_16x16x32_bf16 v[60:63], v[128:131], v[188:191], 0
	v_mfma_f32_16x16x32_bf16 v[56:59], v[136:139], v[188:191], 0
	v_mfma_f32_16x16x32_bf16 v[44:47], v[128:131], v[200:203], 0
	v_mfma_f32_16x16x32_bf16 v[40:43], v[136:139], v[200:203], 0
	v_mfma_f32_16x16x32_bf16 v[28:31], v[128:131], v[208:211], 0
	v_mfma_f32_16x16x32_bf16 v[24:27], v[136:139], v[208:211], 0
	v_mfma_f32_16x16x32_bf16 v[12:15], v[128:131], v[216:219], 0
	v_mfma_f32_16x16x32_bf16 v[8:11], v[136:139], v[216:219], 0
	v_mfma_f32_16x16x32_bf16 v[60:63], v[132:135], v[192:195], v[60:63]
	v_mfma_f32_16x16x32_bf16 v[56:59], v[140:143], v[192:195], v[56:59]
	v_mfma_f32_16x16x32_bf16 v[44:47], v[132:135], v[204:207], v[44:47]
	v_mfma_f32_16x16x32_bf16 v[40:43], v[140:143], v[204:207], v[40:43]
	v_mfma_f32_16x16x32_bf16 v[28:31], v[132:135], v[212:215], v[28:31]
	v_mfma_f32_16x16x32_bf16 v[24:27], v[140:143], v[212:215], v[24:27]
	v_mfma_f32_16x16x32_bf16 v[12:15], v[132:135], v[228:231], v[12:15]
	v_mfma_f32_16x16x32_bf16 v[8:11], v[140:143], v[228:231], v[8:11]
	v_mfma_f32_16x16x32_bf16 v[52:55], v[144:147], v[188:191], 0
	v_mfma_f32_16x16x32_bf16 v[48:51], v[164:167], v[188:191], 0
	v_mfma_f32_16x16x32_bf16 v[36:39], v[144:147], v[200:203], 0
	v_mfma_f32_16x16x32_bf16 v[32:35], v[164:167], v[200:203], 0
	v_mfma_f32_16x16x32_bf16 v[20:23], v[144:147], v[208:211], 0
	v_mfma_f32_16x16x32_bf16 v[16:19], v[164:167], v[208:211], 0
	v_mfma_f32_16x16x32_bf16 v[4:7], v[144:147], v[216:219], 0
	v_mfma_f32_16x16x32_bf16 v[0:3], v[164:167], v[216:219], 0
	v_mfma_f32_16x16x32_bf16 v[52:55], v[148:151], v[192:195], v[52:55]
	v_mfma_f32_16x16x32_bf16 v[48:51], v[184:187], v[192:195], v[48:51]
	v_mfma_f32_16x16x32_bf16 v[36:39], v[148:151], v[204:207], v[36:39]
	v_mfma_f32_16x16x32_bf16 v[32:35], v[184:187], v[204:207], v[32:35]
	v_mfma_f32_16x16x32_bf16 v[20:23], v[148:151], v[212:215], v[20:23]
	v_mfma_f32_16x16x32_bf16 v[16:19], v[184:187], v[212:215], v[16:19]
	v_mfma_f32_16x16x32_bf16 v[4:7], v[148:151], v[228:231], v[4:7]
	v_mfma_f32_16x16x32_bf16 v[0:3], v[184:187], v[228:231], v[0:3]
	s_barrier
	s_setprio 0
	s_add_i32 s12, 0, 0x18000
	s_add_i32 s13, 0, 0x1c000
	v_add_u32_e32 v140, s12, v197
	v_add_u32_e32 v184, s13, v197
	ds_read_b128 v[128:131], v140
	ds_read_b128 v[132:135], v140 offset:1024
	ds_read_b128 v[136:139], v140 offset:2048
	ds_read_b128 v[140:143], v140 offset:3072
	ds_read_b128 v[144:147], v184
	ds_read_b128 v[148:151], v184 offset:1024
	ds_read_b128 v[164:167], v184 offset:2048
	ds_read_b128 v[184:187], v184 offset:3072
	s_add_u32 s0, s54, 0x40000
	s_addc_u32 s1, s55, 0
	s_mov_b32 m0, s58
	ds_read_b128 v[188:191], v198 offset:32768
	ds_read_b128 v[192:195], v198 offset:33792
	ds_read_b128 v[200:203], v198 offset:34816
	ds_read_b128 v[204:207], v198 offset:35840
	ds_read_b128 v[208:211], v198 offset:36864
	ds_read_b128 v[212:215], v198 offset:37888
	ds_read_b128 v[216:219], v198 offset:38912
	ds_read_b128 v[228:231], v198 offset:39936
	global_load_lds_dwordx4 v152, s[0:1]
	s_mov_b32 m0, s59
	s_nop 0
	global_load_lds_dwordx4 v154, s[0:1]
	s_mov_b32 m0, s47
	s_nop 0
	global_load_lds_dwordx4 v[236:237], off
	s_mov_b32 m0, s57
	s_nop 0
	global_load_lds_dwordx4 v[238:239], off
	s_waitcnt vmcnt(8)
	s_waitcnt lgkmcnt(0)
	s_setprio 1
	s_barrier
	v_mfma_f32_16x16x32_bf16 v[124:127], v[128:131], v[188:191], v[124:127]
	v_mfma_f32_16x16x32_bf16 v[120:123], v[136:139], v[188:191], v[120:123]
	v_mfma_f32_16x16x32_bf16 v[108:111], v[128:131], v[200:203], v[108:111]
	v_mfma_f32_16x16x32_bf16 v[104:107], v[136:139], v[200:203], v[104:107]
	v_mfma_f32_16x16x32_bf16 v[92:95], v[128:131], v[208:211], v[92:95]
	v_mfma_f32_16x16x32_bf16 v[88:91], v[136:139], v[208:211], v[88:91]
	v_mfma_f32_16x16x32_bf16 v[76:79], v[128:131], v[216:219], v[76:79]
	v_mfma_f32_16x16x32_bf16 v[72:75], v[136:139], v[216:219], v[72:75]
	v_mfma_f32_16x16x32_bf16 v[124:127], v[132:135], v[192:195], v[124:127]
	v_mfma_f32_16x16x32_bf16 v[120:123], v[140:143], v[192:195], v[120:123]
	v_mfma_f32_16x16x32_bf16 v[108:111], v[132:135], v[204:207], v[108:111]
	v_mfma_f32_16x16x32_bf16 v[104:107], v[140:143], v[204:207], v[104:107]
	v_mfma_f32_16x16x32_bf16 v[92:95], v[132:135], v[212:215], v[92:95]
	v_mfma_f32_16x16x32_bf16 v[88:91], v[140:143], v[212:215], v[88:91]
	v_mfma_f32_16x16x32_bf16 v[76:79], v[132:135], v[228:231], v[76:79]
	v_mfma_f32_16x16x32_bf16 v[72:75], v[140:143], v[228:231], v[72:75]
	v_mfma_f32_16x16x32_bf16 v[116:119], v[144:147], v[188:191], v[116:119]
	v_mfma_f32_16x16x32_bf16 v[112:115], v[164:167], v[188:191], v[112:115]
	v_mfma_f32_16x16x32_bf16 v[100:103], v[144:147], v[200:203], v[100:103]
	v_mfma_f32_16x16x32_bf16 v[96:99], v[164:167], v[200:203], v[96:99]
	v_mfma_f32_16x16x32_bf16 v[84:87], v[144:147], v[208:211], v[84:87]
	v_mfma_f32_16x16x32_bf16 v[80:83], v[164:167], v[208:211], v[80:83]
	v_mfma_f32_16x16x32_bf16 v[68:71], v[144:147], v[216:219], v[68:71]
	v_mfma_f32_16x16x32_bf16 v[64:67], v[164:167], v[216:219], v[64:67]
	v_mfma_f32_16x16x32_bf16 v[116:119], v[148:151], v[192:195], v[116:119]
	v_mfma_f32_16x16x32_bf16 v[112:115], v[184:187], v[192:195], v[112:115]
	v_mfma_f32_16x16x32_bf16 v[100:103], v[148:151], v[204:207], v[100:103]
	v_mfma_f32_16x16x32_bf16 v[96:99], v[184:187], v[204:207], v[96:99]
	v_mfma_f32_16x16x32_bf16 v[84:87], v[148:151], v[212:215], v[84:87]
	v_mfma_f32_16x16x32_bf16 v[80:83], v[184:187], v[212:215], v[80:83]
	v_mfma_f32_16x16x32_bf16 v[68:71], v[148:151], v[228:231], v[68:71]
	v_mfma_f32_16x16x32_bf16 v[64:67], v[184:187], v[228:231], v[64:67]
	s_barrier
	s_setprio 0
	s_add_i32 s0, s12, s56
	v_lshl_add_u64 v[232:233], v[232:233], 0, s[16:17]
	s_mov_b32 m0, s0
	ds_read_b128 v[188:191], v198 offset:49152
	ds_read_b128 v[192:195], v198 offset:50176
	ds_read_b128 v[200:203], v198 offset:51200
	ds_read_b128 v[204:207], v198 offset:52224
	ds_read_b128 v[208:211], v198 offset:53248
	ds_read_b128 v[212:215], v198 offset:54272
	ds_read_b128 v[216:219], v198 offset:55296
	ds_read_b128 v[228:231], v198 offset:56320
	global_load_lds_dwordx4 v[232:233], off
	s_add_i32 m0, s0, 0x2000
	s_add_u32 s0, s52, 0x40080
	v_lshl_add_u64 v[232:233], v[234:235], 0, s[16:17]
	s_addc_u32 s1, s53, 0
	s_add_i32 s12, s13, s56
	global_load_lds_dwordx4 v[232:233], off
	s_mov_b32 m0, s12
	s_nop 0
	global_load_lds_dwordx4 v170, s[0:1]
	s_add_i32 m0, s12, 0x2000
	s_nop 0
	global_load_lds_dwordx4 v156, s[0:1]
	v_lshl_add_u64 v[232:233], v[236:237], 0, s[16:17]
	s_mov_b32 m0, s60
	s_nop 0
	global_load_lds_dwordx4 v[232:233], off
	v_lshl_add_u64 v[232:233], v[238:239], 0, s[16:17]
	s_mov_b32 m0, s61
	s_nop 0
	global_load_lds_dwordx4 v[232:233], off
	s_waitcnt vmcnt(6)
	s_waitcnt lgkmcnt(0)
	s_setprio 1
	s_barrier
	v_mfma_f32_16x16x32_bf16 v[60:63], v[128:131], v[188:191], v[60:63]
	v_mfma_f32_16x16x32_bf16 v[56:59], v[136:139], v[188:191], v[56:59]
	v_mfma_f32_16x16x32_bf16 v[44:47], v[128:131], v[200:203], v[44:47]
	v_mfma_f32_16x16x32_bf16 v[40:43], v[136:139], v[200:203], v[40:43]
	v_mfma_f32_16x16x32_bf16 v[28:31], v[128:131], v[208:211], v[28:31]
	v_mfma_f32_16x16x32_bf16 v[24:27], v[136:139], v[208:211], v[24:27]
	v_mfma_f32_16x16x32_bf16 v[12:15], v[128:131], v[216:219], v[12:15]
	v_mfma_f32_16x16x32_bf16 v[8:11], v[136:139], v[216:219], v[8:11]
	v_mfma_f32_16x16x32_bf16 v[60:63], v[132:135], v[192:195], v[60:63]
	v_mfma_f32_16x16x32_bf16 v[56:59], v[140:143], v[192:195], v[56:59]
	v_mfma_f32_16x16x32_bf16 v[44:47], v[132:135], v[204:207], v[44:47]
	v_mfma_f32_16x16x32_bf16 v[40:43], v[140:143], v[204:207], v[40:43]
	v_mfma_f32_16x16x32_bf16 v[28:31], v[132:135], v[212:215], v[28:31]
	v_mfma_f32_16x16x32_bf16 v[24:27], v[140:143], v[212:215], v[24:27]
	v_mfma_f32_16x16x32_bf16 v[12:15], v[132:135], v[228:231], v[12:15]
	v_mfma_f32_16x16x32_bf16 v[8:11], v[140:143], v[228:231], v[8:11]
	v_mfma_f32_16x16x32_bf16 v[52:55], v[144:147], v[188:191], v[52:55]
	v_mfma_f32_16x16x32_bf16 v[48:51], v[164:167], v[188:191], v[48:51]
	v_mfma_f32_16x16x32_bf16 v[36:39], v[144:147], v[200:203], v[36:39]
	v_mfma_f32_16x16x32_bf16 v[32:35], v[164:167], v[200:203], v[32:35]
	v_mfma_f32_16x16x32_bf16 v[20:23], v[144:147], v[208:211], v[20:23]
	v_mfma_f32_16x16x32_bf16 v[16:19], v[164:167], v[208:211], v[16:19]
	v_mfma_f32_16x16x32_bf16 v[4:7], v[144:147], v[216:219], v[4:7]
	v_mfma_f32_16x16x32_bf16 v[0:3], v[164:167], v[216:219], v[0:3]
	v_mfma_f32_16x16x32_bf16 v[52:55], v[148:151], v[192:195], v[52:55]
	v_mfma_f32_16x16x32_bf16 v[48:51], v[184:187], v[192:195], v[48:51]
	v_mfma_f32_16x16x32_bf16 v[36:39], v[148:151], v[204:207], v[36:39]
	v_mfma_f32_16x16x32_bf16 v[32:35], v[184:187], v[204:207], v[32:35]
	v_mfma_f32_16x16x32_bf16 v[20:23], v[148:151], v[212:215], v[20:23]
	v_mfma_f32_16x16x32_bf16 v[16:19], v[184:187], v[212:215], v[16:19]
	v_mfma_f32_16x16x32_bf16 v[4:7], v[148:151], v[228:231], v[4:7]
	v_mfma_f32_16x16x32_bf16 v[0:3], v[184:187], v[228:231], v[0:3]
	s_barrier
	s_setprio 0
	s_add_i32 s66, s66, 2
	s_add_u32 s64, s64, 0x100
	s_addc_u32 s65, s65, 0
	s_cmp_gt_u32 s66, 13
	s_mov_b64 s[48:49], s[50:51]
.LBB0_776:
	s_add_u32 s50, s48, 0x100
	s_addc_u32 s51, s49, 0
	s_add_i32 s0, 0, 0x10000
	s_cmp_eq_u32 s66, 12
	s_cselect_b32 s55, s37, s51
	s_cselect_b32 s54, s45, s50
	s_cselect_b32 s53, s35, s65
	s_cselect_b32 s52, s63, s64
	s_add_i32 s12, 0, 0x14000
	v_add_u32_e32 v140, s0, v197
	v_add_u32_e32 v184, s12, v197
	ds_read_b128 v[128:131], v140
	ds_read_b128 v[132:135], v140 offset:1024
	ds_read_b128 v[136:139], v140 offset:2048
	ds_read_b128 v[140:143], v140 offset:3072
	ds_read_b128 v[144:147], v184
	ds_read_b128 v[148:151], v184 offset:1024
	ds_read_b128 v[164:167], v184 offset:2048
	ds_read_b128 v[184:187], v184 offset:3072
	s_add_i32 m0, s47, 0xc000
	ds_read_b128 v[188:191], v198
	ds_read_b128 v[192:195], v198 offset:1024
	ds_read_b128 v[200:203], v198 offset:2048
	ds_read_b128 v[204:207], v198 offset:3072
	ds_read_b128 v[208:211], v198 offset:4096
	ds_read_b128 v[212:215], v198 offset:5120
	ds_read_b128 v[216:219], v198 offset:6144
	ds_read_b128 v[228:231], v198 offset:7168
	global_load_lds_dwordx4 v160, s[48:49]
	s_add_i32 m0, s47, 0xe000
	s_nop 0
	global_load_lds_dwordx4 v162, s[48:49]
	s_waitcnt vmcnt(8)
	s_waitcnt lgkmcnt(0)
	s_setprio 1
	s_barrier
	v_mfma_f32_16x16x32_bf16 v[124:127], v[128:131], v[188:191], v[124:127]
	v_mfma_f32_16x16x32_bf16 v[120:123], v[136:139], v[188:191], v[120:123]
	v_mfma_f32_16x16x32_bf16 v[108:111], v[128:131], v[200:203], v[108:111]
	v_mfma_f32_16x16x32_bf16 v[104:107], v[136:139], v[200:203], v[104:107]
	v_mfma_f32_16x16x32_bf16 v[92:95], v[128:131], v[208:211], v[92:95]
	v_mfma_f32_16x16x32_bf16 v[88:91], v[136:139], v[208:211], v[88:91]
	v_mfma_f32_16x16x32_bf16 v[76:79], v[128:131], v[216:219], v[76:79]
	v_mfma_f32_16x16x32_bf16 v[72:75], v[136:139], v[216:219], v[72:75]
	v_mfma_f32_16x16x32_bf16 v[124:127], v[132:135], v[192:195], v[124:127]
	v_mfma_f32_16x16x32_bf16 v[120:123], v[140:143], v[192:195], v[120:123]
	v_mfma_f32_16x16x32_bf16 v[108:111], v[132:135], v[204:207], v[108:111]
	v_mfma_f32_16x16x32_bf16 v[104:107], v[140:143], v[204:207], v[104:107]
	v_mfma_f32_16x16x32_bf16 v[92:95], v[132:135], v[212:215], v[92:95]
	v_mfma_f32_16x16x32_bf16 v[88:91], v[140:143], v[212:215], v[88:91]
	v_mfma_f32_16x16x32_bf16 v[76:79], v[132:135], v[228:231], v[76:79]
	v_mfma_f32_16x16x32_bf16 v[72:75], v[140:143], v[228:231], v[72:75]
	v_mfma_f32_16x16x32_bf16 v[116:119], v[144:147], v[188:191], v[116:119]
	v_mfma_f32_16x16x32_bf16 v[112:115], v[164:167], v[188:191], v[112:115]
	v_mfma_f32_16x16x32_bf16 v[100:103], v[144:147], v[200:203], v[100:103]
	v_mfma_f32_16x16x32_bf16 v[96:99], v[164:167], v[200:203], v[96:99]
	v_mfma_f32_16x16x32_bf16 v[84:87], v[144:147], v[208:211], v[84:87]
	v_mfma_f32_16x16x32_bf16 v[80:83], v[164:167], v[208:211], v[80:83]
	v_mfma_f32_16x16x32_bf16 v[68:71], v[144:147], v[216:219], v[68:71]
	v_mfma_f32_16x16x32_bf16 v[64:67], v[164:167], v[216:219], v[64:67]
	v_mfma_f32_16x16x32_bf16 v[116:119], v[148:151], v[192:195], v[116:119]
	v_mfma_f32_16x16x32_bf16 v[112:115], v[184:187], v[192:195], v[112:115]
	v_mfma_f32_16x16x32_bf16 v[100:103], v[148:151], v[204:207], v[100:103]
	v_mfma_f32_16x16x32_bf16 v[96:99], v[184:187], v[204:207], v[96:99]
	v_mfma_f32_16x16x32_bf16 v[84:87], v[148:151], v[212:215], v[84:87]
	v_mfma_f32_16x16x32_bf16 v[80:83], v[184:187], v[212:215], v[80:83]
	v_mfma_f32_16x16x32_bf16 v[68:71], v[148:151], v[228:231], v[68:71]
	v_mfma_f32_16x16x32_bf16 v[64:67], v[184:187], v[228:231], v[64:67]
	s_barrier
	s_setprio 0
	s_add_i32 s0, s0, s56
	v_lshl_add_u64 v[232:233], s[52:53], 0, v[170:171]
	s_mov_b32 m0, s0
	ds_read_b128 v[188:191], v198 offset:16384
	ds_read_b128 v[192:195], v198 offset:17408
	ds_read_b128 v[200:203], v198 offset:18432
	ds_read_b128 v[204:207], v198 offset:19456
	ds_read_b128 v[208:211], v198 offset:20480
	ds_read_b128 v[212:215], v198 offset:21504
	ds_read_b128 v[216:219], v198 offset:22528
	ds_read_b128 v[228:231], v198 offset:23552
	global_load_lds_dwordx4 v[232:233], off
	s_add_i32 m0, s0, 0x2000
	s_add_u32 s0, s52, 0x40000
	v_lshl_add_u64 v[234:235], s[52:53], 0, v[156:157]
	s_addc_u32 s1, s53, 0
	s_add_i32 s12, s12, s56
	global_load_lds_dwordx4 v[234:235], off
	s_mov_b32 m0, s12
	v_lshl_add_u64 v[238:239], s[54:55], 0, v[154:155]
	global_load_lds_dwordx4 v170, s[0:1]
	s_add_i32 m0, s12, 0x2000
	s_nop 0
	global_load_lds_dwordx4 v156, s[0:1]
	v_lshl_add_u64 v[236:237], s[54:55], 0, v[152:153]
	s_waitcnt vmcnt(6)
	s_waitcnt lgkmcnt(0)
	s_setprio 1
	s_barrier
	v_mfma_f32_16x16x32_bf16 v[60:63], v[128:131], v[188:191], v[60:63]
	v_mfma_f32_16x16x32_bf16 v[56:59], v[136:139], v[188:191], v[56:59]
	v_mfma_f32_16x16x32_bf16 v[44:47], v[128:131], v[200:203], v[44:47]
	v_mfma_f32_16x16x32_bf16 v[40:43], v[136:139], v[200:203], v[40:43]
	v_mfma_f32_16x16x32_bf16 v[28:31], v[128:131], v[208:211], v[28:31]
	v_mfma_f32_16x16x32_bf16 v[24:27], v[136:139], v[208:211], v[24:27]
	v_mfma_f32_16x16x32_bf16 v[12:15], v[128:131], v[216:219], v[12:15]
	v_mfma_f32_16x16x32_bf16 v[8:11], v[136:139], v[216:219], v[8:11]
	v_mfma_f32_16x16x32_bf16 v[60:63], v[132:135], v[192:195], v[60:63]
	v_mfma_f32_16x16x32_bf16 v[56:59], v[140:143], v[192:195], v[56:59]
	v_mfma_f32_16x16x32_bf16 v[44:47], v[132:135], v[204:207], v[44:47]
	v_mfma_f32_16x16x32_bf16 v[40:43], v[140:143], v[204:207], v[40:43]
	v_mfma_f32_16x16x32_bf16 v[28:31], v[132:135], v[212:215], v[28:31]
	v_mfma_f32_16x16x32_bf16 v[24:27], v[140:143], v[212:215], v[24:27]
	v_mfma_f32_16x16x32_bf16 v[12:15], v[132:135], v[228:231], v[12:15]
	v_mfma_f32_16x16x32_bf16 v[8:11], v[140:143], v[228:231], v[8:11]
	v_mfma_f32_16x16x32_bf16 v[52:55], v[144:147], v[188:191], v[52:55]
	v_mfma_f32_16x16x32_bf16 v[48:51], v[164:167], v[188:191], v[48:51]
	v_mfma_f32_16x16x32_bf16 v[36:39], v[144:147], v[200:203], v[36:39]
	v_mfma_f32_16x16x32_bf16 v[32:35], v[164:167], v[200:203], v[32:35]
	v_mfma_f32_16x16x32_bf16 v[20:23], v[144:147], v[208:211], v[20:23]
	v_mfma_f32_16x16x32_bf16 v[16:19], v[164:167], v[208:211], v[16:19]
	v_mfma_f32_16x16x32_bf16 v[4:7], v[144:147], v[216:219], v[4:7]
	v_mfma_f32_16x16x32_bf16 v[0:3], v[164:167], v[216:219], v[0:3]
	v_mfma_f32_16x16x32_bf16 v[52:55], v[148:151], v[192:195], v[52:55]
	v_mfma_f32_16x16x32_bf16 v[48:51], v[184:187], v[192:195], v[48:51]
	v_mfma_f32_16x16x32_bf16 v[36:39], v[148:151], v[204:207], v[36:39]
	v_mfma_f32_16x16x32_bf16 v[32:35], v[184:187], v[204:207], v[32:35]
	v_mfma_f32_16x16x32_bf16 v[20:23], v[148:151], v[212:215], v[20:23]
	v_mfma_f32_16x16x32_bf16 v[16:19], v[184:187], v[212:215], v[16:19]
	v_mfma_f32_16x16x32_bf16 v[4:7], v[148:151], v[228:231], v[4:7]
	v_mfma_f32_16x16x32_bf16 v[0:3], v[184:187], v[228:231], v[0:3]
	s_barrier
	s_setprio 0
	s_add_i32 s12, 0, 0x18000
	s_add_i32 s13, 0, 0x1c000
	v_add_u32_e32 v140, s12, v197
	v_add_u32_e32 v184, s13, v197
	ds_read_b128 v[128:131], v140
	ds_read_b128 v[132:135], v140 offset:1024
	ds_read_b128 v[136:139], v140 offset:2048
	ds_read_b128 v[140:143], v140 offset:3072
	ds_read_b128 v[144:147], v184
	ds_read_b128 v[148:151], v184 offset:1024
	ds_read_b128 v[164:167], v184 offset:2048
	ds_read_b128 v[184:187], v184 offset:3072
	s_add_u32 s0, s54, 0x40000
	s_addc_u32 s1, s55, 0
	s_mov_b32 m0, s58
	ds_read_b128 v[188:191], v198 offset:32768
	ds_read_b128 v[192:195], v198 offset:33792
	ds_read_b128 v[200:203], v198 offset:34816
	ds_read_b128 v[204:207], v198 offset:35840
	ds_read_b128 v[208:211], v198 offset:36864
	ds_read_b128 v[212:215], v198 offset:37888
	ds_read_b128 v[216:219], v198 offset:38912
	ds_read_b128 v[228:231], v198 offset:39936
	global_load_lds_dwordx4 v152, s[0:1]
	s_mov_b32 m0, s59
	s_nop 0
	global_load_lds_dwordx4 v154, s[0:1]
	s_mov_b32 m0, s47
	s_nop 0
	global_load_lds_dwordx4 v[236:237], off
	s_mov_b32 m0, s57
	s_nop 0
	global_load_lds_dwordx4 v[238:239], off
	s_waitcnt vmcnt(8)
	s_waitcnt lgkmcnt(0)
	s_setprio 1
	s_barrier
	v_mfma_f32_16x16x32_bf16 v[124:127], v[128:131], v[188:191], v[124:127]
	v_mfma_f32_16x16x32_bf16 v[120:123], v[136:139], v[188:191], v[120:123]
	v_mfma_f32_16x16x32_bf16 v[108:111], v[128:131], v[200:203], v[108:111]
	v_mfma_f32_16x16x32_bf16 v[104:107], v[136:139], v[200:203], v[104:107]
	v_mfma_f32_16x16x32_bf16 v[92:95], v[128:131], v[208:211], v[92:95]
	v_mfma_f32_16x16x32_bf16 v[88:91], v[136:139], v[208:211], v[88:91]
	v_mfma_f32_16x16x32_bf16 v[76:79], v[128:131], v[216:219], v[76:79]
	v_mfma_f32_16x16x32_bf16 v[72:75], v[136:139], v[216:219], v[72:75]
	v_mfma_f32_16x16x32_bf16 v[124:127], v[132:135], v[192:195], v[124:127]
	v_mfma_f32_16x16x32_bf16 v[120:123], v[140:143], v[192:195], v[120:123]
	v_mfma_f32_16x16x32_bf16 v[108:111], v[132:135], v[204:207], v[108:111]
	v_mfma_f32_16x16x32_bf16 v[104:107], v[140:143], v[204:207], v[104:107]
	v_mfma_f32_16x16x32_bf16 v[92:95], v[132:135], v[212:215], v[92:95]
	v_mfma_f32_16x16x32_bf16 v[88:91], v[140:143], v[212:215], v[88:91]
	v_mfma_f32_16x16x32_bf16 v[76:79], v[132:135], v[228:231], v[76:79]
	v_mfma_f32_16x16x32_bf16 v[72:75], v[140:143], v[228:231], v[72:75]
	v_mfma_f32_16x16x32_bf16 v[116:119], v[144:147], v[188:191], v[116:119]
	v_mfma_f32_16x16x32_bf16 v[112:115], v[164:167], v[188:191], v[112:115]
	v_mfma_f32_16x16x32_bf16 v[100:103], v[144:147], v[200:203], v[100:103]
	v_mfma_f32_16x16x32_bf16 v[96:99], v[164:167], v[200:203], v[96:99]
	v_mfma_f32_16x16x32_bf16 v[84:87], v[144:147], v[208:211], v[84:87]
	v_mfma_f32_16x16x32_bf16 v[80:83], v[164:167], v[208:211], v[80:83]
	v_mfma_f32_16x16x32_bf16 v[68:71], v[144:147], v[216:219], v[68:71]
	v_mfma_f32_16x16x32_bf16 v[64:67], v[164:167], v[216:219], v[64:67]
	v_mfma_f32_16x16x32_bf16 v[116:119], v[148:151], v[192:195], v[116:119]
	v_mfma_f32_16x16x32_bf16 v[112:115], v[184:187], v[192:195], v[112:115]
	v_mfma_f32_16x16x32_bf16 v[100:103], v[148:151], v[204:207], v[100:103]
	v_mfma_f32_16x16x32_bf16 v[96:99], v[184:187], v[204:207], v[96:99]
	v_mfma_f32_16x16x32_bf16 v[84:87], v[148:151], v[212:215], v[84:87]
	v_mfma_f32_16x16x32_bf16 v[80:83], v[184:187], v[212:215], v[80:83]
	v_mfma_f32_16x16x32_bf16 v[68:71], v[148:151], v[228:231], v[68:71]
	v_mfma_f32_16x16x32_bf16 v[64:67], v[184:187], v[228:231], v[64:67]
	s_barrier
	s_setprio 0
	s_add_i32 s0, s12, s56
	v_lshl_add_u64 v[232:233], v[232:233], 0, s[16:17]
	s_mov_b32 m0, s0
	ds_read_b128 v[188:191], v198 offset:49152
	ds_read_b128 v[192:195], v198 offset:50176
	ds_read_b128 v[200:203], v198 offset:51200
	ds_read_b128 v[204:207], v198 offset:52224
	ds_read_b128 v[208:211], v198 offset:53248
	ds_read_b128 v[212:215], v198 offset:54272
	ds_read_b128 v[216:219], v198 offset:55296
	ds_read_b128 v[228:231], v198 offset:56320
	global_load_lds_dwordx4 v[232:233], off
	s_add_i32 m0, s0, 0x2000
	s_add_u32 s0, s52, 0x40080
	v_lshl_add_u64 v[232:233], v[234:235], 0, s[16:17]
	s_addc_u32 s1, s53, 0
	s_add_i32 s12, s13, s56
	global_load_lds_dwordx4 v[232:233], off
	s_mov_b32 m0, s12
	s_nop 0
	global_load_lds_dwordx4 v170, s[0:1]
	s_add_i32 m0, s12, 0x2000
	s_nop 0
	global_load_lds_dwordx4 v156, s[0:1]
	v_lshl_add_u64 v[232:233], v[236:237], 0, s[16:17]
	s_mov_b32 m0, s60
	s_nop 0
	global_load_lds_dwordx4 v[232:233], off
	v_lshl_add_u64 v[232:233], v[238:239], 0, s[16:17]
	s_mov_b32 m0, s61
	s_nop 0
	global_load_lds_dwordx4 v[232:233], off
	s_waitcnt vmcnt(6)
	s_waitcnt lgkmcnt(0)
	s_setprio 1
	s_barrier
	v_mfma_f32_16x16x32_bf16 v[60:63], v[128:131], v[188:191], v[60:63]
	v_mfma_f32_16x16x32_bf16 v[56:59], v[136:139], v[188:191], v[56:59]
	v_mfma_f32_16x16x32_bf16 v[44:47], v[128:131], v[200:203], v[44:47]
	v_mfma_f32_16x16x32_bf16 v[40:43], v[136:139], v[200:203], v[40:43]
	v_mfma_f32_16x16x32_bf16 v[28:31], v[128:131], v[208:211], v[28:31]
	v_mfma_f32_16x16x32_bf16 v[24:27], v[136:139], v[208:211], v[24:27]
	v_mfma_f32_16x16x32_bf16 v[12:15], v[128:131], v[216:219], v[12:15]
	v_mfma_f32_16x16x32_bf16 v[8:11], v[136:139], v[216:219], v[8:11]
	v_mfma_f32_16x16x32_bf16 v[60:63], v[132:135], v[192:195], v[60:63]
	v_mfma_f32_16x16x32_bf16 v[56:59], v[140:143], v[192:195], v[56:59]
	v_mfma_f32_16x16x32_bf16 v[44:47], v[132:135], v[204:207], v[44:47]
	v_mfma_f32_16x16x32_bf16 v[40:43], v[140:143], v[204:207], v[40:43]
	v_mfma_f32_16x16x32_bf16 v[28:31], v[132:135], v[212:215], v[28:31]
	v_mfma_f32_16x16x32_bf16 v[24:27], v[140:143], v[212:215], v[24:27]
	v_mfma_f32_16x16x32_bf16 v[12:15], v[132:135], v[228:231], v[12:15]
	v_mfma_f32_16x16x32_bf16 v[8:11], v[140:143], v[228:231], v[8:11]
	v_mfma_f32_16x16x32_bf16 v[52:55], v[144:147], v[188:191], v[52:55]
	v_mfma_f32_16x16x32_bf16 v[48:51], v[164:167], v[188:191], v[48:51]
	v_mfma_f32_16x16x32_bf16 v[36:39], v[144:147], v[200:203], v[36:39]
	v_mfma_f32_16x16x32_bf16 v[32:35], v[164:167], v[200:203], v[32:35]
	v_mfma_f32_16x16x32_bf16 v[20:23], v[144:147], v[208:211], v[20:23]
	v_mfma_f32_16x16x32_bf16 v[16:19], v[164:167], v[208:211], v[16:19]
	v_mfma_f32_16x16x32_bf16 v[4:7], v[144:147], v[216:219], v[4:7]
	v_mfma_f32_16x16x32_bf16 v[0:3], v[164:167], v[216:219], v[0:3]
	v_mfma_f32_16x16x32_bf16 v[52:55], v[148:151], v[192:195], v[52:55]
	v_mfma_f32_16x16x32_bf16 v[48:51], v[184:187], v[192:195], v[48:51]
	v_mfma_f32_16x16x32_bf16 v[36:39], v[148:151], v[204:207], v[36:39]
	v_mfma_f32_16x16x32_bf16 v[32:35], v[184:187], v[204:207], v[32:35]
	v_mfma_f32_16x16x32_bf16 v[20:23], v[148:151], v[212:215], v[20:23]
	v_mfma_f32_16x16x32_bf16 v[16:19], v[184:187], v[212:215], v[16:19]
	v_mfma_f32_16x16x32_bf16 v[4:7], v[148:151], v[228:231], v[4:7]
	v_mfma_f32_16x16x32_bf16 v[0:3], v[184:187], v[228:231], v[0:3]
	s_barrier
	s_setprio 0
	s_add_i32 s66, s66, 2
	s_add_u32 s64, s64, 0x100
	s_addc_u32 s65, s65, 0
	s_cmp_gt_u32 s66, 13
	s_mov_b64 s[48:49], s[50:51]
	s_cbranch_scc0 .LBB0_776
	s_and_b64 vcc, exec, s[30:31]
	s_cbranch_vccz .LBB0_779
	s_barrier

.Lrestag_863:
	s_add_u32 s62, s60, 0x100
	s_addc_u32 s63, s61, 0
	s_add_i32 s0, 0, 0x10000
	s_cmp_eq_u32 s12, 12
	s_cselect_b32 s67, s23, s63
	s_cselect_b32 s66, s51, s62
	s_cselect_b32 s65, s49, vcc_hi
	s_cselect_b32 s64, s57, vcc_lo
	s_add_i32 s13, 0, 0x14000
	v_add_u32_e32 v64, s0, v228
	v_add_u32_e32 v92, s13, v228
	ds_read_b128 v[48:51], v64
	ds_read_b128 v[52:55], v64 offset:1024
	ds_read_b128 v[60:63], v64 offset:2048
	ds_read_b128 v[64:67], v64 offset:3072
	ds_read_b128 v[72:75], v92
	ds_read_b128 v[80:83], v92 offset:1024
	ds_read_b128 v[84:87], v92 offset:2048
	ds_read_b128 v[92:95], v92 offset:3072
	s_add_i32 m0, s59, 0xc000
	ds_read_b128 v[112:115], v230
	ds_read_b128 v[164:167], v230 offset:1024
	ds_read_b128 v[194:197], v230 offset:2048
	ds_read_b128 v[198:201], v230 offset:3072
	ds_read_b128 v[202:205], v230 offset:4096
	ds_read_b128 v[206:209], v230 offset:5120
	ds_read_b128 v[210:213], v230 offset:6144
	ds_read_b128 v[214:217], v230 offset:7168
	global_load_lds_dwordx4 v190, s[60:61]
	s_add_i32 m0, s59, 0xe000
	s_nop 0
	global_load_lds_dwordx4 v192, s[60:61]
	s_nop 0
	s_waitcnt lgkmcnt(0)
	s_setprio 1
	s_barrier
	v_mfma_f32_16x16x32_bf16 v[160:163], v[48:51], v[112:115], 0
	v_mfma_f32_16x16x32_bf16 v[156:159], v[60:63], v[112:115], 0
	v_mfma_f32_16x16x32_bf16 v[128:131], v[48:51], v[194:197], 0
	v_mfma_f32_16x16x32_bf16 v[124:127], v[60:63], v[194:197], 0
	v_mfma_f32_16x16x32_bf16 v[108:111], v[48:51], v[202:205], 0
	v_mfma_f32_16x16x32_bf16 v[104:107], v[60:63], v[202:205], 0
	v_mfma_f32_16x16x32_bf16 v[100:103], v[48:51], v[210:213], 0
	v_mfma_f32_16x16x32_bf16 v[96:99], v[60:63], v[210:213], 0
	v_mfma_f32_16x16x32_bf16 v[160:163], v[52:55], v[164:167], v[160:163]
	v_mfma_f32_16x16x32_bf16 v[156:159], v[64:67], v[164:167], v[156:159]
	v_mfma_f32_16x16x32_bf16 v[128:131], v[52:55], v[198:201], v[128:131]
	v_mfma_f32_16x16x32_bf16 v[124:127], v[64:67], v[198:201], v[124:127]
	v_mfma_f32_16x16x32_bf16 v[108:111], v[52:55], v[206:209], v[108:111]
	v_mfma_f32_16x16x32_bf16 v[104:107], v[64:67], v[206:209], v[104:107]
	v_mfma_f32_16x16x32_bf16 v[100:103], v[52:55], v[214:217], v[100:103]
	v_mfma_f32_16x16x32_bf16 v[96:99], v[64:67], v[214:217], v[96:99]
	v_mfma_f32_16x16x32_bf16 v[152:155], v[72:75], v[112:115], 0
	v_mfma_f32_16x16x32_bf16 v[120:123], v[72:75], v[194:197], 0
	v_mfma_f32_16x16x32_bf16 v[116:119], v[84:87], v[194:197], 0
	v_mfma_f32_16x16x32_bf16 v[144:147], v[72:75], v[202:205], 0
	v_mfma_f32_16x16x32_bf16 v[140:143], v[84:87], v[202:205], 0
	v_mfma_f32_16x16x32_bf16 v[136:139], v[72:75], v[210:213], 0
	v_mfma_f32_16x16x32_bf16 v[132:135], v[84:87], v[210:213], 0
	v_mfma_f32_16x16x32_bf16 v[152:155], v[80:83], v[164:167], v[152:155]
	v_mfma_f32_16x16x32_bf16 v[112:115], v[84:87], v[112:115], 0
	v_mfma_f32_16x16x32_bf16 v[120:123], v[80:83], v[198:201], v[120:123]
	v_mfma_f32_16x16x32_bf16 v[116:119], v[92:95], v[198:201], v[116:119]
	v_mfma_f32_16x16x32_bf16 v[144:147], v[80:83], v[206:209], v[144:147]
	v_mfma_f32_16x16x32_bf16 v[140:143], v[92:95], v[206:209], v[140:143]
	v_mfma_f32_16x16x32_bf16 v[136:139], v[80:83], v[214:217], v[136:139]
	v_mfma_f32_16x16x32_bf16 v[132:135], v[92:95], v[214:217], v[132:135]
	v_mfma_f32_16x16x32_bf16 v[112:115], v[92:95], v[164:167], v[112:115]
	s_barrier
	s_setprio 0
	s_add_i32 s0, s0, s96
	v_lshl_add_u64 v[218:219], s[64:65], 0, v[170:171]
	s_mov_b32 m0, s0
	ds_read_b128 v[148:151], v230 offset:16384
	ds_read_b128 v[164:167], v230 offset:17408
	ds_read_b128 v[194:197], v230 offset:18432
	ds_read_b128 v[198:201], v230 offset:19456
	ds_read_b128 v[202:205], v230 offset:20480
	ds_read_b128 v[206:209], v230 offset:21504
	ds_read_b128 v[210:213], v230 offset:22528
	ds_read_b128 v[214:217], v230 offset:23552
	global_load_lds_dwordx4 v[218:219], off
	s_add_i32 m0, s0, 0x2000
	s_add_u32 s0, s64, 0x40000
	v_lshl_add_u64 v[232:233], s[64:65], 0, v[188:189]
	s_addc_u32 s1, s65, 0
	s_add_i32 s13, s13, s96
	global_load_lds_dwordx4 v[232:233], off
	s_mov_b32 m0, s13
	v_lshl_add_u64 v[236:237], s[66:67], 0, v[186:187]
	global_load_lds_dwordx4 v170, s[0:1]
	s_add_i32 m0, s13, 0x2000
	s_nop 0
	global_load_lds_dwordx4 v188, s[0:1]
	v_lshl_add_u64 v[234:235], s[66:67], 0, v[184:185]
	s_nop 0
	s_waitcnt lgkmcnt(0)
	s_setprio 1
	s_barrier
	v_mfma_f32_16x16x32_bf16 v[88:91], v[48:51], v[148:151], 0
	v_mfma_f32_16x16x32_bf16 v[76:79], v[60:63], v[148:151], 0
	v_mfma_f32_16x16x32_bf16 v[28:31], v[48:51], v[194:197], 0
	v_mfma_f32_16x16x32_bf16 v[24:27], v[60:63], v[194:197], 0
	v_mfma_f32_16x16x32_bf16 v[12:15], v[48:51], v[202:205], 0
	v_mfma_f32_16x16x32_bf16 v[8:11], v[60:63], v[202:205], 0
	v_mfma_f32_16x16x32_bf16 v[4:7], v[48:51], v[210:213], 0
	v_mfma_f32_16x16x32_bf16 v[0:3], v[60:63], v[210:213], 0
	v_mfma_f32_16x16x32_bf16 v[88:91], v[52:55], v[164:167], v[88:91]
	v_mfma_f32_16x16x32_bf16 v[76:79], v[64:67], v[164:167], v[76:79]
	v_mfma_f32_16x16x32_bf16 v[28:31], v[52:55], v[198:201], v[28:31]
	v_mfma_f32_16x16x32_bf16 v[24:27], v[64:67], v[198:201], v[24:27]
	v_mfma_f32_16x16x32_bf16 v[12:15], v[52:55], v[206:209], v[12:15]
	v_mfma_f32_16x16x32_bf16 v[8:11], v[64:67], v[206:209], v[8:11]
	v_mfma_f32_16x16x32_bf16 v[4:7], v[52:55], v[214:217], v[4:7]
	v_mfma_f32_16x16x32_bf16 v[0:3], v[64:67], v[214:217], v[0:3]
	v_mfma_f32_16x16x32_bf16 v[20:23], v[72:75], v[194:197], 0
	v_mfma_f32_16x16x32_bf16 v[16:19], v[84:87], v[194:197], 0
	v_mfma_f32_16x16x32_bf16 v[44:47], v[72:75], v[202:205], 0
	v_mfma_f32_16x16x32_bf16 v[40:43], v[84:87], v[202:205], 0
	v_mfma_f32_16x16x32_bf16 v[36:39], v[72:75], v[210:213], 0
	v_mfma_f32_16x16x32_bf16 v[32:35], v[84:87], v[210:213], 0
	v_mfma_f32_16x16x32_bf16 v[48:51], v[72:75], v[148:151], 0
	v_mfma_f32_16x16x32_bf16 v[52:55], v[84:87], v[148:151], 0
	v_mfma_f32_16x16x32_bf16 v[20:23], v[80:83], v[198:201], v[20:23]
	v_mfma_f32_16x16x32_bf16 v[16:19], v[92:95], v[198:201], v[16:19]
	v_mfma_f32_16x16x32_bf16 v[44:47], v[80:83], v[206:209], v[44:47]
	v_mfma_f32_16x16x32_bf16 v[40:43], v[92:95], v[206:209], v[40:43]
	v_mfma_f32_16x16x32_bf16 v[36:39], v[80:83], v[214:217], v[36:39]
	v_mfma_f32_16x16x32_bf16 v[32:35], v[92:95], v[214:217], v[32:35]
	v_mfma_f32_16x16x32_bf16 v[48:51], v[80:83], v[164:167], v[48:51]
	v_mfma_f32_16x16x32_bf16 v[52:55], v[92:95], v[164:167], v[52:55]
	s_barrier
	s_setprio 0
	s_add_i32 s13, 0, 0x18000
	s_add_i32 s60, 0, 0x1c000
	v_add_u32_e32 v68, s13, v228
	v_add_u32_e32 v92, s60, v228
	ds_read_b128 v[56:59], v68
	ds_read_b128 v[60:63], v68 offset:1024
	ds_read_b128 v[64:67], v68 offset:2048
	ds_read_b128 v[68:71], v68 offset:3072
	ds_read_b128 v[72:75], v92
	ds_read_b128 v[80:83], v92 offset:1024
	ds_read_b128 v[84:87], v92 offset:2048
	ds_read_b128 v[92:95], v92 offset:3072
	s_add_u32 s0, s66, 0x40000
	s_addc_u32 s1, s67, 0
	s_mov_b32 m0, s39
	ds_read_b128 v[148:151], v230 offset:32768
	ds_read_b128 v[164:167], v230 offset:33792
	ds_read_b128 v[194:197], v230 offset:34816
	ds_read_b128 v[198:201], v230 offset:35840
	ds_read_b128 v[202:205], v230 offset:36864
	ds_read_b128 v[206:209], v230 offset:37888
	ds_read_b128 v[210:213], v230 offset:38912
	ds_read_b128 v[214:217], v230 offset:39936
	global_load_lds_dwordx4 v184, s[0:1]
	s_mov_b32 m0, s76
	s_nop 0
	global_load_lds_dwordx4 v186, s[0:1]
	s_mov_b32 m0, s59
	s_nop 0
	global_load_lds_dwordx4 v[234:235], off
	s_mov_b32 m0, s97
	s_nop 0
	global_load_lds_dwordx4 v[236:237], off
	s_waitcnt vmcnt(8)
	s_waitcnt lgkmcnt(0)
	s_setprio 1
	s_barrier
	v_mfma_f32_16x16x32_bf16 v[160:163], v[56:59], v[148:151], v[160:163]
	v_mfma_f32_16x16x32_bf16 v[156:159], v[64:67], v[148:151], v[156:159]
	v_mfma_f32_16x16x32_bf16 v[128:131], v[56:59], v[194:197], v[128:131]
	v_mfma_f32_16x16x32_bf16 v[124:127], v[64:67], v[194:197], v[124:127]
	v_mfma_f32_16x16x32_bf16 v[108:111], v[56:59], v[202:205], v[108:111]
	v_mfma_f32_16x16x32_bf16 v[104:107], v[64:67], v[202:205], v[104:107]
	v_mfma_f32_16x16x32_bf16 v[100:103], v[56:59], v[210:213], v[100:103]
	v_mfma_f32_16x16x32_bf16 v[96:99], v[64:67], v[210:213], v[96:99]
	v_mfma_f32_16x16x32_bf16 v[160:163], v[60:63], v[164:167], v[160:163]
	v_mfma_f32_16x16x32_bf16 v[156:159], v[68:71], v[164:167], v[156:159]
	v_mfma_f32_16x16x32_bf16 v[128:131], v[60:63], v[198:201], v[128:131]
	v_mfma_f32_16x16x32_bf16 v[124:127], v[68:71], v[198:201], v[124:127]
	v_mfma_f32_16x16x32_bf16 v[108:111], v[60:63], v[206:209], v[108:111]
	v_mfma_f32_16x16x32_bf16 v[104:107], v[68:71], v[206:209], v[104:107]
	v_mfma_f32_16x16x32_bf16 v[100:103], v[60:63], v[214:217], v[100:103]
	v_mfma_f32_16x16x32_bf16 v[96:99], v[68:71], v[214:217], v[96:99]
	v_mfma_f32_16x16x32_bf16 v[112:115], v[84:87], v[148:151], v[112:115]
	v_mfma_f32_16x16x32_bf16 v[152:155], v[72:75], v[148:151], v[152:155]
	v_mfma_f32_16x16x32_bf16 v[148:151], v[92:95], v[164:167], v[112:115]
	v_mfma_f32_16x16x32_bf16 v[112:115], v[72:75], v[194:197], v[120:123]
	v_mfma_f32_16x16x32_bf16 v[120:123], v[80:83], v[198:201], v[112:115]
	v_mfma_f32_16x16x32_bf16 v[112:115], v[84:87], v[194:197], v[116:119]
	v_mfma_f32_16x16x32_bf16 v[116:119], v[92:95], v[198:201], v[112:115]
	v_mfma_f32_16x16x32_bf16 v[112:115], v[72:75], v[202:205], v[144:147]
	v_mfma_f32_16x16x32_bf16 v[144:147], v[80:83], v[206:209], v[112:115]
	v_mfma_f32_16x16x32_bf16 v[112:115], v[84:87], v[202:205], v[140:143]
	v_mfma_f32_16x16x32_bf16 v[140:143], v[92:95], v[206:209], v[112:115]
	v_mfma_f32_16x16x32_bf16 v[112:115], v[72:75], v[210:213], v[136:139]
	v_mfma_f32_16x16x32_bf16 v[136:139], v[80:83], v[214:217], v[112:115]
	v_mfma_f32_16x16x32_bf16 v[112:115], v[84:87], v[210:213], v[132:135]
	v_mfma_f32_16x16x32_bf16 v[152:155], v[80:83], v[164:167], v[152:155]
	v_mfma_f32_16x16x32_bf16 v[132:135], v[92:95], v[214:217], v[112:115]
	s_barrier
	s_setprio 0
	s_add_i32 s0, s13, s96
	v_lshl_add_u64 v[218:219], v[218:219], 0, s[16:17]
	s_mov_b32 m0, s0
	s_nop 0
	ds_read_b128 v[112:115], v230 offset:49152
	ds_read_b128 v[164:167], v230 offset:50176
	ds_read_b128 v[194:197], v230 offset:51200
	ds_read_b128 v[198:201], v230 offset:52224
	ds_read_b128 v[202:205], v230 offset:53248
	ds_read_b128 v[206:209], v230 offset:54272
	ds_read_b128 v[210:213], v230 offset:55296
	ds_read_b128 v[214:217], v230 offset:56320
	global_load_lds_dwordx4 v[218:219], off
	s_add_i32 m0, s0, 0x2000
	s_add_u32 s0, s64, 0x40080
	v_lshl_add_u64 v[218:219], v[232:233], 0, s[16:17]
	s_addc_u32 s1, s65, 0
	s_add_i32 s13, s60, s96
	global_load_lds_dwordx4 v[218:219], off
	s_mov_b32 m0, s13
	s_nop 0
	global_load_lds_dwordx4 v170, s[0:1]
	s_add_i32 m0, s13, 0x2000
	s_nop 0
	global_load_lds_dwordx4 v188, s[0:1]
	v_lshl_add_u64 v[218:219], v[234:235], 0, s[16:17]
	s_mov_b32 m0, s75
	s_nop 0
	global_load_lds_dwordx4 v[218:219], off
	v_lshl_add_u64 v[218:219], v[236:237], 0, s[16:17]
	s_mov_b32 m0, s91
	s_nop 0
	global_load_lds_dwordx4 v[218:219], off
	s_waitcnt vmcnt(6)
	s_waitcnt lgkmcnt(0)
	s_setprio 1
	s_barrier
	v_mfma_f32_16x16x32_bf16 v[88:91], v[56:59], v[112:115], v[88:91]
	v_mfma_f32_16x16x32_bf16 v[76:79], v[64:67], v[112:115], v[76:79]
	v_mfma_f32_16x16x32_bf16 v[28:31], v[56:59], v[194:197], v[28:31]
	v_mfma_f32_16x16x32_bf16 v[24:27], v[64:67], v[194:197], v[24:27]
	v_mfma_f32_16x16x32_bf16 v[12:15], v[56:59], v[202:205], v[12:15]
	v_mfma_f32_16x16x32_bf16 v[8:11], v[64:67], v[202:205], v[8:11]
	v_mfma_f32_16x16x32_bf16 v[4:7], v[56:59], v[210:213], v[4:7]
	v_mfma_f32_16x16x32_bf16 v[0:3], v[64:67], v[210:213], v[0:3]
	v_mfma_f32_16x16x32_bf16 v[88:91], v[60:63], v[164:167], v[88:91]
	v_mfma_f32_16x16x32_bf16 v[76:79], v[68:71], v[164:167], v[76:79]
	v_mfma_f32_16x16x32_bf16 v[28:31], v[60:63], v[198:201], v[28:31]
	v_mfma_f32_16x16x32_bf16 v[24:27], v[68:71], v[198:201], v[24:27]
	v_mfma_f32_16x16x32_bf16 v[12:15], v[60:63], v[206:209], v[12:15]
	v_mfma_f32_16x16x32_bf16 v[8:11], v[68:71], v[206:209], v[8:11]
	v_mfma_f32_16x16x32_bf16 v[4:7], v[60:63], v[214:217], v[4:7]
	v_mfma_f32_16x16x32_bf16 v[0:3], v[68:71], v[214:217], v[0:3]
	v_mfma_f32_16x16x32_bf16 v[48:51], v[72:75], v[112:115], v[48:51]
	v_mfma_f32_16x16x32_bf16 v[68:71], v[80:83], v[164:167], v[48:51]
	v_mfma_f32_16x16x32_bf16 v[48:51], v[84:87], v[112:115], v[52:55]
	v_mfma_f32_16x16x32_bf16 v[20:23], v[72:75], v[194:197], v[20:23]
	v_mfma_f32_16x16x32_bf16 v[16:19], v[84:87], v[194:197], v[16:19]
	v_mfma_f32_16x16x32_bf16 v[44:47], v[72:75], v[202:205], v[44:47]
	v_mfma_f32_16x16x32_bf16 v[40:43], v[84:87], v[202:205], v[40:43]
	v_mfma_f32_16x16x32_bf16 v[36:39], v[72:75], v[210:213], v[36:39]
	v_mfma_f32_16x16x32_bf16 v[32:35], v[84:87], v[210:213], v[32:35]
	v_mfma_f32_16x16x32_bf16 v[56:59], v[92:95], v[164:167], v[48:51]
	v_mfma_f32_16x16x32_bf16 v[20:23], v[80:83], v[198:201], v[20:23]
	v_mfma_f32_16x16x32_bf16 v[16:19], v[92:95], v[198:201], v[16:19]
	v_mfma_f32_16x16x32_bf16 v[44:47], v[80:83], v[206:209], v[44:47]
	v_mfma_f32_16x16x32_bf16 v[40:43], v[92:95], v[206:209], v[40:43]
	v_mfma_f32_16x16x32_bf16 v[36:39], v[80:83], v[214:217], v[36:39]
	v_mfma_f32_16x16x32_bf16 v[32:35], v[92:95], v[214:217], v[32:35]
	s_barrier
	s_setprio 0
	s_add_i32 s12, s12, 2
	s_add_u32 vcc_lo, vcc_lo, 0x100
	s_addc_u32 vcc_hi, vcc_hi, 0
	s_cmp_gt_u32 s12, 13
	s_mov_b64 s[60:61], s[62:63]
.LBB0_863:
	s_add_u32 s62, s60, 0x100
	s_addc_u32 s63, s61, 0
	s_add_i32 s0, 0, 0x10000
	s_cmp_eq_u32 s12, 12
	s_cselect_b32 s67, s23, s63
	s_cselect_b32 s66, s51, s62
	s_cselect_b32 s65, s49, vcc_hi
	s_cselect_b32 s64, s57, vcc_lo
	s_add_i32 s13, 0, 0x14000
	v_add_u32_e32 v64, s0, v228
	v_add_u32_e32 v92, s13, v228
	ds_read_b128 v[48:51], v64
	ds_read_b128 v[52:55], v64 offset:1024
	ds_read_b128 v[60:63], v64 offset:2048
	ds_read_b128 v[64:67], v64 offset:3072
	ds_read_b128 v[72:75], v92
	ds_read_b128 v[80:83], v92 offset:1024
	ds_read_b128 v[84:87], v92 offset:2048
	ds_read_b128 v[92:95], v92 offset:3072
	s_add_i32 m0, s59, 0xc000
	ds_read_b128 v[112:115], v230
	ds_read_b128 v[164:167], v230 offset:1024
	ds_read_b128 v[194:197], v230 offset:2048
	ds_read_b128 v[198:201], v230 offset:3072
	ds_read_b128 v[202:205], v230 offset:4096
	ds_read_b128 v[206:209], v230 offset:5120
	ds_read_b128 v[210:213], v230 offset:6144
	ds_read_b128 v[214:217], v230 offset:7168
	global_load_lds_dwordx4 v190, s[60:61]
	s_add_i32 m0, s59, 0xe000
	s_nop 0
	global_load_lds_dwordx4 v192, s[60:61]
	s_waitcnt vmcnt(8)
	s_waitcnt lgkmcnt(0)
	s_setprio 1
	s_barrier
	v_mfma_f32_16x16x32_bf16 v[160:163], v[48:51], v[112:115], v[160:163]
	v_mfma_f32_16x16x32_bf16 v[156:159], v[60:63], v[112:115], v[156:159]
	v_mfma_f32_16x16x32_bf16 v[128:131], v[48:51], v[194:197], v[128:131]
	v_mfma_f32_16x16x32_bf16 v[124:127], v[60:63], v[194:197], v[124:127]
	v_mfma_f32_16x16x32_bf16 v[108:111], v[48:51], v[202:205], v[108:111]
	v_mfma_f32_16x16x32_bf16 v[104:107], v[60:63], v[202:205], v[104:107]
	v_mfma_f32_16x16x32_bf16 v[100:103], v[48:51], v[210:213], v[100:103]
	v_mfma_f32_16x16x32_bf16 v[96:99], v[60:63], v[210:213], v[96:99]
	v_mfma_f32_16x16x32_bf16 v[160:163], v[52:55], v[164:167], v[160:163]
	v_mfma_f32_16x16x32_bf16 v[156:159], v[64:67], v[164:167], v[156:159]
	v_mfma_f32_16x16x32_bf16 v[128:131], v[52:55], v[198:201], v[128:131]
	v_mfma_f32_16x16x32_bf16 v[124:127], v[64:67], v[198:201], v[124:127]
	v_mfma_f32_16x16x32_bf16 v[108:111], v[52:55], v[206:209], v[108:111]
	v_mfma_f32_16x16x32_bf16 v[104:107], v[64:67], v[206:209], v[104:107]
	v_mfma_f32_16x16x32_bf16 v[100:103], v[52:55], v[214:217], v[100:103]
	v_mfma_f32_16x16x32_bf16 v[96:99], v[64:67], v[214:217], v[96:99]
	v_mfma_f32_16x16x32_bf16 v[152:155], v[72:75], v[112:115], v[152:155]
	v_mfma_f32_16x16x32_bf16 v[120:123], v[72:75], v[194:197], v[120:123]
	v_mfma_f32_16x16x32_bf16 v[116:119], v[84:87], v[194:197], v[116:119]
	v_mfma_f32_16x16x32_bf16 v[144:147], v[72:75], v[202:205], v[144:147]
	v_mfma_f32_16x16x32_bf16 v[140:143], v[84:87], v[202:205], v[140:143]
	v_mfma_f32_16x16x32_bf16 v[136:139], v[72:75], v[210:213], v[136:139]
	v_mfma_f32_16x16x32_bf16 v[132:135], v[84:87], v[210:213], v[132:135]
	v_mfma_f32_16x16x32_bf16 v[152:155], v[80:83], v[164:167], v[152:155]
	v_mfma_f32_16x16x32_bf16 v[112:115], v[84:87], v[112:115], v[148:151]
	v_mfma_f32_16x16x32_bf16 v[120:123], v[80:83], v[198:201], v[120:123]
	v_mfma_f32_16x16x32_bf16 v[116:119], v[92:95], v[198:201], v[116:119]
	v_mfma_f32_16x16x32_bf16 v[144:147], v[80:83], v[206:209], v[144:147]
	v_mfma_f32_16x16x32_bf16 v[140:143], v[92:95], v[206:209], v[140:143]
	v_mfma_f32_16x16x32_bf16 v[136:139], v[80:83], v[214:217], v[136:139]
	v_mfma_f32_16x16x32_bf16 v[132:135], v[92:95], v[214:217], v[132:135]
	v_mfma_f32_16x16x32_bf16 v[112:115], v[92:95], v[164:167], v[112:115]
	s_barrier
	s_setprio 0
	s_add_i32 s0, s0, s96
	v_lshl_add_u64 v[218:219], s[64:65], 0, v[170:171]
	s_mov_b32 m0, s0
	ds_read_b128 v[148:151], v230 offset:16384
	ds_read_b128 v[164:167], v230 offset:17408
	ds_read_b128 v[194:197], v230 offset:18432
	ds_read_b128 v[198:201], v230 offset:19456
	ds_read_b128 v[202:205], v230 offset:20480
	ds_read_b128 v[206:209], v230 offset:21504
	ds_read_b128 v[210:213], v230 offset:22528
	ds_read_b128 v[214:217], v230 offset:23552
	global_load_lds_dwordx4 v[218:219], off
	s_add_i32 m0, s0, 0x2000
	s_add_u32 s0, s64, 0x40000
	v_lshl_add_u64 v[232:233], s[64:65], 0, v[188:189]
	s_addc_u32 s1, s65, 0
	s_add_i32 s13, s13, s96
	global_load_lds_dwordx4 v[232:233], off
	s_mov_b32 m0, s13
	v_lshl_add_u64 v[236:237], s[66:67], 0, v[186:187]
	global_load_lds_dwordx4 v170, s[0:1]
	s_add_i32 m0, s13, 0x2000
	s_nop 0
	global_load_lds_dwordx4 v188, s[0:1]
	v_lshl_add_u64 v[234:235], s[66:67], 0, v[184:185]
	s_waitcnt vmcnt(6)
	s_waitcnt lgkmcnt(0)
	s_setprio 1
	s_barrier
	v_mfma_f32_16x16x32_bf16 v[88:91], v[48:51], v[148:151], v[88:91]
	v_mfma_f32_16x16x32_bf16 v[76:79], v[60:63], v[148:151], v[76:79]
	v_mfma_f32_16x16x32_bf16 v[28:31], v[48:51], v[194:197], v[28:31]
	v_mfma_f32_16x16x32_bf16 v[24:27], v[60:63], v[194:197], v[24:27]
	v_mfma_f32_16x16x32_bf16 v[12:15], v[48:51], v[202:205], v[12:15]
	v_mfma_f32_16x16x32_bf16 v[8:11], v[60:63], v[202:205], v[8:11]
	v_mfma_f32_16x16x32_bf16 v[4:7], v[48:51], v[210:213], v[4:7]
	v_mfma_f32_16x16x32_bf16 v[0:3], v[60:63], v[210:213], v[0:3]
	v_mfma_f32_16x16x32_bf16 v[88:91], v[52:55], v[164:167], v[88:91]
	v_mfma_f32_16x16x32_bf16 v[76:79], v[64:67], v[164:167], v[76:79]
	v_mfma_f32_16x16x32_bf16 v[28:31], v[52:55], v[198:201], v[28:31]
	v_mfma_f32_16x16x32_bf16 v[24:27], v[64:67], v[198:201], v[24:27]
	v_mfma_f32_16x16x32_bf16 v[12:15], v[52:55], v[206:209], v[12:15]
	v_mfma_f32_16x16x32_bf16 v[8:11], v[64:67], v[206:209], v[8:11]
	v_mfma_f32_16x16x32_bf16 v[4:7], v[52:55], v[214:217], v[4:7]
	v_mfma_f32_16x16x32_bf16 v[0:3], v[64:67], v[214:217], v[0:3]
	v_mfma_f32_16x16x32_bf16 v[20:23], v[72:75], v[194:197], v[20:23]
	v_mfma_f32_16x16x32_bf16 v[16:19], v[84:87], v[194:197], v[16:19]
	v_mfma_f32_16x16x32_bf16 v[44:47], v[72:75], v[202:205], v[44:47]
	v_mfma_f32_16x16x32_bf16 v[40:43], v[84:87], v[202:205], v[40:43]
	v_mfma_f32_16x16x32_bf16 v[36:39], v[72:75], v[210:213], v[36:39]
	v_mfma_f32_16x16x32_bf16 v[32:35], v[84:87], v[210:213], v[32:35]
	v_mfma_f32_16x16x32_bf16 v[48:51], v[72:75], v[148:151], v[68:71]
	v_mfma_f32_16x16x32_bf16 v[52:55], v[84:87], v[148:151], v[56:59]
	v_mfma_f32_16x16x32_bf16 v[20:23], v[80:83], v[198:201], v[20:23]
	v_mfma_f32_16x16x32_bf16 v[16:19], v[92:95], v[198:201], v[16:19]
	v_mfma_f32_16x16x32_bf16 v[44:47], v[80:83], v[206:209], v[44:47]
	v_mfma_f32_16x16x32_bf16 v[40:43], v[92:95], v[206:209], v[40:43]
	v_mfma_f32_16x16x32_bf16 v[36:39], v[80:83], v[214:217], v[36:39]
	v_mfma_f32_16x16x32_bf16 v[32:35], v[92:95], v[214:217], v[32:35]
	v_mfma_f32_16x16x32_bf16 v[48:51], v[80:83], v[164:167], v[48:51]
	v_mfma_f32_16x16x32_bf16 v[52:55], v[92:95], v[164:167], v[52:55]
	s_barrier
	s_setprio 0
	s_add_i32 s13, 0, 0x18000
	s_add_i32 s60, 0, 0x1c000
	v_add_u32_e32 v68, s13, v228
	v_add_u32_e32 v92, s60, v228
	ds_read_b128 v[56:59], v68
	ds_read_b128 v[60:63], v68 offset:1024
	ds_read_b128 v[64:67], v68 offset:2048
	ds_read_b128 v[68:71], v68 offset:3072
	ds_read_b128 v[72:75], v92
	ds_read_b128 v[80:83], v92 offset:1024
	ds_read_b128 v[84:87], v92 offset:2048
	ds_read_b128 v[92:95], v92 offset:3072
	s_add_u32 s0, s66, 0x40000
	s_addc_u32 s1, s67, 0
	s_mov_b32 m0, s39
	ds_read_b128 v[148:151], v230 offset:32768
	ds_read_b128 v[164:167], v230 offset:33792
	ds_read_b128 v[194:197], v230 offset:34816
	ds_read_b128 v[198:201], v230 offset:35840
	ds_read_b128 v[202:205], v230 offset:36864
	ds_read_b128 v[206:209], v230 offset:37888
	ds_read_b128 v[210:213], v230 offset:38912
	ds_read_b128 v[214:217], v230 offset:39936
	global_load_lds_dwordx4 v184, s[0:1]
	s_mov_b32 m0, s76
	s_nop 0
	global_load_lds_dwordx4 v186, s[0:1]
	s_mov_b32 m0, s59
	s_nop 0
	global_load_lds_dwordx4 v[234:235], off
	s_mov_b32 m0, s97
	s_nop 0
	global_load_lds_dwordx4 v[236:237], off
	s_waitcnt vmcnt(8)
	s_waitcnt lgkmcnt(0)
	s_setprio 1
	s_barrier
	v_mfma_f32_16x16x32_bf16 v[160:163], v[56:59], v[148:151], v[160:163]
	v_mfma_f32_16x16x32_bf16 v[156:159], v[64:67], v[148:151], v[156:159]
	v_mfma_f32_16x16x32_bf16 v[128:131], v[56:59], v[194:197], v[128:131]
	v_mfma_f32_16x16x32_bf16 v[124:127], v[64:67], v[194:197], v[124:127]
	v_mfma_f32_16x16x32_bf16 v[108:111], v[56:59], v[202:205], v[108:111]
	v_mfma_f32_16x16x32_bf16 v[104:107], v[64:67], v[202:205], v[104:107]
	v_mfma_f32_16x16x32_bf16 v[100:103], v[56:59], v[210:213], v[100:103]
	v_mfma_f32_16x16x32_bf16 v[96:99], v[64:67], v[210:213], v[96:99]
	v_mfma_f32_16x16x32_bf16 v[160:163], v[60:63], v[164:167], v[160:163]
	v_mfma_f32_16x16x32_bf16 v[156:159], v[68:71], v[164:167], v[156:159]
	v_mfma_f32_16x16x32_bf16 v[128:131], v[60:63], v[198:201], v[128:131]
	v_mfma_f32_16x16x32_bf16 v[124:127], v[68:71], v[198:201], v[124:127]
	v_mfma_f32_16x16x32_bf16 v[108:111], v[60:63], v[206:209], v[108:111]
	v_mfma_f32_16x16x32_bf16 v[104:107], v[68:71], v[206:209], v[104:107]
	v_mfma_f32_16x16x32_bf16 v[100:103], v[60:63], v[214:217], v[100:103]
	v_mfma_f32_16x16x32_bf16 v[96:99], v[68:71], v[214:217], v[96:99]
	v_mfma_f32_16x16x32_bf16 v[112:115], v[84:87], v[148:151], v[112:115]
	v_mfma_f32_16x16x32_bf16 v[152:155], v[72:75], v[148:151], v[152:155]
	v_mfma_f32_16x16x32_bf16 v[148:151], v[92:95], v[164:167], v[112:115]
	v_mfma_f32_16x16x32_bf16 v[112:115], v[72:75], v[194:197], v[120:123]
	v_mfma_f32_16x16x32_bf16 v[120:123], v[80:83], v[198:201], v[112:115]
	v_mfma_f32_16x16x32_bf16 v[112:115], v[84:87], v[194:197], v[116:119]
	v_mfma_f32_16x16x32_bf16 v[116:119], v[92:95], v[198:201], v[112:115]
	v_mfma_f32_16x16x32_bf16 v[112:115], v[72:75], v[202:205], v[144:147]
	v_mfma_f32_16x16x32_bf16 v[144:147], v[80:83], v[206:209], v[112:115]
	v_mfma_f32_16x16x32_bf16 v[112:115], v[84:87], v[202:205], v[140:143]
	v_mfma_f32_16x16x32_bf16 v[140:143], v[92:95], v[206:209], v[112:115]
	v_mfma_f32_16x16x32_bf16 v[112:115], v[72:75], v[210:213], v[136:139]
	v_mfma_f32_16x16x32_bf16 v[136:139], v[80:83], v[214:217], v[112:115]
	v_mfma_f32_16x16x32_bf16 v[112:115], v[84:87], v[210:213], v[132:135]
	v_mfma_f32_16x16x32_bf16 v[152:155], v[80:83], v[164:167], v[152:155]
	v_mfma_f32_16x16x32_bf16 v[132:135], v[92:95], v[214:217], v[112:115]
	s_barrier
	s_setprio 0
	s_add_i32 s0, s13, s96
	v_lshl_add_u64 v[218:219], v[218:219], 0, s[16:17]
	s_mov_b32 m0, s0
	s_nop 0
	ds_read_b128 v[112:115], v230 offset:49152
	ds_read_b128 v[164:167], v230 offset:50176
	ds_read_b128 v[194:197], v230 offset:51200
	ds_read_b128 v[198:201], v230 offset:52224
	ds_read_b128 v[202:205], v230 offset:53248
	ds_read_b128 v[206:209], v230 offset:54272
	ds_read_b128 v[210:213], v230 offset:55296
	ds_read_b128 v[214:217], v230 offset:56320
	global_load_lds_dwordx4 v[218:219], off
	s_add_i32 m0, s0, 0x2000
	s_add_u32 s0, s64, 0x40080
	v_lshl_add_u64 v[218:219], v[232:233], 0, s[16:17]
	s_addc_u32 s1, s65, 0
	s_add_i32 s13, s60, s96
	global_load_lds_dwordx4 v[218:219], off
	s_mov_b32 m0, s13
	s_nop 0
	global_load_lds_dwordx4 v170, s[0:1]
	s_add_i32 m0, s13, 0x2000
	s_nop 0
	global_load_lds_dwordx4 v188, s[0:1]
	v_lshl_add_u64 v[218:219], v[234:235], 0, s[16:17]
	s_mov_b32 m0, s75
	s_nop 0
	global_load_lds_dwordx4 v[218:219], off
	v_lshl_add_u64 v[218:219], v[236:237], 0, s[16:17]
	s_mov_b32 m0, s91
	s_nop 0
	global_load_lds_dwordx4 v[218:219], off
	s_waitcnt vmcnt(6)
	s_waitcnt lgkmcnt(0)
	s_setprio 1
	s_barrier
	v_mfma_f32_16x16x32_bf16 v[88:91], v[56:59], v[112:115], v[88:91]
	v_mfma_f32_16x16x32_bf16 v[76:79], v[64:67], v[112:115], v[76:79]
	v_mfma_f32_16x16x32_bf16 v[28:31], v[56:59], v[194:197], v[28:31]
	v_mfma_f32_16x16x32_bf16 v[24:27], v[64:67], v[194:197], v[24:27]
	v_mfma_f32_16x16x32_bf16 v[12:15], v[56:59], v[202:205], v[12:15]
	v_mfma_f32_16x16x32_bf16 v[8:11], v[64:67], v[202:205], v[8:11]
	v_mfma_f32_16x16x32_bf16 v[4:7], v[56:59], v[210:213], v[4:7]
	v_mfma_f32_16x16x32_bf16 v[0:3], v[64:67], v[210:213], v[0:3]
	v_mfma_f32_16x16x32_bf16 v[88:91], v[60:63], v[164:167], v[88:91]
	v_mfma_f32_16x16x32_bf16 v[76:79], v[68:71], v[164:167], v[76:79]
	v_mfma_f32_16x16x32_bf16 v[28:31], v[60:63], v[198:201], v[28:31]
	v_mfma_f32_16x16x32_bf16 v[24:27], v[68:71], v[198:201], v[24:27]
	v_mfma_f32_16x16x32_bf16 v[12:15], v[60:63], v[206:209], v[12:15]
	v_mfma_f32_16x16x32_bf16 v[8:11], v[68:71], v[206:209], v[8:11]
	v_mfma_f32_16x16x32_bf16 v[4:7], v[60:63], v[214:217], v[4:7]
	v_mfma_f32_16x16x32_bf16 v[0:3], v[68:71], v[214:217], v[0:3]
	v_mfma_f32_16x16x32_bf16 v[48:51], v[72:75], v[112:115], v[48:51]
	v_mfma_f32_16x16x32_bf16 v[68:71], v[80:83], v[164:167], v[48:51]
	v_mfma_f32_16x16x32_bf16 v[48:51], v[84:87], v[112:115], v[52:55]
	v_mfma_f32_16x16x32_bf16 v[20:23], v[72:75], v[194:197], v[20:23]
	v_mfma_f32_16x16x32_bf16 v[16:19], v[84:87], v[194:197], v[16:19]
	v_mfma_f32_16x16x32_bf16 v[44:47], v[72:75], v[202:205], v[44:47]
	v_mfma_f32_16x16x32_bf16 v[40:43], v[84:87], v[202:205], v[40:43]
	v_mfma_f32_16x16x32_bf16 v[36:39], v[72:75], v[210:213], v[36:39]
	v_mfma_f32_16x16x32_bf16 v[32:35], v[84:87], v[210:213], v[32:35]
	v_mfma_f32_16x16x32_bf16 v[56:59], v[92:95], v[164:167], v[48:51]
	v_mfma_f32_16x16x32_bf16 v[20:23], v[80:83], v[198:201], v[20:23]
	v_mfma_f32_16x16x32_bf16 v[16:19], v[92:95], v[198:201], v[16:19]
	v_mfma_f32_16x16x32_bf16 v[44:47], v[80:83], v[206:209], v[44:47]
	v_mfma_f32_16x16x32_bf16 v[40:43], v[92:95], v[206:209], v[40:43]
	v_mfma_f32_16x16x32_bf16 v[36:39], v[80:83], v[214:217], v[36:39]
	v_mfma_f32_16x16x32_bf16 v[32:35], v[92:95], v[214:217], v[32:35]
	s_barrier
	s_setprio 0
	s_add_i32 s12, s12, 2
	s_add_u32 vcc_lo, vcc_lo, 0x100
	s_addc_u32 vcc_hi, vcc_hi, 0
	s_cmp_gt_u32 s12, 13
	s_mov_b64 s[60:61], s[62:63]
	s_cbranch_scc0 .LBB0_863
	s_and_b64 vcc, exec, s[42:43]
	s_cbranch_vccz .LBB0_866
	s_barrier

.Lrestag_1029:
	s_add_u32 s34, s30, 0x100
	s_addc_u32 s35, s31, 0
	s_add_i32 s0, 0, 0x10000
	s_cmp_eq_u32 s12, 40
	s_cselect_b32 s41, s7, s35
	s_cselect_b32 s40, s6, s34
	v_add_u32_e32 v150, s0, v153
	s_cselect_b32 s37, s27, s55
	s_cselect_b32 s36, s26, s54
	s_add_i32 s13, 0, 0x14000
	ds_read_b128 v[128:131], v150
	ds_read_b128 v[146:149], v150 offset:1024
	ds_read_b128 v[156:159], v150 offset:2048
	ds_read_b128 v[160:163], v150 offset:3072
	v_add_u32_e32 v150, s13, v153
	ds_read_b128 v[164:167], v150
	ds_read_b128 v[184:187], v150 offset:1024
	ds_read_b128 v[188:191], v150 offset:2048
	ds_read_b128 v[192:195], v150 offset:3072
	s_add_i32 m0, s43, 0xc000
	ds_read_b128 v[196:199], v154
	ds_read_b128 v[200:203], v154 offset:1024
	ds_read_b128 v[204:207], v154 offset:2048
	ds_read_b128 v[208:211], v154 offset:3072
	ds_read_b128 v[212:215], v154 offset:4096
	ds_read_b128 v[216:219], v154 offset:5120
	ds_read_b128 v[228:231], v154 offset:6144
	ds_read_b128 v[232:235], v154 offset:7168
	global_load_lds_dwordx4 v142, s[30:31]
	s_add_i32 m0, s43, 0xe000
	s_nop 0
	global_load_lds_dwordx4 v144, s[30:31]
	s_nop 0
	s_waitcnt lgkmcnt(0)
	s_setprio 1
	s_barrier
	v_mfma_f32_16x16x32_bf16 v[124:127], v[128:131], v[196:199], 0
	v_mfma_f32_16x16x32_bf16 v[120:123], v[156:159], v[196:199], 0
	v_mfma_f32_16x16x32_bf16 v[112:115], v[128:131], v[204:207], 0
	v_mfma_f32_16x16x32_bf16 v[104:107], v[156:159], v[204:207], 0
	v_mfma_f32_16x16x32_bf16 v[96:99], v[128:131], v[212:215], 0
	v_mfma_f32_16x16x32_bf16 v[88:91], v[156:159], v[212:215], 0
	v_mfma_f32_16x16x32_bf16 v[80:83], v[128:131], v[228:231], 0
	v_mfma_f32_16x16x32_bf16 v[72:75], v[156:159], v[228:231], 0
	v_mfma_f32_16x16x32_bf16 v[124:127], v[146:149], v[200:203], v[124:127]
	v_mfma_f32_16x16x32_bf16 v[120:123], v[160:163], v[200:203], v[120:123]
	v_mfma_f32_16x16x32_bf16 v[112:115], v[146:149], v[208:211], v[112:115]
	v_mfma_f32_16x16x32_bf16 v[104:107], v[160:163], v[208:211], v[104:107]
	v_mfma_f32_16x16x32_bf16 v[96:99], v[146:149], v[216:219], v[96:99]
	v_mfma_f32_16x16x32_bf16 v[88:91], v[160:163], v[216:219], v[88:91]
	v_mfma_f32_16x16x32_bf16 v[80:83], v[146:149], v[232:235], v[80:83]
	v_mfma_f32_16x16x32_bf16 v[72:75], v[160:163], v[232:235], v[72:75]
	v_mfma_f32_16x16x32_bf16 v[116:119], v[164:167], v[196:199], 0
	v_mfma_f32_16x16x32_bf16 v[108:111], v[188:191], v[196:199], 0
	v_mfma_f32_16x16x32_bf16 v[100:103], v[164:167], v[204:207], 0
	v_mfma_f32_16x16x32_bf16 v[92:95], v[188:191], v[204:207], 0
	v_mfma_f32_16x16x32_bf16 v[84:87], v[164:167], v[212:215], 0
	v_mfma_f32_16x16x32_bf16 v[76:79], v[188:191], v[212:215], 0
	v_mfma_f32_16x16x32_bf16 v[68:71], v[164:167], v[228:231], 0
	v_mfma_f32_16x16x32_bf16 v[64:67], v[188:191], v[228:231], 0
	v_mfma_f32_16x16x32_bf16 v[116:119], v[184:187], v[200:203], v[116:119]
	v_mfma_f32_16x16x32_bf16 v[108:111], v[192:195], v[200:203], v[108:111]
	v_mfma_f32_16x16x32_bf16 v[100:103], v[184:187], v[208:211], v[100:103]
	v_mfma_f32_16x16x32_bf16 v[92:95], v[192:195], v[208:211], v[92:95]
	v_mfma_f32_16x16x32_bf16 v[84:87], v[184:187], v[216:219], v[84:87]
	v_mfma_f32_16x16x32_bf16 v[76:79], v[192:195], v[216:219], v[76:79]
	v_mfma_f32_16x16x32_bf16 v[68:71], v[184:187], v[232:235], v[68:71]
	v_mfma_f32_16x16x32_bf16 v[64:67], v[192:195], v[232:235], v[64:67]
	s_barrier
	s_setprio 0
	s_add_i32 s0, s0, s42
	v_lshl_add_u64 v[150:151], s[36:37], 0, v[170:171]
	s_mov_b32 m0, s0
	ds_read_b128 v[196:199], v154 offset:16384
	ds_read_b128 v[200:203], v154 offset:17408
	ds_read_b128 v[204:207], v154 offset:18432
	ds_read_b128 v[208:211], v154 offset:19456
	ds_read_b128 v[212:215], v154 offset:20480
	ds_read_b128 v[216:219], v154 offset:21504
	ds_read_b128 v[228:231], v154 offset:22528
	ds_read_b128 v[232:235], v154 offset:23552
	global_load_lds_dwordx4 v[150:151], off
	s_add_i32 m0, s0, 0x2000
	s_add_u32 s0, s36, 0xb0000
	v_lshl_add_u64 v[236:237], s[36:37], 0, v[136:137]
	s_addc_u32 s1, s37, 0
	s_add_i32 s13, s13, s42
	global_load_lds_dwordx4 v[236:237], off
	s_mov_b32 m0, s13
	v_lshl_add_u64 v[240:241], s[40:41], 0, v[134:135]
	global_load_lds_dwordx4 v170, s[0:1]
	s_add_i32 m0, s13, 0x2000
	s_nop 0
	global_load_lds_dwordx4 v136, s[0:1]
	v_lshl_add_u64 v[238:239], s[40:41], 0, v[132:133]
	s_nop 0
	s_waitcnt lgkmcnt(0)
	s_setprio 1
	s_barrier
	v_mfma_f32_16x16x32_bf16 v[60:63], v[128:131], v[196:199], 0
	v_mfma_f32_16x16x32_bf16 v[56:59], v[156:159], v[196:199], 0
	v_mfma_f32_16x16x32_bf16 v[48:51], v[128:131], v[204:207], 0
	v_mfma_f32_16x16x32_bf16 v[40:43], v[156:159], v[204:207], 0
	v_mfma_f32_16x16x32_bf16 v[32:35], v[128:131], v[212:215], 0
	v_mfma_f32_16x16x32_bf16 v[24:27], v[156:159], v[212:215], 0
	v_mfma_f32_16x16x32_bf16 v[16:19], v[128:131], v[228:231], 0
	v_mfma_f32_16x16x32_bf16 v[8:11], v[156:159], v[228:231], 0
	v_mfma_f32_16x16x32_bf16 v[60:63], v[146:149], v[200:203], v[60:63]
	v_mfma_f32_16x16x32_bf16 v[56:59], v[160:163], v[200:203], v[56:59]
	v_mfma_f32_16x16x32_bf16 v[48:51], v[146:149], v[208:211], v[48:51]
	v_mfma_f32_16x16x32_bf16 v[40:43], v[160:163], v[208:211], v[40:43]
	v_mfma_f32_16x16x32_bf16 v[32:35], v[146:149], v[216:219], v[32:35]
	v_mfma_f32_16x16x32_bf16 v[24:27], v[160:163], v[216:219], v[24:27]
	v_mfma_f32_16x16x32_bf16 v[16:19], v[146:149], v[232:235], v[16:19]
	v_mfma_f32_16x16x32_bf16 v[8:11], v[160:163], v[232:235], v[8:11]
	v_mfma_f32_16x16x32_bf16 v[52:55], v[164:167], v[196:199], 0
	v_mfma_f32_16x16x32_bf16 v[44:47], v[188:191], v[196:199], 0
	v_mfma_f32_16x16x32_bf16 v[36:39], v[164:167], v[204:207], 0
	v_mfma_f32_16x16x32_bf16 v[28:31], v[188:191], v[204:207], 0
	v_mfma_f32_16x16x32_bf16 v[20:23], v[164:167], v[212:215], 0
	v_mfma_f32_16x16x32_bf16 v[12:15], v[188:191], v[212:215], 0
	v_mfma_f32_16x16x32_bf16 v[4:7], v[164:167], v[228:231], 0
	v_mfma_f32_16x16x32_bf16 v[0:3], v[188:191], v[228:231], 0
	v_mfma_f32_16x16x32_bf16 v[52:55], v[184:187], v[200:203], v[52:55]
	v_mfma_f32_16x16x32_bf16 v[44:47], v[192:195], v[200:203], v[44:47]
	v_mfma_f32_16x16x32_bf16 v[36:39], v[184:187], v[208:211], v[36:39]
	v_mfma_f32_16x16x32_bf16 v[28:31], v[192:195], v[208:211], v[28:31]
	v_mfma_f32_16x16x32_bf16 v[20:23], v[184:187], v[216:219], v[20:23]
	v_mfma_f32_16x16x32_bf16 v[12:15], v[192:195], v[216:219], v[12:15]
	v_mfma_f32_16x16x32_bf16 v[4:7], v[184:187], v[232:235], v[4:7]
	v_mfma_f32_16x16x32_bf16 v[0:3], v[192:195], v[232:235], v[0:3]
	s_barrier
	s_setprio 0
	s_add_i32 s13, 0, 0x18000
	v_add_u32_e32 v155, s13, v153
	s_add_i32 s30, 0, 0x1c000
	ds_read_b128 v[128:131], v155
	ds_read_b128 v[146:149], v155 offset:1024
	ds_read_b128 v[156:159], v155 offset:2048
	ds_read_b128 v[160:163], v155 offset:3072
	v_add_u32_e32 v155, s30, v153
	ds_read_b128 v[164:167], v155
	ds_read_b128 v[184:187], v155 offset:1024
	ds_read_b128 v[188:191], v155 offset:2048
	ds_read_b128 v[192:195], v155 offset:3072
	s_add_u32 s0, s40, 0xb0000
	s_addc_u32 s1, s41, 0
	s_mov_b32 m0, s45
	ds_read_b128 v[196:199], v154 offset:32768
	ds_read_b128 v[200:203], v154 offset:33792
	ds_read_b128 v[204:207], v154 offset:34816
	ds_read_b128 v[208:211], v154 offset:35840
	ds_read_b128 v[212:215], v154 offset:36864
	ds_read_b128 v[216:219], v154 offset:37888
	ds_read_b128 v[228:231], v154 offset:38912
	ds_read_b128 v[232:235], v154 offset:39936
	global_load_lds_dwordx4 v132, s[0:1]
	s_mov_b32 m0, s46
	s_nop 0
	global_load_lds_dwordx4 v134, s[0:1]
	s_mov_b32 m0, s43
	s_nop 0
	global_load_lds_dwordx4 v[238:239], off
	s_mov_b32 m0, s44
	s_nop 0
	global_load_lds_dwordx4 v[240:241], off
	s_waitcnt vmcnt(8)
	s_waitcnt lgkmcnt(0)
	s_setprio 1
	s_barrier
	v_mfma_f32_16x16x32_bf16 v[124:127], v[128:131], v[196:199], v[124:127]
	v_mfma_f32_16x16x32_bf16 v[120:123], v[156:159], v[196:199], v[120:123]
	v_mfma_f32_16x16x32_bf16 v[112:115], v[128:131], v[204:207], v[112:115]
	v_mfma_f32_16x16x32_bf16 v[104:107], v[156:159], v[204:207], v[104:107]
	v_mfma_f32_16x16x32_bf16 v[96:99], v[128:131], v[212:215], v[96:99]
	v_mfma_f32_16x16x32_bf16 v[88:91], v[156:159], v[212:215], v[88:91]
	v_mfma_f32_16x16x32_bf16 v[80:83], v[128:131], v[228:231], v[80:83]
	v_mfma_f32_16x16x32_bf16 v[72:75], v[156:159], v[228:231], v[72:75]
	v_mfma_f32_16x16x32_bf16 v[124:127], v[146:149], v[200:203], v[124:127]
	v_mfma_f32_16x16x32_bf16 v[120:123], v[160:163], v[200:203], v[120:123]
	v_mfma_f32_16x16x32_bf16 v[112:115], v[146:149], v[208:211], v[112:115]
	v_mfma_f32_16x16x32_bf16 v[104:107], v[160:163], v[208:211], v[104:107]
	v_mfma_f32_16x16x32_bf16 v[96:99], v[146:149], v[216:219], v[96:99]
	v_mfma_f32_16x16x32_bf16 v[88:91], v[160:163], v[216:219], v[88:91]
	v_mfma_f32_16x16x32_bf16 v[80:83], v[146:149], v[232:235], v[80:83]
	v_mfma_f32_16x16x32_bf16 v[72:75], v[160:163], v[232:235], v[72:75]
	v_mfma_f32_16x16x32_bf16 v[116:119], v[164:167], v[196:199], v[116:119]
	v_mfma_f32_16x16x32_bf16 v[108:111], v[188:191], v[196:199], v[108:111]
	v_mfma_f32_16x16x32_bf16 v[100:103], v[164:167], v[204:207], v[100:103]
	v_mfma_f32_16x16x32_bf16 v[92:95], v[188:191], v[204:207], v[92:95]
	v_mfma_f32_16x16x32_bf16 v[84:87], v[164:167], v[212:215], v[84:87]
	v_mfma_f32_16x16x32_bf16 v[76:79], v[188:191], v[212:215], v[76:79]
	v_mfma_f32_16x16x32_bf16 v[68:71], v[164:167], v[228:231], v[68:71]
	v_mfma_f32_16x16x32_bf16 v[64:67], v[188:191], v[228:231], v[64:67]
	v_mfma_f32_16x16x32_bf16 v[116:119], v[184:187], v[200:203], v[116:119]
	v_mfma_f32_16x16x32_bf16 v[108:111], v[192:195], v[200:203], v[108:111]
	v_mfma_f32_16x16x32_bf16 v[100:103], v[184:187], v[208:211], v[100:103]
	v_mfma_f32_16x16x32_bf16 v[92:95], v[192:195], v[208:211], v[92:95]
	v_mfma_f32_16x16x32_bf16 v[84:87], v[184:187], v[216:219], v[84:87]
	v_mfma_f32_16x16x32_bf16 v[76:79], v[192:195], v[216:219], v[76:79]
	v_mfma_f32_16x16x32_bf16 v[68:71], v[184:187], v[232:235], v[68:71]
	v_mfma_f32_16x16x32_bf16 v[64:67], v[192:195], v[232:235], v[64:67]
	s_barrier
	s_setprio 0
	s_add_i32 s0, s13, s42
	v_lshl_add_u64 v[150:151], v[150:151], 0, s[16:17]
	s_mov_b32 m0, s0
	ds_read_b128 v[196:199], v154 offset:49152
	ds_read_b128 v[200:203], v154 offset:50176
	ds_read_b128 v[204:207], v154 offset:51200
	ds_read_b128 v[208:211], v154 offset:52224
	ds_read_b128 v[212:215], v154 offset:53248
	ds_read_b128 v[216:219], v154 offset:54272
	ds_read_b128 v[228:231], v154 offset:55296
	ds_read_b128 v[232:235], v154 offset:56320
	global_load_lds_dwordx4 v[150:151], off
	s_add_i32 m0, s0, 0x2000
	s_add_u32 s0, s36, 0xb0080
	v_lshl_add_u64 v[150:151], v[236:237], 0, s[16:17]
	s_addc_u32 s1, s37, 0
	s_add_i32 s13, s30, s42
	global_load_lds_dwordx4 v[150:151], off
	s_mov_b32 m0, s13
	s_nop 0
	global_load_lds_dwordx4 v170, s[0:1]
	s_add_i32 m0, s13, 0x2000
	s_nop 0
	global_load_lds_dwordx4 v136, s[0:1]
	v_lshl_add_u64 v[150:151], v[238:239], 0, s[16:17]
	s_mov_b32 m0, s47
	s_nop 0
	global_load_lds_dwordx4 v[150:151], off
	v_lshl_add_u64 v[150:151], v[240:241], 0, s[16:17]
	s_mov_b32 m0, s48
	s_nop 0
	global_load_lds_dwordx4 v[150:151], off
	s_waitcnt vmcnt(6)
	s_waitcnt lgkmcnt(0)
	s_setprio 1
	s_barrier
	v_mfma_f32_16x16x32_bf16 v[60:63], v[128:131], v[196:199], v[60:63]
	v_mfma_f32_16x16x32_bf16 v[56:59], v[156:159], v[196:199], v[56:59]
	v_mfma_f32_16x16x32_bf16 v[48:51], v[128:131], v[204:207], v[48:51]
	v_mfma_f32_16x16x32_bf16 v[40:43], v[156:159], v[204:207], v[40:43]
	v_mfma_f32_16x16x32_bf16 v[32:35], v[128:131], v[212:215], v[32:35]
	v_mfma_f32_16x16x32_bf16 v[24:27], v[156:159], v[212:215], v[24:27]
	v_mfma_f32_16x16x32_bf16 v[16:19], v[128:131], v[228:231], v[16:19]
	v_mfma_f32_16x16x32_bf16 v[8:11], v[156:159], v[228:231], v[8:11]
	v_mfma_f32_16x16x32_bf16 v[60:63], v[146:149], v[200:203], v[60:63]
	v_mfma_f32_16x16x32_bf16 v[56:59], v[160:163], v[200:203], v[56:59]
	v_mfma_f32_16x16x32_bf16 v[48:51], v[146:149], v[208:211], v[48:51]
	v_mfma_f32_16x16x32_bf16 v[40:43], v[160:163], v[208:211], v[40:43]
	v_mfma_f32_16x16x32_bf16 v[32:35], v[146:149], v[216:219], v[32:35]
	v_mfma_f32_16x16x32_bf16 v[24:27], v[160:163], v[216:219], v[24:27]
	v_mfma_f32_16x16x32_bf16 v[16:19], v[146:149], v[232:235], v[16:19]
	v_mfma_f32_16x16x32_bf16 v[8:11], v[160:163], v[232:235], v[8:11]
	v_mfma_f32_16x16x32_bf16 v[52:55], v[164:167], v[196:199], v[52:55]
	v_mfma_f32_16x16x32_bf16 v[44:47], v[188:191], v[196:199], v[44:47]
	v_mfma_f32_16x16x32_bf16 v[36:39], v[164:167], v[204:207], v[36:39]
	v_mfma_f32_16x16x32_bf16 v[28:31], v[188:191], v[204:207], v[28:31]
	v_mfma_f32_16x16x32_bf16 v[20:23], v[164:167], v[212:215], v[20:23]
	v_mfma_f32_16x16x32_bf16 v[12:15], v[188:191], v[212:215], v[12:15]
	v_mfma_f32_16x16x32_bf16 v[4:7], v[164:167], v[228:231], v[4:7]
	v_mfma_f32_16x16x32_bf16 v[0:3], v[188:191], v[228:231], v[0:3]
	v_mfma_f32_16x16x32_bf16 v[52:55], v[184:187], v[200:203], v[52:55]
	v_mfma_f32_16x16x32_bf16 v[44:47], v[192:195], v[200:203], v[44:47]
	v_mfma_f32_16x16x32_bf16 v[36:39], v[184:187], v[208:211], v[36:39]
	v_mfma_f32_16x16x32_bf16 v[28:31], v[192:195], v[208:211], v[28:31]
	v_mfma_f32_16x16x32_bf16 v[20:23], v[184:187], v[216:219], v[20:23]
	v_mfma_f32_16x16x32_bf16 v[12:15], v[192:195], v[216:219], v[12:15]
	v_mfma_f32_16x16x32_bf16 v[4:7], v[184:187], v[232:235], v[4:7]
	v_mfma_f32_16x16x32_bf16 v[0:3], v[192:195], v[232:235], v[0:3]
	s_barrier
	s_setprio 0
	s_add_i32 s12, s12, 2
	s_add_u32 s54, s54, 0x100
	s_addc_u32 s55, s55, 0
	s_cmp_gt_u32 s12, 41
	s_mov_b64 s[30:31], s[34:35]
.LBB0_1029:
	s_add_u32 s34, s30, 0x100
	s_addc_u32 s35, s31, 0
	s_add_i32 s0, 0, 0x10000
	s_cmp_eq_u32 s12, 40
	s_cselect_b32 s41, s7, s35
	s_cselect_b32 s40, s6, s34
	v_add_u32_e32 v150, s0, v153
	s_cselect_b32 s37, s27, s55
	s_cselect_b32 s36, s26, s54
	s_add_i32 s13, 0, 0x14000
	ds_read_b128 v[128:131], v150
	ds_read_b128 v[146:149], v150 offset:1024
	ds_read_b128 v[156:159], v150 offset:2048
	ds_read_b128 v[160:163], v150 offset:3072
	v_add_u32_e32 v150, s13, v153
	ds_read_b128 v[164:167], v150
	ds_read_b128 v[184:187], v150 offset:1024
	ds_read_b128 v[188:191], v150 offset:2048
	ds_read_b128 v[192:195], v150 offset:3072
	s_add_i32 m0, s43, 0xc000
	ds_read_b128 v[196:199], v154
	ds_read_b128 v[200:203], v154 offset:1024
	ds_read_b128 v[204:207], v154 offset:2048
	ds_read_b128 v[208:211], v154 offset:3072
	ds_read_b128 v[212:215], v154 offset:4096
	ds_read_b128 v[216:219], v154 offset:5120
	ds_read_b128 v[228:231], v154 offset:6144
	ds_read_b128 v[232:235], v154 offset:7168
	global_load_lds_dwordx4 v142, s[30:31]
	s_add_i32 m0, s43, 0xe000
	s_nop 0
	global_load_lds_dwordx4 v144, s[30:31]
	s_waitcnt vmcnt(8)
	s_waitcnt lgkmcnt(0)
	s_setprio 1
	s_barrier
	v_mfma_f32_16x16x32_bf16 v[124:127], v[128:131], v[196:199], v[124:127]
	v_mfma_f32_16x16x32_bf16 v[120:123], v[156:159], v[196:199], v[120:123]
	v_mfma_f32_16x16x32_bf16 v[112:115], v[128:131], v[204:207], v[112:115]
	v_mfma_f32_16x16x32_bf16 v[104:107], v[156:159], v[204:207], v[104:107]
	v_mfma_f32_16x16x32_bf16 v[96:99], v[128:131], v[212:215], v[96:99]
	v_mfma_f32_16x16x32_bf16 v[88:91], v[156:159], v[212:215], v[88:91]
	v_mfma_f32_16x16x32_bf16 v[80:83], v[128:131], v[228:231], v[80:83]
	v_mfma_f32_16x16x32_bf16 v[72:75], v[156:159], v[228:231], v[72:75]
	v_mfma_f32_16x16x32_bf16 v[124:127], v[146:149], v[200:203], v[124:127]
	v_mfma_f32_16x16x32_bf16 v[120:123], v[160:163], v[200:203], v[120:123]
	v_mfma_f32_16x16x32_bf16 v[112:115], v[146:149], v[208:211], v[112:115]
	v_mfma_f32_16x16x32_bf16 v[104:107], v[160:163], v[208:211], v[104:107]
	v_mfma_f32_16x16x32_bf16 v[96:99], v[146:149], v[216:219], v[96:99]
	v_mfma_f32_16x16x32_bf16 v[88:91], v[160:163], v[216:219], v[88:91]
	v_mfma_f32_16x16x32_bf16 v[80:83], v[146:149], v[232:235], v[80:83]
	v_mfma_f32_16x16x32_bf16 v[72:75], v[160:163], v[232:235], v[72:75]
	v_mfma_f32_16x16x32_bf16 v[116:119], v[164:167], v[196:199], v[116:119]
	v_mfma_f32_16x16x32_bf16 v[108:111], v[188:191], v[196:199], v[108:111]
	v_mfma_f32_16x16x32_bf16 v[100:103], v[164:167], v[204:207], v[100:103]
	v_mfma_f32_16x16x32_bf16 v[92:95], v[188:191], v[204:207], v[92:95]
	v_mfma_f32_16x16x32_bf16 v[84:87], v[164:167], v[212:215], v[84:87]
	v_mfma_f32_16x16x32_bf16 v[76:79], v[188:191], v[212:215], v[76:79]
	v_mfma_f32_16x16x32_bf16 v[68:71], v[164:167], v[228:231], v[68:71]
	v_mfma_f32_16x16x32_bf16 v[64:67], v[188:191], v[228:231], v[64:67]
	v_mfma_f32_16x16x32_bf16 v[116:119], v[184:187], v[200:203], v[116:119]
	v_mfma_f32_16x16x32_bf16 v[108:111], v[192:195], v[200:203], v[108:111]
	v_mfma_f32_16x16x32_bf16 v[100:103], v[184:187], v[208:211], v[100:103]
	v_mfma_f32_16x16x32_bf16 v[92:95], v[192:195], v[208:211], v[92:95]
	v_mfma_f32_16x16x32_bf16 v[84:87], v[184:187], v[216:219], v[84:87]
	v_mfma_f32_16x16x32_bf16 v[76:79], v[192:195], v[216:219], v[76:79]
	v_mfma_f32_16x16x32_bf16 v[68:71], v[184:187], v[232:235], v[68:71]
	v_mfma_f32_16x16x32_bf16 v[64:67], v[192:195], v[232:235], v[64:67]
	s_barrier
	s_setprio 0
	s_add_i32 s0, s0, s42
	v_lshl_add_u64 v[150:151], s[36:37], 0, v[170:171]
	s_mov_b32 m0, s0
	ds_read_b128 v[196:199], v154 offset:16384
	ds_read_b128 v[200:203], v154 offset:17408
	ds_read_b128 v[204:207], v154 offset:18432
	ds_read_b128 v[208:211], v154 offset:19456
	ds_read_b128 v[212:215], v154 offset:20480
	ds_read_b128 v[216:219], v154 offset:21504
	ds_read_b128 v[228:231], v154 offset:22528
	ds_read_b128 v[232:235], v154 offset:23552
	global_load_lds_dwordx4 v[150:151], off
	s_add_i32 m0, s0, 0x2000
	s_add_u32 s0, s36, 0xb0000
	v_lshl_add_u64 v[236:237], s[36:37], 0, v[136:137]
	s_addc_u32 s1, s37, 0
	s_add_i32 s13, s13, s42
	global_load_lds_dwordx4 v[236:237], off
	s_mov_b32 m0, s13
	v_lshl_add_u64 v[240:241], s[40:41], 0, v[134:135]
	global_load_lds_dwordx4 v170, s[0:1]
	s_add_i32 m0, s13, 0x2000
	s_nop 0
	global_load_lds_dwordx4 v136, s[0:1]
	v_lshl_add_u64 v[238:239], s[40:41], 0, v[132:133]
	s_waitcnt vmcnt(6)
	s_waitcnt lgkmcnt(0)
	s_setprio 1
	s_barrier
	v_mfma_f32_16x16x32_bf16 v[60:63], v[128:131], v[196:199], v[60:63]
	v_mfma_f32_16x16x32_bf16 v[56:59], v[156:159], v[196:199], v[56:59]
	v_mfma_f32_16x16x32_bf16 v[48:51], v[128:131], v[204:207], v[48:51]
	v_mfma_f32_16x16x32_bf16 v[40:43], v[156:159], v[204:207], v[40:43]
	v_mfma_f32_16x16x32_bf16 v[32:35], v[128:131], v[212:215], v[32:35]
	v_mfma_f32_16x16x32_bf16 v[24:27], v[156:159], v[212:215], v[24:27]
	v_mfma_f32_16x16x32_bf16 v[16:19], v[128:131], v[228:231], v[16:19]
	v_mfma_f32_16x16x32_bf16 v[8:11], v[156:159], v[228:231], v[8:11]
	v_mfma_f32_16x16x32_bf16 v[60:63], v[146:149], v[200:203], v[60:63]
	v_mfma_f32_16x16x32_bf16 v[56:59], v[160:163], v[200:203], v[56:59]
	v_mfma_f32_16x16x32_bf16 v[48:51], v[146:149], v[208:211], v[48:51]
	v_mfma_f32_16x16x32_bf16 v[40:43], v[160:163], v[208:211], v[40:43]
	v_mfma_f32_16x16x32_bf16 v[32:35], v[146:149], v[216:219], v[32:35]
	v_mfma_f32_16x16x32_bf16 v[24:27], v[160:163], v[216:219], v[24:27]
	v_mfma_f32_16x16x32_bf16 v[16:19], v[146:149], v[232:235], v[16:19]
	v_mfma_f32_16x16x32_bf16 v[8:11], v[160:163], v[232:235], v[8:11]
	v_mfma_f32_16x16x32_bf16 v[52:55], v[164:167], v[196:199], v[52:55]
	v_mfma_f32_16x16x32_bf16 v[44:47], v[188:191], v[196:199], v[44:47]
	v_mfma_f32_16x16x32_bf16 v[36:39], v[164:167], v[204:207], v[36:39]
	v_mfma_f32_16x16x32_bf16 v[28:31], v[188:191], v[204:207], v[28:31]
	v_mfma_f32_16x16x32_bf16 v[20:23], v[164:167], v[212:215], v[20:23]
	v_mfma_f32_16x16x32_bf16 v[12:15], v[188:191], v[212:215], v[12:15]
	v_mfma_f32_16x16x32_bf16 v[4:7], v[164:167], v[228:231], v[4:7]
	v_mfma_f32_16x16x32_bf16 v[0:3], v[188:191], v[228:231], v[0:3]
	v_mfma_f32_16x16x32_bf16 v[52:55], v[184:187], v[200:203], v[52:55]
	v_mfma_f32_16x16x32_bf16 v[44:47], v[192:195], v[200:203], v[44:47]
	v_mfma_f32_16x16x32_bf16 v[36:39], v[184:187], v[208:211], v[36:39]
	v_mfma_f32_16x16x32_bf16 v[28:31], v[192:195], v[208:211], v[28:31]
	v_mfma_f32_16x16x32_bf16 v[20:23], v[184:187], v[216:219], v[20:23]
	v_mfma_f32_16x16x32_bf16 v[12:15], v[192:195], v[216:219], v[12:15]
	v_mfma_f32_16x16x32_bf16 v[4:7], v[184:187], v[232:235], v[4:7]
	v_mfma_f32_16x16x32_bf16 v[0:3], v[192:195], v[232:235], v[0:3]
	s_barrier
	s_setprio 0
	s_add_i32 s13, 0, 0x18000
	v_add_u32_e32 v155, s13, v153
	s_add_i32 s30, 0, 0x1c000
	ds_read_b128 v[128:131], v155
	ds_read_b128 v[146:149], v155 offset:1024
	ds_read_b128 v[156:159], v155 offset:2048
	ds_read_b128 v[160:163], v155 offset:3072
	v_add_u32_e32 v155, s30, v153
	ds_read_b128 v[164:167], v155
	ds_read_b128 v[184:187], v155 offset:1024
	ds_read_b128 v[188:191], v155 offset:2048
	ds_read_b128 v[192:195], v155 offset:3072
	s_add_u32 s0, s40, 0xb0000
	s_addc_u32 s1, s41, 0
	s_mov_b32 m0, s45
	ds_read_b128 v[196:199], v154 offset:32768
	ds_read_b128 v[200:203], v154 offset:33792
	ds_read_b128 v[204:207], v154 offset:34816
	ds_read_b128 v[208:211], v154 offset:35840
	ds_read_b128 v[212:215], v154 offset:36864
	ds_read_b128 v[216:219], v154 offset:37888
	ds_read_b128 v[228:231], v154 offset:38912
	ds_read_b128 v[232:235], v154 offset:39936
	global_load_lds_dwordx4 v132, s[0:1]
	s_mov_b32 m0, s46
	s_nop 0
	global_load_lds_dwordx4 v134, s[0:1]
	s_mov_b32 m0, s43
	s_nop 0
	global_load_lds_dwordx4 v[238:239], off
	s_mov_b32 m0, s44
	s_nop 0
	global_load_lds_dwordx4 v[240:241], off
	s_waitcnt vmcnt(8)
	s_waitcnt lgkmcnt(0)
	s_setprio 1
	s_barrier
	v_mfma_f32_16x16x32_bf16 v[124:127], v[128:131], v[196:199], v[124:127]
	v_mfma_f32_16x16x32_bf16 v[120:123], v[156:159], v[196:199], v[120:123]
	v_mfma_f32_16x16x32_bf16 v[112:115], v[128:131], v[204:207], v[112:115]
	v_mfma_f32_16x16x32_bf16 v[104:107], v[156:159], v[204:207], v[104:107]
	v_mfma_f32_16x16x32_bf16 v[96:99], v[128:131], v[212:215], v[96:99]
	v_mfma_f32_16x16x32_bf16 v[88:91], v[156:159], v[212:215], v[88:91]
	v_mfma_f32_16x16x32_bf16 v[80:83], v[128:131], v[228:231], v[80:83]
	v_mfma_f32_16x16x32_bf16 v[72:75], v[156:159], v[228:231], v[72:75]
	v_mfma_f32_16x16x32_bf16 v[124:127], v[146:149], v[200:203], v[124:127]
	v_mfma_f32_16x16x32_bf16 v[120:123], v[160:163], v[200:203], v[120:123]
	v_mfma_f32_16x16x32_bf16 v[112:115], v[146:149], v[208:211], v[112:115]
	v_mfma_f32_16x16x32_bf16 v[104:107], v[160:163], v[208:211], v[104:107]
	v_mfma_f32_16x16x32_bf16 v[96:99], v[146:149], v[216:219], v[96:99]
	v_mfma_f32_16x16x32_bf16 v[88:91], v[160:163], v[216:219], v[88:91]
	v_mfma_f32_16x16x32_bf16 v[80:83], v[146:149], v[232:235], v[80:83]
	v_mfma_f32_16x16x32_bf16 v[72:75], v[160:163], v[232:235], v[72:75]
	v_mfma_f32_16x16x32_bf16 v[116:119], v[164:167], v[196:199], v[116:119]
	v_mfma_f32_16x16x32_bf16 v[108:111], v[188:191], v[196:199], v[108:111]
	v_mfma_f32_16x16x32_bf16 v[100:103], v[164:167], v[204:207], v[100:103]
	v_mfma_f32_16x16x32_bf16 v[92:95], v[188:191], v[204:207], v[92:95]
	v_mfma_f32_16x16x32_bf16 v[84:87], v[164:167], v[212:215], v[84:87]
	v_mfma_f32_16x16x32_bf16 v[76:79], v[188:191], v[212:215], v[76:79]
	v_mfma_f32_16x16x32_bf16 v[68:71], v[164:167], v[228:231], v[68:71]
	v_mfma_f32_16x16x32_bf16 v[64:67], v[188:191], v[228:231], v[64:67]
	v_mfma_f32_16x16x32_bf16 v[116:119], v[184:187], v[200:203], v[116:119]
	v_mfma_f32_16x16x32_bf16 v[108:111], v[192:195], v[200:203], v[108:111]
	v_mfma_f32_16x16x32_bf16 v[100:103], v[184:187], v[208:211], v[100:103]
	v_mfma_f32_16x16x32_bf16 v[92:95], v[192:195], v[208:211], v[92:95]
	v_mfma_f32_16x16x32_bf16 v[84:87], v[184:187], v[216:219], v[84:87]
	v_mfma_f32_16x16x32_bf16 v[76:79], v[192:195], v[216:219], v[76:79]
	v_mfma_f32_16x16x32_bf16 v[68:71], v[184:187], v[232:235], v[68:71]
	v_mfma_f32_16x16x32_bf16 v[64:67], v[192:195], v[232:235], v[64:67]
	s_barrier
	s_setprio 0
	s_add_i32 s0, s13, s42
	v_lshl_add_u64 v[150:151], v[150:151], 0, s[16:17]
	s_mov_b32 m0, s0
	ds_read_b128 v[196:199], v154 offset:49152
	ds_read_b128 v[200:203], v154 offset:50176
	ds_read_b128 v[204:207], v154 offset:51200
	ds_read_b128 v[208:211], v154 offset:52224
	ds_read_b128 v[212:215], v154 offset:53248
	ds_read_b128 v[216:219], v154 offset:54272
	ds_read_b128 v[228:231], v154 offset:55296
	ds_read_b128 v[232:235], v154 offset:56320
	global_load_lds_dwordx4 v[150:151], off
	s_add_i32 m0, s0, 0x2000
	s_add_u32 s0, s36, 0xb0080
	v_lshl_add_u64 v[150:151], v[236:237], 0, s[16:17]
	s_addc_u32 s1, s37, 0
	s_add_i32 s13, s30, s42
	global_load_lds_dwordx4 v[150:151], off
	s_mov_b32 m0, s13
	s_nop 0
	global_load_lds_dwordx4 v170, s[0:1]
	s_add_i32 m0, s13, 0x2000
	s_nop 0
	global_load_lds_dwordx4 v136, s[0:1]
	v_lshl_add_u64 v[150:151], v[238:239], 0, s[16:17]
	s_mov_b32 m0, s47
	s_nop 0
	global_load_lds_dwordx4 v[150:151], off
	v_lshl_add_u64 v[150:151], v[240:241], 0, s[16:17]
	s_mov_b32 m0, s48
	s_nop 0
	global_load_lds_dwordx4 v[150:151], off
	s_waitcnt vmcnt(6)
	s_waitcnt lgkmcnt(0)
	s_setprio 1
	s_barrier
	v_mfma_f32_16x16x32_bf16 v[60:63], v[128:131], v[196:199], v[60:63]
	v_mfma_f32_16x16x32_bf16 v[56:59], v[156:159], v[196:199], v[56:59]
	v_mfma_f32_16x16x32_bf16 v[48:51], v[128:131], v[204:207], v[48:51]
	v_mfma_f32_16x16x32_bf16 v[40:43], v[156:159], v[204:207], v[40:43]
	v_mfma_f32_16x16x32_bf16 v[32:35], v[128:131], v[212:215], v[32:35]
	v_mfma_f32_16x16x32_bf16 v[24:27], v[156:159], v[212:215], v[24:27]
	v_mfma_f32_16x16x32_bf16 v[16:19], v[128:131], v[228:231], v[16:19]
	v_mfma_f32_16x16x32_bf16 v[8:11], v[156:159], v[228:231], v[8:11]
	v_mfma_f32_16x16x32_bf16 v[60:63], v[146:149], v[200:203], v[60:63]
	v_mfma_f32_16x16x32_bf16 v[56:59], v[160:163], v[200:203], v[56:59]
	v_mfma_f32_16x16x32_bf16 v[48:51], v[146:149], v[208:211], v[48:51]
	v_mfma_f32_16x16x32_bf16 v[40:43], v[160:163], v[208:211], v[40:43]
	v_mfma_f32_16x16x32_bf16 v[32:35], v[146:149], v[216:219], v[32:35]
	v_mfma_f32_16x16x32_bf16 v[24:27], v[160:163], v[216:219], v[24:27]
	v_mfma_f32_16x16x32_bf16 v[16:19], v[146:149], v[232:235], v[16:19]
	v_mfma_f32_16x16x32_bf16 v[8:11], v[160:163], v[232:235], v[8:11]
	v_mfma_f32_16x16x32_bf16 v[52:55], v[164:167], v[196:199], v[52:55]
	v_mfma_f32_16x16x32_bf16 v[44:47], v[188:191], v[196:199], v[44:47]
	v_mfma_f32_16x16x32_bf16 v[36:39], v[164:167], v[204:207], v[36:39]
	v_mfma_f32_16x16x32_bf16 v[28:31], v[188:191], v[204:207], v[28:31]
	v_mfma_f32_16x16x32_bf16 v[20:23], v[164:167], v[212:215], v[20:23]
	v_mfma_f32_16x16x32_bf16 v[12:15], v[188:191], v[212:215], v[12:15]
	v_mfma_f32_16x16x32_bf16 v[4:7], v[164:167], v[228:231], v[4:7]
	v_mfma_f32_16x16x32_bf16 v[0:3], v[188:191], v[228:231], v[0:3]
	v_mfma_f32_16x16x32_bf16 v[52:55], v[184:187], v[200:203], v[52:55]
	v_mfma_f32_16x16x32_bf16 v[44:47], v[192:195], v[200:203], v[44:47]
	v_mfma_f32_16x16x32_bf16 v[36:39], v[184:187], v[208:211], v[36:39]
	v_mfma_f32_16x16x32_bf16 v[28:31], v[192:195], v[208:211], v[28:31]
	v_mfma_f32_16x16x32_bf16 v[20:23], v[184:187], v[216:219], v[20:23]
	v_mfma_f32_16x16x32_bf16 v[12:15], v[192:195], v[216:219], v[12:15]
	v_mfma_f32_16x16x32_bf16 v[4:7], v[184:187], v[232:235], v[4:7]
	v_mfma_f32_16x16x32_bf16 v[0:3], v[192:195], v[232:235], v[0:3]
	s_barrier
	s_setprio 0
	s_add_i32 s12, s12, 2
	s_add_u32 s54, s54, 0x100
	s_addc_u32 s55, s55, 0
	s_cmp_gt_u32 s12, 41
	s_mov_b64 s[30:31], s[34:35]
	s_cbranch_scc0 .LBB0_1029
	s_and_b64 vcc, exec, s[24:25]
	s_cbranch_vccz .LBB0_1032
	s_barrier

.Lrestag_1061:
	s_add_u32 s40, s36, 0x100
	s_addc_u32 s41, s37, 0
	s_add_i32 s0, 0, 0x10000
	s_cmp_eq_u32 s12, 40
	s_cselect_b32 s45, s9, s41
	s_cselect_b32 s44, s8, s40
	s_cselect_b32 s43, s35, s59
	s_cselect_b32 s42, s34, s58
	s_add_i32 s13, 0, 0x14000
	v_add_u32_e32 v140, s0, v197
	v_add_u32_e32 v184, s13, v197
	ds_read_b128 v[128:131], v140
	ds_read_b128 v[132:135], v140 offset:1024
	ds_read_b128 v[136:139], v140 offset:2048
	ds_read_b128 v[140:143], v140 offset:3072
	ds_read_b128 v[144:147], v184
	ds_read_b128 v[148:151], v184 offset:1024
	ds_read_b128 v[164:167], v184 offset:2048
	ds_read_b128 v[184:187], v184 offset:3072
	s_add_i32 m0, s47, 0xc000
	ds_read_b128 v[188:191], v198
	ds_read_b128 v[192:195], v198 offset:1024
	ds_read_b128 v[200:203], v198 offset:2048
	ds_read_b128 v[204:207], v198 offset:3072
	ds_read_b128 v[208:211], v198 offset:4096
	ds_read_b128 v[212:215], v198 offset:5120
	ds_read_b128 v[216:219], v198 offset:6144
	ds_read_b128 v[228:231], v198 offset:7168
	global_load_lds_dwordx4 v160, s[36:37]
	s_add_i32 m0, s47, 0xe000
	s_nop 0
	global_load_lds_dwordx4 v162, s[36:37]
	s_nop 0
	s_waitcnt lgkmcnt(0)
	s_setprio 1
	s_barrier
	v_mfma_f32_16x16x32_bf16 v[124:127], v[128:131], v[188:191], 0
	v_mfma_f32_16x16x32_bf16 v[120:123], v[136:139], v[188:191], 0
	v_mfma_f32_16x16x32_bf16 v[108:111], v[128:131], v[200:203], 0
	v_mfma_f32_16x16x32_bf16 v[104:107], v[136:139], v[200:203], 0
	v_mfma_f32_16x16x32_bf16 v[92:95], v[128:131], v[208:211], 0
	v_mfma_f32_16x16x32_bf16 v[88:91], v[136:139], v[208:211], 0
	v_mfma_f32_16x16x32_bf16 v[76:79], v[128:131], v[216:219], 0
	v_mfma_f32_16x16x32_bf16 v[72:75], v[136:139], v[216:219], 0
	v_mfma_f32_16x16x32_bf16 v[124:127], v[132:135], v[192:195], v[124:127]
	v_mfma_f32_16x16x32_bf16 v[120:123], v[140:143], v[192:195], v[120:123]
	v_mfma_f32_16x16x32_bf16 v[108:111], v[132:135], v[204:207], v[108:111]
	v_mfma_f32_16x16x32_bf16 v[104:107], v[140:143], v[204:207], v[104:107]
	v_mfma_f32_16x16x32_bf16 v[92:95], v[132:135], v[212:215], v[92:95]
	v_mfma_f32_16x16x32_bf16 v[88:91], v[140:143], v[212:215], v[88:91]
	v_mfma_f32_16x16x32_bf16 v[76:79], v[132:135], v[228:231], v[76:79]
	v_mfma_f32_16x16x32_bf16 v[72:75], v[140:143], v[228:231], v[72:75]
	v_mfma_f32_16x16x32_bf16 v[116:119], v[144:147], v[188:191], 0
	v_mfma_f32_16x16x32_bf16 v[112:115], v[164:167], v[188:191], 0
	v_mfma_f32_16x16x32_bf16 v[100:103], v[144:147], v[200:203], 0
	v_mfma_f32_16x16x32_bf16 v[96:99], v[164:167], v[200:203], 0
	v_mfma_f32_16x16x32_bf16 v[84:87], v[144:147], v[208:211], 0
	v_mfma_f32_16x16x32_bf16 v[80:83], v[164:167], v[208:211], 0
	v_mfma_f32_16x16x32_bf16 v[68:71], v[144:147], v[216:219], 0
	v_mfma_f32_16x16x32_bf16 v[64:67], v[164:167], v[216:219], 0
	v_mfma_f32_16x16x32_bf16 v[116:119], v[148:151], v[192:195], v[116:119]
	v_mfma_f32_16x16x32_bf16 v[112:115], v[184:187], v[192:195], v[112:115]
	v_mfma_f32_16x16x32_bf16 v[100:103], v[148:151], v[204:207], v[100:103]
	v_mfma_f32_16x16x32_bf16 v[96:99], v[184:187], v[204:207], v[96:99]
	v_mfma_f32_16x16x32_bf16 v[84:87], v[148:151], v[212:215], v[84:87]
	v_mfma_f32_16x16x32_bf16 v[80:83], v[184:187], v[212:215], v[80:83]
	v_mfma_f32_16x16x32_bf16 v[68:71], v[148:151], v[228:231], v[68:71]
	v_mfma_f32_16x16x32_bf16 v[64:67], v[184:187], v[228:231], v[64:67]
	s_barrier
	s_setprio 0
	s_add_i32 s0, s0, s46
	v_lshl_add_u64 v[232:233], s[42:43], 0, v[170:171]
	s_mov_b32 m0, s0
	ds_read_b128 v[188:191], v198 offset:16384
	ds_read_b128 v[192:195], v198 offset:17408
	ds_read_b128 v[200:203], v198 offset:18432
	ds_read_b128 v[204:207], v198 offset:19456
	ds_read_b128 v[208:211], v198 offset:20480
	ds_read_b128 v[212:215], v198 offset:21504
	ds_read_b128 v[216:219], v198 offset:22528
	ds_read_b128 v[228:231], v198 offset:23552
	global_load_lds_dwordx4 v[232:233], off
	s_add_i32 m0, s0, 0x2000
	s_add_u32 s0, s42, 0xb0000
	v_lshl_add_u64 v[234:235], s[42:43], 0, v[156:157]
	s_addc_u32 s1, s43, 0
	s_add_i32 s13, s13, s46
	global_load_lds_dwordx4 v[234:235], off
	s_mov_b32 m0, s13
	v_lshl_add_u64 v[238:239], s[44:45], 0, v[154:155]
	global_load_lds_dwordx4 v170, s[0:1]
	s_add_i32 m0, s13, 0x2000
	s_nop 0
	global_load_lds_dwordx4 v156, s[0:1]
	v_lshl_add_u64 v[236:237], s[44:45], 0, v[152:153]
	s_nop 0
	s_waitcnt lgkmcnt(0)
	s_setprio 1
	s_barrier
	v_mfma_f32_16x16x32_bf16 v[60:63], v[128:131], v[188:191], 0
	v_mfma_f32_16x16x32_bf16 v[56:59], v[136:139], v[188:191], 0
	v_mfma_f32_16x16x32_bf16 v[44:47], v[128:131], v[200:203], 0
	v_mfma_f32_16x16x32_bf16 v[40:43], v[136:139], v[200:203], 0
	v_mfma_f32_16x16x32_bf16 v[28:31], v[128:131], v[208:211], 0
	v_mfma_f32_16x16x32_bf16 v[24:27], v[136:139], v[208:211], 0
	v_mfma_f32_16x16x32_bf16 v[12:15], v[128:131], v[216:219], 0
	v_mfma_f32_16x16x32_bf16 v[8:11], v[136:139], v[216:219], 0
	v_mfma_f32_16x16x32_bf16 v[60:63], v[132:135], v[192:195], v[60:63]
	v_mfma_f32_16x16x32_bf16 v[56:59], v[140:143], v[192:195], v[56:59]
	v_mfma_f32_16x16x32_bf16 v[44:47], v[132:135], v[204:207], v[44:47]
	v_mfma_f32_16x16x32_bf16 v[40:43], v[140:143], v[204:207], v[40:43]
	v_mfma_f32_16x16x32_bf16 v[28:31], v[132:135], v[212:215], v[28:31]
	v_mfma_f32_16x16x32_bf16 v[24:27], v[140:143], v[212:215], v[24:27]
	v_mfma_f32_16x16x32_bf16 v[12:15], v[132:135], v[228:231], v[12:15]
	v_mfma_f32_16x16x32_bf16 v[8:11], v[140:143], v[228:231], v[8:11]
	v_mfma_f32_16x16x32_bf16 v[52:55], v[144:147], v[188:191], 0
	v_mfma_f32_16x16x32_bf16 v[48:51], v[164:167], v[188:191], 0
	v_mfma_f32_16x16x32_bf16 v[36:39], v[144:147], v[200:203], 0
	v_mfma_f32_16x16x32_bf16 v[32:35], v[164:167], v[200:203], 0
	v_mfma_f32_16x16x32_bf16 v[20:23], v[144:147], v[208:211], 0
	v_mfma_f32_16x16x32_bf16 v[16:19], v[164:167], v[208:211], 0
	v_mfma_f32_16x16x32_bf16 v[4:7], v[144:147], v[216:219], 0
	v_mfma_f32_16x16x32_bf16 v[0:3], v[164:167], v[216:219], 0
	v_mfma_f32_16x16x32_bf16 v[52:55], v[148:151], v[192:195], v[52:55]
	v_mfma_f32_16x16x32_bf16 v[48:51], v[184:187], v[192:195], v[48:51]
	v_mfma_f32_16x16x32_bf16 v[36:39], v[148:151], v[204:207], v[36:39]
	v_mfma_f32_16x16x32_bf16 v[32:35], v[184:187], v[204:207], v[32:35]
	v_mfma_f32_16x16x32_bf16 v[20:23], v[148:151], v[212:215], v[20:23]
	v_mfma_f32_16x16x32_bf16 v[16:19], v[184:187], v[212:215], v[16:19]
	v_mfma_f32_16x16x32_bf16 v[4:7], v[148:151], v[228:231], v[4:7]
	v_mfma_f32_16x16x32_bf16 v[0:3], v[184:187], v[228:231], v[0:3]
	s_barrier
	s_setprio 0
	s_add_i32 s13, 0, 0x18000
	s_add_i32 s36, 0, 0x1c000
	v_add_u32_e32 v140, s13, v197
	v_add_u32_e32 v184, s36, v197
	ds_read_b128 v[128:131], v140
	ds_read_b128 v[132:135], v140 offset:1024
	ds_read_b128 v[136:139], v140 offset:2048
	ds_read_b128 v[140:143], v140 offset:3072
	ds_read_b128 v[144:147], v184
	ds_read_b128 v[148:151], v184 offset:1024
	ds_read_b128 v[164:167], v184 offset:2048
	ds_read_b128 v[184:187], v184 offset:3072
	s_add_u32 s0, s44, 0xb0000
	s_addc_u32 s1, s45, 0
	s_mov_b32 m0, s49
	ds_read_b128 v[188:191], v198 offset:32768
	ds_read_b128 v[192:195], v198 offset:33792
	ds_read_b128 v[200:203], v198 offset:34816
	ds_read_b128 v[204:207], v198 offset:35840
	ds_read_b128 v[208:211], v198 offset:36864
	ds_read_b128 v[212:215], v198 offset:37888
	ds_read_b128 v[216:219], v198 offset:38912
	ds_read_b128 v[228:231], v198 offset:39936
	global_load_lds_dwordx4 v152, s[0:1]
	s_mov_b32 m0, s50
	s_nop 0
	global_load_lds_dwordx4 v154, s[0:1]
	s_mov_b32 m0, s47
	s_nop 0
	global_load_lds_dwordx4 v[236:237], off
	s_mov_b32 m0, s48
	s_nop 0
	global_load_lds_dwordx4 v[238:239], off
	s_waitcnt vmcnt(8)
	s_waitcnt lgkmcnt(0)
	s_setprio 1
	s_barrier
	v_mfma_f32_16x16x32_bf16 v[124:127], v[128:131], v[188:191], v[124:127]
	v_mfma_f32_16x16x32_bf16 v[120:123], v[136:139], v[188:191], v[120:123]
	v_mfma_f32_16x16x32_bf16 v[108:111], v[128:131], v[200:203], v[108:111]
	v_mfma_f32_16x16x32_bf16 v[104:107], v[136:139], v[200:203], v[104:107]
	v_mfma_f32_16x16x32_bf16 v[92:95], v[128:131], v[208:211], v[92:95]
	v_mfma_f32_16x16x32_bf16 v[88:91], v[136:139], v[208:211], v[88:91]
	v_mfma_f32_16x16x32_bf16 v[76:79], v[128:131], v[216:219], v[76:79]
	v_mfma_f32_16x16x32_bf16 v[72:75], v[136:139], v[216:219], v[72:75]
	v_mfma_f32_16x16x32_bf16 v[124:127], v[132:135], v[192:195], v[124:127]
	v_mfma_f32_16x16x32_bf16 v[120:123], v[140:143], v[192:195], v[120:123]
	v_mfma_f32_16x16x32_bf16 v[108:111], v[132:135], v[204:207], v[108:111]
	v_mfma_f32_16x16x32_bf16 v[104:107], v[140:143], v[204:207], v[104:107]
	v_mfma_f32_16x16x32_bf16 v[92:95], v[132:135], v[212:215], v[92:95]
	v_mfma_f32_16x16x32_bf16 v[88:91], v[140:143], v[212:215], v[88:91]
	v_mfma_f32_16x16x32_bf16 v[76:79], v[132:135], v[228:231], v[76:79]
	v_mfma_f32_16x16x32_bf16 v[72:75], v[140:143], v[228:231], v[72:75]
	v_mfma_f32_16x16x32_bf16 v[116:119], v[144:147], v[188:191], v[116:119]
	v_mfma_f32_16x16x32_bf16 v[112:115], v[164:167], v[188:191], v[112:115]
	v_mfma_f32_16x16x32_bf16 v[100:103], v[144:147], v[200:203], v[100:103]
	v_mfma_f32_16x16x32_bf16 v[96:99], v[164:167], v[200:203], v[96:99]
	v_mfma_f32_16x16x32_bf16 v[84:87], v[144:147], v[208:211], v[84:87]
	v_mfma_f32_16x16x32_bf16 v[80:83], v[164:167], v[208:211], v[80:83]
	v_mfma_f32_16x16x32_bf16 v[68:71], v[144:147], v[216:219], v[68:71]
	v_mfma_f32_16x16x32_bf16 v[64:67], v[164:167], v[216:219], v[64:67]
	v_mfma_f32_16x16x32_bf16 v[116:119], v[148:151], v[192:195], v[116:119]
	v_mfma_f32_16x16x32_bf16 v[112:115], v[184:187], v[192:195], v[112:115]
	v_mfma_f32_16x16x32_bf16 v[100:103], v[148:151], v[204:207], v[100:103]
	v_mfma_f32_16x16x32_bf16 v[96:99], v[184:187], v[204:207], v[96:99]
	v_mfma_f32_16x16x32_bf16 v[84:87], v[148:151], v[212:215], v[84:87]
	v_mfma_f32_16x16x32_bf16 v[80:83], v[184:187], v[212:215], v[80:83]
	v_mfma_f32_16x16x32_bf16 v[68:71], v[148:151], v[228:231], v[68:71]
	v_mfma_f32_16x16x32_bf16 v[64:67], v[184:187], v[228:231], v[64:67]
	s_barrier
	s_setprio 0
	s_add_i32 s0, s13, s46
	v_lshl_add_u64 v[232:233], v[232:233], 0, s[16:17]
	s_mov_b32 m0, s0
	ds_read_b128 v[188:191], v198 offset:49152
	ds_read_b128 v[192:195], v198 offset:50176
	ds_read_b128 v[200:203], v198 offset:51200
	ds_read_b128 v[204:207], v198 offset:52224
	ds_read_b128 v[208:211], v198 offset:53248
	ds_read_b128 v[212:215], v198 offset:54272
	ds_read_b128 v[216:219], v198 offset:55296
	ds_read_b128 v[228:231], v198 offset:56320
	global_load_lds_dwordx4 v[232:233], off
	s_add_i32 m0, s0, 0x2000
	s_add_u32 s0, s42, 0xb0080
	v_lshl_add_u64 v[232:233], v[234:235], 0, s[16:17]
	s_addc_u32 s1, s43, 0
	s_add_i32 s13, s36, s46
	global_load_lds_dwordx4 v[232:233], off
	s_mov_b32 m0, s13
	s_nop 0
	global_load_lds_dwordx4 v170, s[0:1]
	s_add_i32 m0, s13, 0x2000
	s_nop 0
	global_load_lds_dwordx4 v156, s[0:1]
	v_lshl_add_u64 v[232:233], v[236:237], 0, s[16:17]
	s_mov_b32 m0, s51
	s_nop 0
	global_load_lds_dwordx4 v[232:233], off
	v_lshl_add_u64 v[232:233], v[238:239], 0, s[16:17]
	s_mov_b32 m0, s52
	s_nop 0
	global_load_lds_dwordx4 v[232:233], off
	s_waitcnt vmcnt(6)
	s_waitcnt lgkmcnt(0)
	s_setprio 1
	s_barrier
	v_mfma_f32_16x16x32_bf16 v[60:63], v[128:131], v[188:191], v[60:63]
	v_mfma_f32_16x16x32_bf16 v[56:59], v[136:139], v[188:191], v[56:59]
	v_mfma_f32_16x16x32_bf16 v[44:47], v[128:131], v[200:203], v[44:47]
	v_mfma_f32_16x16x32_bf16 v[40:43], v[136:139], v[200:203], v[40:43]
	v_mfma_f32_16x16x32_bf16 v[28:31], v[128:131], v[208:211], v[28:31]
	v_mfma_f32_16x16x32_bf16 v[24:27], v[136:139], v[208:211], v[24:27]
	v_mfma_f32_16x16x32_bf16 v[12:15], v[128:131], v[216:219], v[12:15]
	v_mfma_f32_16x16x32_bf16 v[8:11], v[136:139], v[216:219], v[8:11]
	v_mfma_f32_16x16x32_bf16 v[60:63], v[132:135], v[192:195], v[60:63]
	v_mfma_f32_16x16x32_bf16 v[56:59], v[140:143], v[192:195], v[56:59]
	v_mfma_f32_16x16x32_bf16 v[44:47], v[132:135], v[204:207], v[44:47]
	v_mfma_f32_16x16x32_bf16 v[40:43], v[140:143], v[204:207], v[40:43]
	v_mfma_f32_16x16x32_bf16 v[28:31], v[132:135], v[212:215], v[28:31]
	v_mfma_f32_16x16x32_bf16 v[24:27], v[140:143], v[212:215], v[24:27]
	v_mfma_f32_16x16x32_bf16 v[12:15], v[132:135], v[228:231], v[12:15]
	v_mfma_f32_16x16x32_bf16 v[8:11], v[140:143], v[228:231], v[8:11]
	v_mfma_f32_16x16x32_bf16 v[52:55], v[144:147], v[188:191], v[52:55]
	v_mfma_f32_16x16x32_bf16 v[48:51], v[164:167], v[188:191], v[48:51]
	v_mfma_f32_16x16x32_bf16 v[36:39], v[144:147], v[200:203], v[36:39]
	v_mfma_f32_16x16x32_bf16 v[32:35], v[164:167], v[200:203], v[32:35]
	v_mfma_f32_16x16x32_bf16 v[20:23], v[144:147], v[208:211], v[20:23]
	v_mfma_f32_16x16x32_bf16 v[16:19], v[164:167], v[208:211], v[16:19]
	v_mfma_f32_16x16x32_bf16 v[4:7], v[144:147], v[216:219], v[4:7]
	v_mfma_f32_16x16x32_bf16 v[0:3], v[164:167], v[216:219], v[0:3]
	v_mfma_f32_16x16x32_bf16 v[52:55], v[148:151], v[192:195], v[52:55]
	v_mfma_f32_16x16x32_bf16 v[48:51], v[184:187], v[192:195], v[48:51]
	v_mfma_f32_16x16x32_bf16 v[36:39], v[148:151], v[204:207], v[36:39]
	v_mfma_f32_16x16x32_bf16 v[32:35], v[184:187], v[204:207], v[32:35]
	v_mfma_f32_16x16x32_bf16 v[20:23], v[148:151], v[212:215], v[20:23]
	v_mfma_f32_16x16x32_bf16 v[16:19], v[184:187], v[212:215], v[16:19]
	v_mfma_f32_16x16x32_bf16 v[4:7], v[148:151], v[228:231], v[4:7]
	v_mfma_f32_16x16x32_bf16 v[0:3], v[184:187], v[228:231], v[0:3]
	s_barrier
	s_setprio 0
	s_add_i32 s12, s12, 2
	s_add_u32 s58, s58, 0x100
	s_addc_u32 s59, s59, 0
	s_cmp_gt_u32 s12, 41
	s_mov_b64 s[36:37], s[40:41]
.LBB0_1061:
	s_add_u32 s40, s36, 0x100
	s_addc_u32 s41, s37, 0
	s_add_i32 s0, 0, 0x10000
	s_cmp_eq_u32 s12, 40
	s_cselect_b32 s45, s9, s41
	s_cselect_b32 s44, s8, s40
	s_cselect_b32 s43, s35, s59
	s_cselect_b32 s42, s34, s58
	s_add_i32 s13, 0, 0x14000
	v_add_u32_e32 v140, s0, v197
	v_add_u32_e32 v184, s13, v197
	ds_read_b128 v[128:131], v140
	ds_read_b128 v[132:135], v140 offset:1024
	ds_read_b128 v[136:139], v140 offset:2048
	ds_read_b128 v[140:143], v140 offset:3072
	ds_read_b128 v[144:147], v184
	ds_read_b128 v[148:151], v184 offset:1024
	ds_read_b128 v[164:167], v184 offset:2048
	ds_read_b128 v[184:187], v184 offset:3072
	s_add_i32 m0, s47, 0xc000
	ds_read_b128 v[188:191], v198
	ds_read_b128 v[192:195], v198 offset:1024
	ds_read_b128 v[200:203], v198 offset:2048
	ds_read_b128 v[204:207], v198 offset:3072
	ds_read_b128 v[208:211], v198 offset:4096
	ds_read_b128 v[212:215], v198 offset:5120
	ds_read_b128 v[216:219], v198 offset:6144
	ds_read_b128 v[228:231], v198 offset:7168
	global_load_lds_dwordx4 v160, s[36:37]
	s_add_i32 m0, s47, 0xe000
	s_nop 0
	global_load_lds_dwordx4 v162, s[36:37]
	s_waitcnt vmcnt(8)
	s_waitcnt lgkmcnt(0)
	s_setprio 1
	s_barrier
	v_mfma_f32_16x16x32_bf16 v[124:127], v[128:131], v[188:191], v[124:127]
	v_mfma_f32_16x16x32_bf16 v[120:123], v[136:139], v[188:191], v[120:123]
	v_mfma_f32_16x16x32_bf16 v[108:111], v[128:131], v[200:203], v[108:111]
	v_mfma_f32_16x16x32_bf16 v[104:107], v[136:139], v[200:203], v[104:107]
	v_mfma_f32_16x16x32_bf16 v[92:95], v[128:131], v[208:211], v[92:95]
	v_mfma_f32_16x16x32_bf16 v[88:91], v[136:139], v[208:211], v[88:91]
	v_mfma_f32_16x16x32_bf16 v[76:79], v[128:131], v[216:219], v[76:79]
	v_mfma_f32_16x16x32_bf16 v[72:75], v[136:139], v[216:219], v[72:75]
	v_mfma_f32_16x16x32_bf16 v[124:127], v[132:135], v[192:195], v[124:127]
	v_mfma_f32_16x16x32_bf16 v[120:123], v[140:143], v[192:195], v[120:123]
	v_mfma_f32_16x16x32_bf16 v[108:111], v[132:135], v[204:207], v[108:111]
	v_mfma_f32_16x16x32_bf16 v[104:107], v[140:143], v[204:207], v[104:107]
	v_mfma_f32_16x16x32_bf16 v[92:95], v[132:135], v[212:215], v[92:95]
	v_mfma_f32_16x16x32_bf16 v[88:91], v[140:143], v[212:215], v[88:91]
	v_mfma_f32_16x16x32_bf16 v[76:79], v[132:135], v[228:231], v[76:79]
	v_mfma_f32_16x16x32_bf16 v[72:75], v[140:143], v[228:231], v[72:75]
	v_mfma_f32_16x16x32_bf16 v[116:119], v[144:147], v[188:191], v[116:119]
	v_mfma_f32_16x16x32_bf16 v[112:115], v[164:167], v[188:191], v[112:115]
	v_mfma_f32_16x16x32_bf16 v[100:103], v[144:147], v[200:203], v[100:103]
	v_mfma_f32_16x16x32_bf16 v[96:99], v[164:167], v[200:203], v[96:99]
	v_mfma_f32_16x16x32_bf16 v[84:87], v[144:147], v[208:211], v[84:87]
	v_mfma_f32_16x16x32_bf16 v[80:83], v[164:167], v[208:211], v[80:83]
	v_mfma_f32_16x16x32_bf16 v[68:71], v[144:147], v[216:219], v[68:71]
	v_mfma_f32_16x16x32_bf16 v[64:67], v[164:167], v[216:219], v[64:67]
	v_mfma_f32_16x16x32_bf16 v[116:119], v[148:151], v[192:195], v[116:119]
	v_mfma_f32_16x16x32_bf16 v[112:115], v[184:187], v[192:195], v[112:115]
	v_mfma_f32_16x16x32_bf16 v[100:103], v[148:151], v[204:207], v[100:103]
	v_mfma_f32_16x16x32_bf16 v[96:99], v[184:187], v[204:207], v[96:99]
	v_mfma_f32_16x16x32_bf16 v[84:87], v[148:151], v[212:215], v[84:87]
	v_mfma_f32_16x16x32_bf16 v[80:83], v[184:187], v[212:215], v[80:83]
	v_mfma_f32_16x16x32_bf16 v[68:71], v[148:151], v[228:231], v[68:71]
	v_mfma_f32_16x16x32_bf16 v[64:67], v[184:187], v[228:231], v[64:67]
	s_barrier
	s_setprio 0
	s_add_i32 s0, s0, s46
	v_lshl_add_u64 v[232:233], s[42:43], 0, v[170:171]
	s_mov_b32 m0, s0
	ds_read_b128 v[188:191], v198 offset:16384
	ds_read_b128 v[192:195], v198 offset:17408
	ds_read_b128 v[200:203], v198 offset:18432
	ds_read_b128 v[204:207], v198 offset:19456
	ds_read_b128 v[208:211], v198 offset:20480
	ds_read_b128 v[212:215], v198 offset:21504
	ds_read_b128 v[216:219], v198 offset:22528
	ds_read_b128 v[228:231], v198 offset:23552
	global_load_lds_dwordx4 v[232:233], off
	s_add_i32 m0, s0, 0x2000
	s_add_u32 s0, s42, 0xb0000
	v_lshl_add_u64 v[234:235], s[42:43], 0, v[156:157]
	s_addc_u32 s1, s43, 0
	s_add_i32 s13, s13, s46
	global_load_lds_dwordx4 v[234:235], off
	s_mov_b32 m0, s13
	v_lshl_add_u64 v[238:239], s[44:45], 0, v[154:155]
	global_load_lds_dwordx4 v170, s[0:1]
	s_add_i32 m0, s13, 0x2000
	s_nop 0
	global_load_lds_dwordx4 v156, s[0:1]
	v_lshl_add_u64 v[236:237], s[44:45], 0, v[152:153]
	s_waitcnt vmcnt(6)
	s_waitcnt lgkmcnt(0)
	s_setprio 1
	s_barrier
	v_mfma_f32_16x16x32_bf16 v[60:63], v[128:131], v[188:191], v[60:63]
	v_mfma_f32_16x16x32_bf16 v[56:59], v[136:139], v[188:191], v[56:59]
	v_mfma_f32_16x16x32_bf16 v[44:47], v[128:131], v[200:203], v[44:47]
	v_mfma_f32_16x16x32_bf16 v[40:43], v[136:139], v[200:203], v[40:43]
	v_mfma_f32_16x16x32_bf16 v[28:31], v[128:131], v[208:211], v[28:31]
	v_mfma_f32_16x16x32_bf16 v[24:27], v[136:139], v[208:211], v[24:27]
	v_mfma_f32_16x16x32_bf16 v[12:15], v[128:131], v[216:219], v[12:15]
	v_mfma_f32_16x16x32_bf16 v[8:11], v[136:139], v[216:219], v[8:11]
	v_mfma_f32_16x16x32_bf16 v[60:63], v[132:135], v[192:195], v[60:63]
	v_mfma_f32_16x16x32_bf16 v[56:59], v[140:143], v[192:195], v[56:59]
	v_mfma_f32_16x16x32_bf16 v[44:47], v[132:135], v[204:207], v[44:47]
	v_mfma_f32_16x16x32_bf16 v[40:43], v[140:143], v[204:207], v[40:43]
	v_mfma_f32_16x16x32_bf16 v[28:31], v[132:135], v[212:215], v[28:31]
	v_mfma_f32_16x16x32_bf16 v[24:27], v[140:143], v[212:215], v[24:27]
	v_mfma_f32_16x16x32_bf16 v[12:15], v[132:135], v[228:231], v[12:15]
	v_mfma_f32_16x16x32_bf16 v[8:11], v[140:143], v[228:231], v[8:11]
	v_mfma_f32_16x16x32_bf16 v[52:55], v[144:147], v[188:191], v[52:55]
	v_mfma_f32_16x16x32_bf16 v[48:51], v[164:167], v[188:191], v[48:51]
	v_mfma_f32_16x16x32_bf16 v[36:39], v[144:147], v[200:203], v[36:39]
	v_mfma_f32_16x16x32_bf16 v[32:35], v[164:167], v[200:203], v[32:35]
	v_mfma_f32_16x16x32_bf16 v[20:23], v[144:147], v[208:211], v[20:23]
	v_mfma_f32_16x16x32_bf16 v[16:19], v[164:167], v[208:211], v[16:19]
	v_mfma_f32_16x16x32_bf16 v[4:7], v[144:147], v[216:219], v[4:7]
	v_mfma_f32_16x16x32_bf16 v[0:3], v[164:167], v[216:219], v[0:3]
	v_mfma_f32_16x16x32_bf16 v[52:55], v[148:151], v[192:195], v[52:55]
	v_mfma_f32_16x16x32_bf16 v[48:51], v[184:187], v[192:195], v[48:51]
	v_mfma_f32_16x16x32_bf16 v[36:39], v[148:151], v[204:207], v[36:39]
	v_mfma_f32_16x16x32_bf16 v[32:35], v[184:187], v[204:207], v[32:35]
	v_mfma_f32_16x16x32_bf16 v[20:23], v[148:151], v[212:215], v[20:23]
	v_mfma_f32_16x16x32_bf16 v[16:19], v[184:187], v[212:215], v[16:19]
	v_mfma_f32_16x16x32_bf16 v[4:7], v[148:151], v[228:231], v[4:7]
	v_mfma_f32_16x16x32_bf16 v[0:3], v[184:187], v[228:231], v[0:3]
	s_barrier
	s_setprio 0
	s_add_i32 s13, 0, 0x18000
	s_add_i32 s36, 0, 0x1c000
	v_add_u32_e32 v140, s13, v197
	v_add_u32_e32 v184, s36, v197
	ds_read_b128 v[128:131], v140
	ds_read_b128 v[132:135], v140 offset:1024
	ds_read_b128 v[136:139], v140 offset:2048
	ds_read_b128 v[140:143], v140 offset:3072
	ds_read_b128 v[144:147], v184
	ds_read_b128 v[148:151], v184 offset:1024
	ds_read_b128 v[164:167], v184 offset:2048
	ds_read_b128 v[184:187], v184 offset:3072
	s_add_u32 s0, s44, 0xb0000
	s_addc_u32 s1, s45, 0
	s_mov_b32 m0, s49
	ds_read_b128 v[188:191], v198 offset:32768
	ds_read_b128 v[192:195], v198 offset:33792
	ds_read_b128 v[200:203], v198 offset:34816
	ds_read_b128 v[204:207], v198 offset:35840
	ds_read_b128 v[208:211], v198 offset:36864
	ds_read_b128 v[212:215], v198 offset:37888
	ds_read_b128 v[216:219], v198 offset:38912
	ds_read_b128 v[228:231], v198 offset:39936
	global_load_lds_dwordx4 v152, s[0:1]
	s_mov_b32 m0, s50
	s_nop 0
	global_load_lds_dwordx4 v154, s[0:1]
	s_mov_b32 m0, s47
	s_nop 0
	global_load_lds_dwordx4 v[236:237], off
	s_mov_b32 m0, s48
	s_nop 0
	global_load_lds_dwordx4 v[238:239], off
	s_waitcnt vmcnt(8)
	s_waitcnt lgkmcnt(0)
	s_setprio 1
	s_barrier
	v_mfma_f32_16x16x32_bf16 v[124:127], v[128:131], v[188:191], v[124:127]
	v_mfma_f32_16x16x32_bf16 v[120:123], v[136:139], v[188:191], v[120:123]
	v_mfma_f32_16x16x32_bf16 v[108:111], v[128:131], v[200:203], v[108:111]
	v_mfma_f32_16x16x32_bf16 v[104:107], v[136:139], v[200:203], v[104:107]
	v_mfma_f32_16x16x32_bf16 v[92:95], v[128:131], v[208:211], v[92:95]
	v_mfma_f32_16x16x32_bf16 v[88:91], v[136:139], v[208:211], v[88:91]
	v_mfma_f32_16x16x32_bf16 v[76:79], v[128:131], v[216:219], v[76:79]
	v_mfma_f32_16x16x32_bf16 v[72:75], v[136:139], v[216:219], v[72:75]
	v_mfma_f32_16x16x32_bf16 v[124:127], v[132:135], v[192:195], v[124:127]
	v_mfma_f32_16x16x32_bf16 v[120:123], v[140:143], v[192:195], v[120:123]
	v_mfma_f32_16x16x32_bf16 v[108:111], v[132:135], v[204:207], v[108:111]
	v_mfma_f32_16x16x32_bf16 v[104:107], v[140:143], v[204:207], v[104:107]
	v_mfma_f32_16x16x32_bf16 v[92:95], v[132:135], v[212:215], v[92:95]
	v_mfma_f32_16x16x32_bf16 v[88:91], v[140:143], v[212:215], v[88:91]
	v_mfma_f32_16x16x32_bf16 v[76:79], v[132:135], v[228:231], v[76:79]
	v_mfma_f32_16x16x32_bf16 v[72:75], v[140:143], v[228:231], v[72:75]
	v_mfma_f32_16x16x32_bf16 v[116:119], v[144:147], v[188:191], v[116:119]
	v_mfma_f32_16x16x32_bf16 v[112:115], v[164:167], v[188:191], v[112:115]
	v_mfma_f32_16x16x32_bf16 v[100:103], v[144:147], v[200:203], v[100:103]
	v_mfma_f32_16x16x32_bf16 v[96:99], v[164:167], v[200:203], v[96:99]
	v_mfma_f32_16x16x32_bf16 v[84:87], v[144:147], v[208:211], v[84:87]
	v_mfma_f32_16x16x32_bf16 v[80:83], v[164:167], v[208:211], v[80:83]
	v_mfma_f32_16x16x32_bf16 v[68:71], v[144:147], v[216:219], v[68:71]
	v_mfma_f32_16x16x32_bf16 v[64:67], v[164:167], v[216:219], v[64:67]
	v_mfma_f32_16x16x32_bf16 v[116:119], v[148:151], v[192:195], v[116:119]
	v_mfma_f32_16x16x32_bf16 v[112:115], v[184:187], v[192:195], v[112:115]
	v_mfma_f32_16x16x32_bf16 v[100:103], v[148:151], v[204:207], v[100:103]
	v_mfma_f32_16x16x32_bf16 v[96:99], v[184:187], v[204:207], v[96:99]
	v_mfma_f32_16x16x32_bf16 v[84:87], v[148:151], v[212:215], v[84:87]
	v_mfma_f32_16x16x32_bf16 v[80:83], v[184:187], v[212:215], v[80:83]
	v_mfma_f32_16x16x32_bf16 v[68:71], v[148:151], v[228:231], v[68:71]
	v_mfma_f32_16x16x32_bf16 v[64:67], v[184:187], v[228:231], v[64:67]
	s_barrier
	s_setprio 0
	s_add_i32 s0, s13, s46
	v_lshl_add_u64 v[232:233], v[232:233], 0, s[16:17]
	s_mov_b32 m0, s0
	ds_read_b128 v[188:191], v198 offset:49152
	ds_read_b128 v[192:195], v198 offset:50176
	ds_read_b128 v[200:203], v198 offset:51200
	ds_read_b128 v[204:207], v198 offset:52224
	ds_read_b128 v[208:211], v198 offset:53248
	ds_read_b128 v[212:215], v198 offset:54272
	ds_read_b128 v[216:219], v198 offset:55296
	ds_read_b128 v[228:231], v198 offset:56320
	global_load_lds_dwordx4 v[232:233], off
	s_add_i32 m0, s0, 0x2000
	s_add_u32 s0, s42, 0xb0080
	v_lshl_add_u64 v[232:233], v[234:235], 0, s[16:17]
	s_addc_u32 s1, s43, 0
	s_add_i32 s13, s36, s46
	global_load_lds_dwordx4 v[232:233], off
	s_mov_b32 m0, s13
	s_nop 0
	global_load_lds_dwordx4 v170, s[0:1]
	s_add_i32 m0, s13, 0x2000
	s_nop 0
	global_load_lds_dwordx4 v156, s[0:1]
	v_lshl_add_u64 v[232:233], v[236:237], 0, s[16:17]
	s_mov_b32 m0, s51
	s_nop 0
	global_load_lds_dwordx4 v[232:233], off
	v_lshl_add_u64 v[232:233], v[238:239], 0, s[16:17]
	s_mov_b32 m0, s52
	s_nop 0
	global_load_lds_dwordx4 v[232:233], off
	s_waitcnt vmcnt(6)
	s_waitcnt lgkmcnt(0)
	s_setprio 1
	s_barrier
	v_mfma_f32_16x16x32_bf16 v[60:63], v[128:131], v[188:191], v[60:63]
	v_mfma_f32_16x16x32_bf16 v[56:59], v[136:139], v[188:191], v[56:59]
	v_mfma_f32_16x16x32_bf16 v[44:47], v[128:131], v[200:203], v[44:47]
	v_mfma_f32_16x16x32_bf16 v[40:43], v[136:139], v[200:203], v[40:43]
	v_mfma_f32_16x16x32_bf16 v[28:31], v[128:131], v[208:211], v[28:31]
	v_mfma_f32_16x16x32_bf16 v[24:27], v[136:139], v[208:211], v[24:27]
	v_mfma_f32_16x16x32_bf16 v[12:15], v[128:131], v[216:219], v[12:15]
	v_mfma_f32_16x16x32_bf16 v[8:11], v[136:139], v[216:219], v[8:11]
	v_mfma_f32_16x16x32_bf16 v[60:63], v[132:135], v[192:195], v[60:63]
	v_mfma_f32_16x16x32_bf16 v[56:59], v[140:143], v[192:195], v[56:59]
	v_mfma_f32_16x16x32_bf16 v[44:47], v[132:135], v[204:207], v[44:47]
	v_mfma_f32_16x16x32_bf16 v[40:43], v[140:143], v[204:207], v[40:43]
	v_mfma_f32_16x16x32_bf16 v[28:31], v[132:135], v[212:215], v[28:31]
	v_mfma_f32_16x16x32_bf16 v[24:27], v[140:143], v[212:215], v[24:27]
	v_mfma_f32_16x16x32_bf16 v[12:15], v[132:135], v[228:231], v[12:15]
	v_mfma_f32_16x16x32_bf16 v[8:11], v[140:143], v[228:231], v[8:11]
	v_mfma_f32_16x16x32_bf16 v[52:55], v[144:147], v[188:191], v[52:55]
	v_mfma_f32_16x16x32_bf16 v[48:51], v[164:167], v[188:191], v[48:51]
	v_mfma_f32_16x16x32_bf16 v[36:39], v[144:147], v[200:203], v[36:39]
	v_mfma_f32_16x16x32_bf16 v[32:35], v[164:167], v[200:203], v[32:35]
	v_mfma_f32_16x16x32_bf16 v[20:23], v[144:147], v[208:211], v[20:23]
	v_mfma_f32_16x16x32_bf16 v[16:19], v[164:167], v[208:211], v[16:19]
	v_mfma_f32_16x16x32_bf16 v[4:7], v[144:147], v[216:219], v[4:7]
	v_mfma_f32_16x16x32_bf16 v[0:3], v[164:167], v[216:219], v[0:3]
	v_mfma_f32_16x16x32_bf16 v[52:55], v[148:151], v[192:195], v[52:55]
	v_mfma_f32_16x16x32_bf16 v[48:51], v[184:187], v[192:195], v[48:51]
	v_mfma_f32_16x16x32_bf16 v[36:39], v[148:151], v[204:207], v[36:39]
	v_mfma_f32_16x16x32_bf16 v[32:35], v[184:187], v[204:207], v[32:35]
	v_mfma_f32_16x16x32_bf16 v[20:23], v[148:151], v[212:215], v[20:23]
	v_mfma_f32_16x16x32_bf16 v[16:19], v[184:187], v[212:215], v[16:19]
	v_mfma_f32_16x16x32_bf16 v[4:7], v[148:151], v[228:231], v[4:7]
	v_mfma_f32_16x16x32_bf16 v[0:3], v[184:187], v[228:231], v[0:3]
	s_barrier
	s_setprio 0
	s_add_i32 s12, s12, 2
	s_add_u32 s58, s58, 0x100
	s_addc_u32 s59, s59, 0
	s_cmp_gt_u32 s12, 41
	s_mov_b64 s[36:37], s[40:41]
	s_cbranch_scc0 .LBB0_1061
	s_and_b64 vcc, exec, s[30:31]
	s_cbranch_vccz .LBB0_1064
	s_barrier
